# peeled first K-loop iteration in all 8 gemm phases: first MFMA per accumulator uses srcC=0, per-unit accumulator zeroing (128 v_mov) removed
# speedup vs baseline: 1.0321x; 1.0181x over previous
; #define PG8_STAGE(bufoff, gbase, voff) do { _Pragma("unroll") for (int _i = 0; _i < 2; ++_i) \
;         __builtin_amdgcn_global_load_lds((const unsigned*)((const char*)(gbase) + (voff)[_i]), (PG8_LAS unsigned*)(lds + (bufoff) + ldsw + _i * 8192), 16, 0, 0); } while (0)
; #define PG8_LDA(dst, b, h) do { _Pragma("unroll") for (int m = 0; m < 4; ++m) _Pragma("unroll") for (int k = 0; k < 2; ++k) dst[m][k] = *(const PG8_LAS bf16x8*)(lds + PG8_SA(b, h) + aoff + m * 2048 + k * 1024); } while (0)
; #define PG8_LDB(dst, b, h) do { _Pragma("unroll") for (int n = 0; n < 2; ++n) _Pragma("unroll") for (int k = 0; k < 2; ++k) dst[n][k] = *(const PG8_LAS bf16x8*)(lds + PG8_SB(b, h) + boff + n * 2048 + k * 1024); } while (0)
; #define PG8_WAIT_V(n) asm volatile("s_waitcnt vmcnt(" #n ")" ::: "memory")
; template <class Epi, class Sched, bool ALIGN_EPI = false, bool SP2 = false>
; __device__ __forceinline__ void gemm_phase(PG8_LAS unsigned char* lds, const Gemm g, const Sched& S, const Epi& E, int wave_in) {
;     ...
;         const char* nA = has_next ? (const char*)g.A + (size_t)(nxt.pm >> g.ash) * g.astride + (size_t)nxt.pm * tstep : cA; const char* nB = has_next ? (const char*)g.Bt + (size_t)(nxt.pm >> g.bsh) * g.bstride + (size_t)nxt.pn * tstep : cB;
;         for (int t = 0; t < nt; t += 2) {
;             const bool last = (t == nt - 2);
;             const char* a1 = cA + (size_t)(t + 1) * kstep;
;             const char* a2 = last ? nA : cA + (size_t)(t + 2) * kstep; const char* b2 = last ? nB : cB + (size_t)(t + 2) * kstep;
;             const char* a3 = a2 + kstep; const char* b3 = b2 + kstep;
;             if (last && has_next) S.a_ready(nxt);
;             if constexpr (SP2) {
;             PG8_LDB(B0, 0, 0); PG8_LDB(B1, 0, 1); PG8_SCHED; PG8_LDA(At, 0, 0); PG8_STAGE(PG8_SA(1, 1), a1 + hstep, voffA);
;             PG8_WAIT_V(8); PG8_WAIT_L(0); PG8_BAR; PG8_MMA(0, 0, At, B0); PG8_MMA(0, 1, At, B1); PG8_BAR; PG8_SCHED;
;             PG8_LDA(At, 0, 1); PG8_STAGE(PG8_SB(0, 0), b2, voffB); PG8_STAGE(PG8_SB(0, 1), b2 + hstep, voffB); PG8_STAGE(PG8_SA(0, 0), a2, voffA);
;     ...
; #pragma unroll
;         for (int a = 0; a < 2; ++a)
; #pragma unroll
;             for (int b = 0; b < 2; ++b)
; #pragma unroll
;                 for (int m = 0; m < 4; ++m)
; #pragma unroll
;                     for (int n = 0; n < 2; ++n) acc[a][b][m][n] = (f32x4){0.f, 0.f, 0.f, 0.f};
.LBB0_253:
	s_ashr_i32 s23, s22, 31
	s_lshl_b64 s[24:25], s[22:23], 19
	s_add_u32 s24, s62, s24
	s_addc_u32 s25, s63, s25
	s_and_b64 s[26:27], s[18:19], exec
	s_cselect_b32 s23, s25, s37
	s_cselect_b32 s29, s24, s36
	s_ashr_i32 s21, s20, 31
	s_lshl_b64 s[26:27], s[20:21], 19
	s_add_u32 s26, s64, s26
	s_addc_u32 s27, s65, s27
	s_and_b64 s[38:39], s[18:19], exec
	s_cselect_b32 s21, s27, s35
	s_cselect_b32 s31, s26, s34
	s_add_u32 s76, s34, 0x100
	s_addc_u32 s77, s35, 0
	s_add_u32 s34, s36, 0x40080
	s_addc_u32 s35, s37, 0
	s_mov_b32 s78, -2
	v_add_u32_e32 v174, s43, v160
	v_add_u32_e32 v190, s44, v160
	ds_read_b128 v[162:165], v174
	ds_read_b128 v[166:169], v174 offset:1024
	ds_read_b128 v[170:173], v174 offset:2048
	ds_read_b128 v[174:177], v174 offset:3072
	ds_read_b128 v[178:181], v190
	ds_read_b128 v[182:185], v190 offset:1024
	ds_read_b128 v[186:189], v190 offset:2048
	ds_read_b128 v[190:193], v190 offset:3072
	s_add_u32 s36, s34, 0xfffc0080
	s_addc_u32 s37, s35, -1
	s_cmp_eq_u32 s78, 12
	s_cselect_b32 s39, s23, s37
	s_cselect_b32 s38, s29, s36
	s_cselect_b32 s37, s21, s77
	s_cselect_b32 s36, s31, s76
	v_lshl_add_u64 v[226:227], s[34:35], 0, v[156:157]
	s_add_i32 m0, s67, 0xc000
	ds_read_b128 v[194:197], v161
	ds_read_b128 v[198:201], v161 offset:1024
	ds_read_b128 v[202:205], v161 offset:2048
	ds_read_b128 v[206:209], v161 offset:3072
	ds_read_b128 v[210:213], v161 offset:4096
	ds_read_b128 v[214:217], v161 offset:5120
	ds_read_b128 v[218:221], v161 offset:6144
	ds_read_b128 v[222:225], v161 offset:7168
	global_load_lds_dwordx4 v[226:227], off
	v_lshl_add_u64 v[226:227], s[34:35], 0, v[154:155]
	s_add_i32 m0, s67, 0xe000
	s_nop 0
	global_load_lds_dwordx4 v[226:227], off
	s_waitcnt vmcnt(8)
	s_waitcnt lgkmcnt(0)
	s_barrier
	s_setprio 1
	s_waitcnt lgkmcnt(0)
	v_mfma_f32_16x16x32_bf16 v[124:127], v[162:165], v[194:197], 0
	v_mfma_f32_16x16x32_bf16 v[120:123], v[170:173], v[194:197], 0
	v_mfma_f32_16x16x32_bf16 v[116:119], v[162:165], v[202:205], 0
	v_mfma_f32_16x16x32_bf16 v[108:111], v[170:173], v[202:205], 0
	v_mfma_f32_16x16x32_bf16 v[100:103], v[162:165], v[210:213], 0
	v_mfma_f32_16x16x32_bf16 v[92:95], v[170:173], v[210:213], 0
	v_mfma_f32_16x16x32_bf16 v[84:87], v[162:165], v[218:221], 0
	v_mfma_f32_16x16x32_bf16 v[76:79], v[170:173], v[218:221], 0
	v_mfma_f32_16x16x32_bf16 v[124:127], v[166:169], v[198:201], v[124:127]
	v_mfma_f32_16x16x32_bf16 v[120:123], v[174:177], v[198:201], v[120:123]
	v_mfma_f32_16x16x32_bf16 v[116:119], v[166:169], v[206:209], v[116:119]
	v_mfma_f32_16x16x32_bf16 v[108:111], v[174:177], v[206:209], v[108:111]
	v_mfma_f32_16x16x32_bf16 v[100:103], v[166:169], v[214:217], v[100:103]
	v_mfma_f32_16x16x32_bf16 v[92:95], v[174:177], v[214:217], v[92:95]
	v_mfma_f32_16x16x32_bf16 v[84:87], v[166:169], v[222:225], v[84:87]
	v_mfma_f32_16x16x32_bf16 v[76:79], v[174:177], v[222:225], v[76:79]
	s_setprio 0
	s_setprio 1
	v_mfma_f32_16x16x32_bf16 v[112:115], v[178:181], v[194:197], 0
	v_mfma_f32_16x16x32_bf16 v[104:107], v[186:189], v[194:197], 0
	v_mfma_f32_16x16x32_bf16 v[96:99], v[178:181], v[202:205], 0
	v_mfma_f32_16x16x32_bf16 v[88:91], v[186:189], v[202:205], 0
	v_mfma_f32_16x16x32_bf16 v[80:83], v[178:181], v[210:213], 0
	v_mfma_f32_16x16x32_bf16 v[72:75], v[186:189], v[210:213], 0
	v_mfma_f32_16x16x32_bf16 v[68:71], v[178:181], v[218:221], 0
	v_mfma_f32_16x16x32_bf16 v[64:67], v[186:189], v[218:221], 0
	v_mfma_f32_16x16x32_bf16 v[112:115], v[182:185], v[198:201], v[112:115]
	v_mfma_f32_16x16x32_bf16 v[104:107], v[190:193], v[198:201], v[104:107]
	v_mfma_f32_16x16x32_bf16 v[96:99], v[182:185], v[206:209], v[96:99]
	v_mfma_f32_16x16x32_bf16 v[88:91], v[190:193], v[206:209], v[88:91]
	v_mfma_f32_16x16x32_bf16 v[80:83], v[182:185], v[214:217], v[80:83]
	v_mfma_f32_16x16x32_bf16 v[72:75], v[190:193], v[214:217], v[72:75]
	v_mfma_f32_16x16x32_bf16 v[68:71], v[182:185], v[222:225], v[68:71]
	v_mfma_f32_16x16x32_bf16 v[64:67], v[190:193], v[222:225], v[64:67]
	s_setprio 0
	s_barrier
	s_add_i32 s79, s43, s66
	v_lshl_add_u64 v[226:227], s[36:37], 0, v[132:133]
	s_mov_b32 m0, s79
	ds_read_b128 v[194:197], v161 offset:16384
	ds_read_b128 v[198:201], v161 offset:17408
	ds_read_b128 v[202:205], v161 offset:18432
	ds_read_b128 v[206:209], v161 offset:19456
	ds_read_b128 v[210:213], v161 offset:20480
	ds_read_b128 v[214:217], v161 offset:21504
	ds_read_b128 v[218:221], v161 offset:22528
	ds_read_b128 v[222:225], v161 offset:23552
	global_load_lds_dwordx4 v[226:227], off
	s_add_i32 m0, s79, 0x2000
	s_add_u32 s80, s36, 0x40000
	v_lshl_add_u64 v[228:229], s[36:37], 0, v[136:137]
	s_addc_u32 s81, s37, 0
	s_add_i32 s79, s44, s66
	global_load_lds_dwordx4 v[228:229], off
	v_lshl_add_u64 v[230:231], s[80:81], 0, v[132:133]
	s_mov_b32 m0, s79
	v_lshl_add_u64 v[232:233], s[38:39], 0, v[134:135]
	global_load_lds_dwordx4 v[230:231], off
	v_lshl_add_u64 v[230:231], s[80:81], 0, v[136:137]
	s_add_i32 m0, s79, 0x2000
	s_nop 0
	global_load_lds_dwordx4 v[230:231], off
	v_lshl_add_u64 v[230:231], s[38:39], 0, v[130:131]
	s_mov_b32 m0, s67
	s_nop 0
	global_load_lds_dwordx4 v[230:231], off
	s_mov_b32 m0, s68
	s_nop 0
	global_load_lds_dwordx4 v[232:233], off
	s_waitcnt vmcnt(8)
	s_waitcnt lgkmcnt(0)
	s_barrier
; #define PG8_STAGE(bufoff, gbase, voff) do { _Pragma("unroll") for (int _i = 0; _i < 2; ++_i) \
;         __builtin_amdgcn_global_load_lds((const unsigned*)((const char*)(gbase) + (voff)[_i]), (PG8_LAS unsigned*)(lds + (bufoff) + ldsw + _i * 8192), 16, 0, 0); } while (0)
; #define PG8_LDA(dst, b, h) do { _Pragma("unroll") for (int m = 0; m < 4; ++m) _Pragma("unroll") for (int k = 0; k < 2; ++k) dst[m][k] = *(const PG8_LAS bf16x8*)(lds + PG8_SA(b, h) + aoff + m * 2048 + k * 1024); } while (0)
; #define PG8_LDB(dst, b, h) do { _Pragma("unroll") for (int n = 0; n < 2; ++n) _Pragma("unroll") for (int k = 0; k < 2; ++k) dst[n][k] = *(const PG8_LAS bf16x8*)(lds + PG8_SB(b, h) + boff + n * 2048 + k * 1024); } while (0)
; #define PG8_MMA(ai, bj, At, Bt) do { __builtin_amdgcn_s_setprio(1); _Pragma("unroll") for (int m = 0; m < 4; ++m) _Pragma("unroll") for (int n = 0; n < 2; ++n) _Pragma("unroll") for (int k = 0; k < 2; ++k) \
;         acc[ai][bj][m][n] = __builtin_amdgcn_mfma_f32_16x16x32_bf16(Bt[n][k], At[m][k], acc[ai][bj][m][n], 0, 0, 0); __builtin_amdgcn_s_setprio(0); } while (0)
; #define PG8_WAIT_V(n) asm volatile("s_waitcnt vmcnt(" #n ")" ::: "memory")
; #define PG8_WAIT_L(n) asm volatile("s_waitcnt lgkmcnt(" #n ")" ::: "memory")
; #define PG8_BAR __builtin_amdgcn_s_barrier()
; #define PG8_SCHED __builtin_amdgcn_sched_barrier(0)
; template <class Epi, class Sched, bool ALIGN_EPI = false, bool SP2 = false>
; __device__ __forceinline__ void gemm_phase(PG8_LAS unsigned char* lds, const Gemm g, const Sched& S, const Epi& E, int wave_in) {
;     ...
;             PG8_WAIT_V(8); PG8_WAIT_L(0); PG8_BAR; PG8_MMA(1, 0, At, B0); PG8_MMA(1, 1, At, B1); PG8_BAR; PG8_SCHED;
;             PG8_LDB(B0, 1, 0); PG8_LDB(B1, 1, 1); PG8_SCHED; PG8_LDA(At, 1, 0); PG8_STAGE(PG8_SA(0, 1), a2 + hstep, voffA);
;             PG8_WAIT_V(8); PG8_WAIT_L(0); PG8_BAR; PG8_MMA(0, 0, At, B0); PG8_MMA(0, 1, At, B1); PG8_BAR; PG8_SCHED;
	s_setprio 1
	s_waitcnt lgkmcnt(0)
	v_mfma_f32_16x16x32_bf16 v[60:63], v[162:165], v[194:197], 0
	v_mfma_f32_16x16x32_bf16 v[56:59], v[170:173], v[194:197], 0
	v_mfma_f32_16x16x32_bf16 v[52:55], v[162:165], v[202:205], 0
	v_mfma_f32_16x16x32_bf16 v[44:47], v[170:173], v[202:205], 0
	v_mfma_f32_16x16x32_bf16 v[36:39], v[162:165], v[210:213], 0
	v_mfma_f32_16x16x32_bf16 v[28:31], v[170:173], v[210:213], 0
	v_mfma_f32_16x16x32_bf16 v[20:23], v[162:165], v[218:221], 0
	v_mfma_f32_16x16x32_bf16 v[12:15], v[170:173], v[218:221], 0
	v_mfma_f32_16x16x32_bf16 v[60:63], v[166:169], v[198:201], v[60:63]
	v_mfma_f32_16x16x32_bf16 v[56:59], v[174:177], v[198:201], v[56:59]
	v_mfma_f32_16x16x32_bf16 v[52:55], v[166:169], v[206:209], v[52:55]
	v_mfma_f32_16x16x32_bf16 v[44:47], v[174:177], v[206:209], v[44:47]
	v_mfma_f32_16x16x32_bf16 v[36:39], v[166:169], v[214:217], v[36:39]
	v_mfma_f32_16x16x32_bf16 v[28:31], v[174:177], v[214:217], v[28:31]
	v_mfma_f32_16x16x32_bf16 v[20:23], v[166:169], v[222:225], v[20:23]
	v_mfma_f32_16x16x32_bf16 v[12:15], v[174:177], v[222:225], v[12:15]
	s_setprio 0
	s_setprio 1
	v_mfma_f32_16x16x32_bf16 v[48:51], v[178:181], v[194:197], 0
	v_mfma_f32_16x16x32_bf16 v[40:43], v[186:189], v[194:197], 0
	v_mfma_f32_16x16x32_bf16 v[32:35], v[178:181], v[202:205], 0
	v_mfma_f32_16x16x32_bf16 v[24:27], v[186:189], v[202:205], 0
	v_mfma_f32_16x16x32_bf16 v[16:19], v[178:181], v[210:213], 0
	v_mfma_f32_16x16x32_bf16 v[8:11], v[186:189], v[210:213], 0
	v_mfma_f32_16x16x32_bf16 v[4:7], v[178:181], v[218:221], 0
	v_mfma_f32_16x16x32_bf16 v[0:3], v[186:189], v[218:221], 0
	v_mfma_f32_16x16x32_bf16 v[48:51], v[182:185], v[198:201], v[48:51]
	v_mfma_f32_16x16x32_bf16 v[40:43], v[190:193], v[198:201], v[40:43]
	v_mfma_f32_16x16x32_bf16 v[32:35], v[182:185], v[206:209], v[32:35]
	v_mfma_f32_16x16x32_bf16 v[24:27], v[190:193], v[206:209], v[24:27]
	v_mfma_f32_16x16x32_bf16 v[16:19], v[182:185], v[214:217], v[16:19]
	v_mfma_f32_16x16x32_bf16 v[8:11], v[190:193], v[214:217], v[8:11]
	v_mfma_f32_16x16x32_bf16 v[4:7], v[182:185], v[222:225], v[4:7]
	v_mfma_f32_16x16x32_bf16 v[0:3], v[190:193], v[222:225], v[0:3]
	s_setprio 0
	s_barrier
	v_add_u32_e32 v174, s45, v160
	v_add_u32_e32 v190, s46, v160
	ds_read_b128 v[162:165], v174
	ds_read_b128 v[166:169], v174 offset:1024
	ds_read_b128 v[170:173], v174 offset:2048
	ds_read_b128 v[174:177], v174 offset:3072
	ds_read_b128 v[178:181], v190
	ds_read_b128 v[182:185], v190 offset:1024
	ds_read_b128 v[186:189], v190 offset:2048
	ds_read_b128 v[190:193], v190 offset:3072
	s_add_u32 s38, s38, 0x40000
	s_addc_u32 s39, s39, 0
	s_mov_b32 m0, s69
	v_lshl_add_u64 v[234:235], s[38:39], 0, v[130:131]
	ds_read_b128 v[194:197], v161 offset:32768
	ds_read_b128 v[198:201], v161 offset:33792
	ds_read_b128 v[202:205], v161 offset:34816
	ds_read_b128 v[206:209], v161 offset:35840
	ds_read_b128 v[210:213], v161 offset:36864
	ds_read_b128 v[214:217], v161 offset:37888
	ds_read_b128 v[218:221], v161 offset:38912
	ds_read_b128 v[222:225], v161 offset:39936
	global_load_lds_dwordx4 v[234:235], off
	v_lshl_add_u64 v[234:235], s[38:39], 0, v[134:135]
	s_mov_b32 m0, s70
	s_nop 0
	global_load_lds_dwordx4 v[234:235], off
	s_waitcnt vmcnt(8)
	s_waitcnt lgkmcnt(0)
	s_barrier
	s_setprio 1
	s_waitcnt lgkmcnt(0)
	v_mfma_f32_16x16x32_bf16 v[124:127], v[162:165], v[194:197], v[124:127]
	v_mfma_f32_16x16x32_bf16 v[120:123], v[170:173], v[194:197], v[120:123]
	v_mfma_f32_16x16x32_bf16 v[116:119], v[162:165], v[202:205], v[116:119]
	v_mfma_f32_16x16x32_bf16 v[108:111], v[170:173], v[202:205], v[108:111]
	v_mfma_f32_16x16x32_bf16 v[100:103], v[162:165], v[210:213], v[100:103]
	v_mfma_f32_16x16x32_bf16 v[92:95], v[170:173], v[210:213], v[92:95]
	v_mfma_f32_16x16x32_bf16 v[84:87], v[162:165], v[218:221], v[84:87]
	v_mfma_f32_16x16x32_bf16 v[76:79], v[170:173], v[218:221], v[76:79]
	v_mfma_f32_16x16x32_bf16 v[124:127], v[166:169], v[198:201], v[124:127]
	v_mfma_f32_16x16x32_bf16 v[120:123], v[174:177], v[198:201], v[120:123]
	v_mfma_f32_16x16x32_bf16 v[116:119], v[166:169], v[206:209], v[116:119]
	v_mfma_f32_16x16x32_bf16 v[108:111], v[174:177], v[206:209], v[108:111]
	v_mfma_f32_16x16x32_bf16 v[100:103], v[166:169], v[214:217], v[100:103]
	v_mfma_f32_16x16x32_bf16 v[92:95], v[174:177], v[214:217], v[92:95]
	v_mfma_f32_16x16x32_bf16 v[84:87], v[166:169], v[222:225], v[84:87]
	v_mfma_f32_16x16x32_bf16 v[76:79], v[174:177], v[222:225], v[76:79]
	s_setprio 0
	s_setprio 1
	v_mfma_f32_16x16x32_bf16 v[112:115], v[178:181], v[194:197], v[112:115]
	v_mfma_f32_16x16x32_bf16 v[104:107], v[186:189], v[194:197], v[104:107]
	v_mfma_f32_16x16x32_bf16 v[96:99], v[178:181], v[202:205], v[96:99]
	v_mfma_f32_16x16x32_bf16 v[88:91], v[186:189], v[202:205], v[88:91]
	v_mfma_f32_16x16x32_bf16 v[80:83], v[178:181], v[210:213], v[80:83]
	v_mfma_f32_16x16x32_bf16 v[72:75], v[186:189], v[210:213], v[72:75]
	v_mfma_f32_16x16x32_bf16 v[68:71], v[178:181], v[218:221], v[68:71]
	v_mfma_f32_16x16x32_bf16 v[64:67], v[186:189], v[218:221], v[64:67]
	v_mfma_f32_16x16x32_bf16 v[112:115], v[182:185], v[198:201], v[112:115]
	v_mfma_f32_16x16x32_bf16 v[104:107], v[190:193], v[198:201], v[104:107]
	v_mfma_f32_16x16x32_bf16 v[96:99], v[182:185], v[206:209], v[96:99]
	v_mfma_f32_16x16x32_bf16 v[88:91], v[190:193], v[206:209], v[88:91]
	v_mfma_f32_16x16x32_bf16 v[80:83], v[182:185], v[214:217], v[80:83]
	v_mfma_f32_16x16x32_bf16 v[72:75], v[190:193], v[214:217], v[72:75]
	v_mfma_f32_16x16x32_bf16 v[68:71], v[182:185], v[222:225], v[68:71]
	v_mfma_f32_16x16x32_bf16 v[64:67], v[190:193], v[222:225], v[64:67]
	s_setprio 0
	s_barrier
; #define PG8_STAGE(bufoff, gbase, voff) do { _Pragma("unroll") for (int _i = 0; _i < 2; ++_i) \
;         __builtin_amdgcn_global_load_lds((const unsigned*)((const char*)(gbase) + (voff)[_i]), (PG8_LAS unsigned*)(lds + (bufoff) + ldsw + _i * 8192), 16, 0, 0); } while (0)
; #define PG8_LDA(dst, b, h) do { _Pragma("unroll") for (int m = 0; m < 4; ++m) _Pragma("unroll") for (int k = 0; k < 2; ++k) dst[m][k] = *(const PG8_LAS bf16x8*)(lds + PG8_SA(b, h) + aoff + m * 2048 + k * 1024); } while (0)
; #define PG8_WAIT_V(n) asm volatile("s_waitcnt vmcnt(" #n ")" ::: "memory")
; #define PG8_WAIT_L(n) asm volatile("s_waitcnt lgkmcnt(" #n ")" ::: "memory")
; #define PG8_BAR __builtin_amdgcn_s_barrier()
; template <class Epi, class Sched, bool ALIGN_EPI = false, bool SP2 = false>
; __device__ __forceinline__ void gemm_phase(PG8_LAS unsigned char* lds, const Gemm g, const Sched& S, const Epi& E, int wave_in) {
;     ...
;         for (int t = 0; t < nt; t += 2) {
;             const bool last = (t == nt - 2);
;             const char* a1 = cA + (size_t)(t + 1) * kstep;
;             const char* a2 = last ? nA : cA + (size_t)(t + 2) * kstep; const char* b2 = last ? nB : cB + (size_t)(t + 2) * kstep;
;             const char* a3 = a2 + kstep; const char* b3 = b2 + kstep;
;             if (last && has_next) S.a_ready(nxt);
;             if constexpr (SP2) {
;             PG8_LDB(B0, 0, 0); PG8_LDB(B1, 0, 1); PG8_SCHED; PG8_LDA(At, 0, 0); PG8_STAGE(PG8_SA(1, 1), a1 + hstep, voffA);
;             PG8_WAIT_V(8); PG8_WAIT_L(0); PG8_BAR; PG8_MMA(0, 0, At, B0); PG8_MMA(0, 1, At, B1); PG8_BAR; PG8_SCHED;
;             PG8_LDA(At, 0, 1); PG8_STAGE(PG8_SB(0, 0), b2, voffB); PG8_STAGE(PG8_SB(0, 1), b2 + hstep, voffB); PG8_STAGE(PG8_SA(0, 0), a2, voffA);
;             PG8_WAIT_V(8); PG8_WAIT_L(0); PG8_BAR; PG8_MMA(1, 0, At, B0); PG8_MMA(1, 1, At, B1); PG8_BAR; PG8_SCHED;
;             PG8_LDB(B0, 1, 0); PG8_LDB(B1, 1, 1); PG8_SCHED; PG8_LDA(At, 1, 0); PG8_STAGE(PG8_SA(0, 1), a2 + hstep, voffA);
;             PG8_WAIT_V(8); PG8_WAIT_L(0); PG8_BAR; PG8_MMA(0, 0, At, B0); PG8_MMA(0, 1, At, B1); PG8_BAR; PG8_SCHED;
;             PG8_LDA(At, 1, 1); PG8_STAGE(PG8_SB(1, 0), b3, voffB); PG8_STAGE(PG8_SB(1, 1), b3 + hstep, voffB); PG8_STAGE(PG8_SA(1, 0), a3, voffA);
;             PG8_WAIT_V(8); PG8_WAIT_L(0); PG8_BAR; PG8_MMA(1, 0, At, B0); PG8_MMA(1, 1, At, B1); PG8_BAR; PG8_SCHED;
	s_add_i32 s38, s45, s66
	v_lshl_add_u64 v[226:227], v[226:227], 0, s[6:7]
	s_mov_b32 m0, s38
	ds_read_b128 v[194:197], v161 offset:49152
	ds_read_b128 v[198:201], v161 offset:50176
	ds_read_b128 v[202:205], v161 offset:51200
	ds_read_b128 v[206:209], v161 offset:52224
	ds_read_b128 v[210:213], v161 offset:53248
	ds_read_b128 v[214:217], v161 offset:54272
	ds_read_b128 v[218:221], v161 offset:55296
	ds_read_b128 v[222:225], v161 offset:56320
	global_load_lds_dwordx4 v[226:227], off
	s_add_i32 m0, s38, 0x2000
	s_add_u32 s36, s36, 0x40080
	v_lshl_add_u64 v[226:227], v[228:229], 0, s[6:7]
	s_addc_u32 s37, s37, 0
	s_add_i32 s38, s46, s66
	global_load_lds_dwordx4 v[226:227], off
	v_lshl_add_u64 v[226:227], s[36:37], 0, v[132:133]
	s_mov_b32 m0, s38
	s_nop 0
	global_load_lds_dwordx4 v[226:227], off
	v_lshl_add_u64 v[226:227], s[36:37], 0, v[136:137]
	s_add_i32 m0, s38, 0x2000
	s_nop 0
	global_load_lds_dwordx4 v[226:227], off
	v_lshl_add_u64 v[226:227], v[230:231], 0, s[6:7]
	s_mov_b32 m0, s73
	s_nop 0
	global_load_lds_dwordx4 v[226:227], off
	v_lshl_add_u64 v[226:227], v[232:233], 0, s[6:7]
	s_mov_b32 m0, s74
	s_nop 0
	global_load_lds_dwordx4 v[226:227], off
	s_waitcnt vmcnt(8)
	s_waitcnt lgkmcnt(0)
	s_barrier
	s_setprio 1
	s_waitcnt lgkmcnt(0)
	v_mfma_f32_16x16x32_bf16 v[60:63], v[162:165], v[194:197], v[60:63]
	v_mfma_f32_16x16x32_bf16 v[56:59], v[170:173], v[194:197], v[56:59]
	v_mfma_f32_16x16x32_bf16 v[52:55], v[162:165], v[202:205], v[52:55]
	v_mfma_f32_16x16x32_bf16 v[44:47], v[170:173], v[202:205], v[44:47]
	v_mfma_f32_16x16x32_bf16 v[36:39], v[162:165], v[210:213], v[36:39]
	v_mfma_f32_16x16x32_bf16 v[28:31], v[170:173], v[210:213], v[28:31]
	v_mfma_f32_16x16x32_bf16 v[20:23], v[162:165], v[218:221], v[20:23]
	v_mfma_f32_16x16x32_bf16 v[12:15], v[170:173], v[218:221], v[12:15]
	v_mfma_f32_16x16x32_bf16 v[60:63], v[166:169], v[198:201], v[60:63]
	v_mfma_f32_16x16x32_bf16 v[56:59], v[174:177], v[198:201], v[56:59]
	v_mfma_f32_16x16x32_bf16 v[52:55], v[166:169], v[206:209], v[52:55]
	v_mfma_f32_16x16x32_bf16 v[44:47], v[174:177], v[206:209], v[44:47]
	v_mfma_f32_16x16x32_bf16 v[36:39], v[166:169], v[214:217], v[36:39]
	v_mfma_f32_16x16x32_bf16 v[28:31], v[174:177], v[214:217], v[28:31]
	v_mfma_f32_16x16x32_bf16 v[20:23], v[166:169], v[222:225], v[20:23]
	v_mfma_f32_16x16x32_bf16 v[12:15], v[174:177], v[222:225], v[12:15]
	s_setprio 0
	s_setprio 1
	v_mfma_f32_16x16x32_bf16 v[48:51], v[178:181], v[194:197], v[48:51]
	v_mfma_f32_16x16x32_bf16 v[40:43], v[186:189], v[194:197], v[40:43]
	v_mfma_f32_16x16x32_bf16 v[32:35], v[178:181], v[202:205], v[32:35]
	v_mfma_f32_16x16x32_bf16 v[24:27], v[186:189], v[202:205], v[24:27]
	v_mfma_f32_16x16x32_bf16 v[16:19], v[178:181], v[210:213], v[16:19]
	v_mfma_f32_16x16x32_bf16 v[8:11], v[186:189], v[210:213], v[8:11]
	v_mfma_f32_16x16x32_bf16 v[4:7], v[178:181], v[218:221], v[4:7]
	v_mfma_f32_16x16x32_bf16 v[0:3], v[186:189], v[218:221], v[0:3]
	v_mfma_f32_16x16x32_bf16 v[48:51], v[182:185], v[198:201], v[48:51]
	v_mfma_f32_16x16x32_bf16 v[40:43], v[190:193], v[198:201], v[40:43]
	v_mfma_f32_16x16x32_bf16 v[32:35], v[182:185], v[206:209], v[32:35]
	v_mfma_f32_16x16x32_bf16 v[24:27], v[190:193], v[206:209], v[24:27]
	v_mfma_f32_16x16x32_bf16 v[16:19], v[182:185], v[214:217], v[16:19]
	v_mfma_f32_16x16x32_bf16 v[8:11], v[190:193], v[214:217], v[8:11]
	v_mfma_f32_16x16x32_bf16 v[4:7], v[182:185], v[222:225], v[4:7]
	v_mfma_f32_16x16x32_bf16 v[0:3], v[190:193], v[222:225], v[0:3]
	s_setprio 0
	s_barrier
	s_add_i32 s78, s78, 2
	s_add_u32 s76, s76, 0x100
	s_addc_u32 s77, s77, 0
	s_add_u32 s34, s34, 0x100
	s_addc_u32 s35, s35, 0
	s_cmp_gt_u32 s78, 13
	s_cbranch_scc1 .Lkexit_0

; #define PG8_BAR __builtin_amdgcn_s_barrier()
; template <class Epi, class Sched, bool ALIGN_EPI = false, bool SP2 = false>
; __device__ __forceinline__ void gemm_phase(PG8_LAS unsigned char* lds, const Gemm g, const Sched& S, const Epi& E, int wave_in) {
;     ...
;         if constexpr (ALIGN_EPI) { if (wr == 0) PG8_BAR; }
.Lkexit_0:
	s_and_b64 vcc, exec, s[16:17]
	s_cbranch_vccz .LBB0_257
	s_barrier

; #define PG8_STAGE(bufoff, gbase, voff) do { _Pragma("unroll") for (int _i = 0; _i < 2; ++_i) \
;         __builtin_amdgcn_global_load_lds((const unsigned*)((const char*)(gbase) + (voff)[_i]), (PG8_LAS unsigned*)(lds + (bufoff) + ldsw + _i * 8192), 16, 0, 0); } while (0)
; #define PG8_LDA(dst, b, h) do { _Pragma("unroll") for (int m = 0; m < 4; ++m) _Pragma("unroll") for (int k = 0; k < 2; ++k) dst[m][k] = *(const PG8_LAS bf16x8*)(lds + PG8_SA(b, h) + aoff + m * 2048 + k * 1024); } while (0)
; #define PG8_LDB(dst, b, h) do { _Pragma("unroll") for (int n = 0; n < 2; ++n) _Pragma("unroll") for (int k = 0; k < 2; ++k) dst[n][k] = *(const PG8_LAS bf16x8*)(lds + PG8_SB(b, h) + boff + n * 2048 + k * 1024); } while (0)
; #define PG8_WAIT_V(n) asm volatile("s_waitcnt vmcnt(" #n ")" ::: "memory")
; template <class Epi, class Sched, bool ALIGN_EPI = false, bool SP2 = false>
; __device__ __forceinline__ void gemm_phase(PG8_LAS unsigned char* lds, const Gemm g, const Sched& S, const Epi& E, int wave_in) {
;     ...
;         const char* nA = has_next ? (const char*)g.A + (size_t)(nxt.pm >> g.ash) * g.astride + (size_t)nxt.pm * tstep : cA; const char* nB = has_next ? (const char*)g.Bt + (size_t)(nxt.pm >> g.bsh) * g.bstride + (size_t)nxt.pn * tstep : cB;
;         for (int t = 0; t < nt; t += 2) {
;             const bool last = (t == nt - 2);
;             const char* a1 = cA + (size_t)(t + 1) * kstep;
;             const char* a2 = last ? nA : cA + (size_t)(t + 2) * kstep; const char* b2 = last ? nB : cB + (size_t)(t + 2) * kstep;
;             const char* a3 = a2 + kstep; const char* b3 = b2 + kstep;
;             if (last && has_next) S.a_ready(nxt);
;             if constexpr (SP2) {
;             PG8_LDB(B0, 0, 0); PG8_LDB(B1, 0, 1); PG8_SCHED; PG8_LDA(At, 0, 0); PG8_STAGE(PG8_SA(1, 1), a1 + hstep, voffA);
;             PG8_WAIT_V(8); PG8_WAIT_L(0); PG8_BAR; PG8_MMA(0, 0, At, B0); PG8_MMA(0, 1, At, B1); PG8_BAR; PG8_SCHED;
;             PG8_LDA(At, 0, 1); PG8_STAGE(PG8_SB(0, 0), b2, voffB); PG8_STAGE(PG8_SB(0, 1), b2 + hstep, voffB); PG8_STAGE(PG8_SA(0, 0), a2, voffA);
;     ...
; #pragma unroll
;         for (int a = 0; a < 2; ++a)
; #pragma unroll
;             for (int b = 0; b < 2; ++b)
; #pragma unroll
;                 for (int m = 0; m < 4; ++m)
; #pragma unroll
;                     for (int n = 0; n < 2; ++n) acc[a][b][m][n] = (f32x4){0.f, 0.f, 0.f, 0.f};
.LBB0_272:
	s_ashr_i32 s77, s76, 31
	s_lshl_b64 s[8:9], s[76:77], 19
	s_add_u32 s84, s22, s8
	s_addc_u32 s85, s23, s9
	s_and_b64 s[8:9], s[40:41], exec
	s_cselect_b32 s8, s85, s5
	s_cselect_b32 s9, s84, s4
	s_ashr_i32 s95, s94, 31
	s_lshl_b64 s[10:11], s[94:95], 19
	v_readlane_b32 s16, v255, 39
	v_readlane_b32 s17, v255, 40
	s_add_u32 s24, s16, s10
	s_addc_u32 s25, s17, s11
	s_and_b64 s[10:11], s[40:41], exec
	s_cselect_b32 s16, s25, s1
	s_cselect_b32 s17, s24, s0
	s_add_u32 s31, s0, 0x100
	s_addc_u32 s33, s1, 0
	s_add_u32 s0, s4, 0x40080
	s_addc_u32 s1, s5, 0
	s_mov_b32 s34, -2
	s_waitcnt lgkmcnt(0)
	s_add_u32 s4, s0, 0xfffc0080
	s_addc_u32 s5, s1, -1
	s_add_i32 s42, s35, 0x100
	s_cmp_eq_u32 s34, 12
	s_cselect_b32 s11, s8, s5
	s_cselect_b32 s10, s9, s4
	s_cselect_b32 s5, s16, s33
	s_cselect_b32 s4, s17, s31
	s_add_i32 s44, s90, 0x100
	v_add_u32_e32 v168, s42, v177
	v_add_u32_e32 v188, s44, v177
	ds_read_b128 v[156:159], v168
	ds_read_b128 v[160:163], v168 offset:1024
	ds_read_b128 v[164:167], v168 offset:2048
	ds_read_b128 v[168:171], v168 offset:3072
	ds_read_b128 v[172:175], v188
	ds_read_b128 v[180:183], v188 offset:1024
	ds_read_b128 v[184:187], v188 offset:2048
	ds_read_b128 v[188:191], v188 offset:3072
	v_lshl_add_u64 v[230:231], s[0:1], 0, v[154:155]
	s_add_i32 m0, s67, 0xc000
	ds_read_b128 v[198:201], v179
	ds_read_b128 v[202:205], v179 offset:1024
	ds_read_b128 v[206:209], v179 offset:2048
	ds_read_b128 v[210:213], v179 offset:3072
	ds_read_b128 v[214:217], v179 offset:4096
	ds_read_b128 v[218:221], v179 offset:5120
	ds_read_b128 v[222:225], v179 offset:6144
	ds_read_b128 v[226:229], v179 offset:7168
	global_load_lds_dwordx4 v[230:231], off
	v_lshl_add_u64 v[230:231], s[0:1], 0, v[152:153]
	s_add_i32 m0, s67, 0xe000
	s_nop 0
	global_load_lds_dwordx4 v[230:231], off
	s_waitcnt vmcnt(8)
	s_waitcnt lgkmcnt(0)
	s_barrier
	s_setprio 1
	s_waitcnt lgkmcnt(0)
	v_mfma_f32_16x16x32_bf16 v[124:127], v[156:159], v[198:201], 0
	v_mfma_f32_16x16x32_bf16 v[120:123], v[164:167], v[198:201], 0
	v_mfma_f32_16x16x32_bf16 v[108:111], v[156:159], v[206:209], 0
	v_mfma_f32_16x16x32_bf16 v[104:107], v[164:167], v[206:209], 0
	v_mfma_f32_16x16x32_bf16 v[92:95], v[156:159], v[214:217], 0
	v_mfma_f32_16x16x32_bf16 v[88:91], v[164:167], v[214:217], 0
	v_mfma_f32_16x16x32_bf16 v[76:79], v[156:159], v[222:225], 0
	v_mfma_f32_16x16x32_bf16 v[72:75], v[164:167], v[222:225], 0
	v_mfma_f32_16x16x32_bf16 v[124:127], v[160:163], v[202:205], v[124:127]
	v_mfma_f32_16x16x32_bf16 v[120:123], v[168:171], v[202:205], v[120:123]
	v_mfma_f32_16x16x32_bf16 v[108:111], v[160:163], v[210:213], v[108:111]
	v_mfma_f32_16x16x32_bf16 v[104:107], v[168:171], v[210:213], v[104:107]
	v_mfma_f32_16x16x32_bf16 v[92:95], v[160:163], v[218:221], v[92:95]
	v_mfma_f32_16x16x32_bf16 v[88:91], v[168:171], v[218:221], v[88:91]
	v_mfma_f32_16x16x32_bf16 v[76:79], v[160:163], v[226:229], v[76:79]
	v_mfma_f32_16x16x32_bf16 v[72:75], v[168:171], v[226:229], v[72:75]
	s_setprio 0
	s_setprio 1
	v_mfma_f32_16x16x32_bf16 v[116:119], v[172:175], v[198:201], 0
	v_mfma_f32_16x16x32_bf16 v[112:115], v[184:187], v[198:201], 0
	v_mfma_f32_16x16x32_bf16 v[100:103], v[172:175], v[206:209], 0
	v_mfma_f32_16x16x32_bf16 v[96:99], v[184:187], v[206:209], 0
	v_mfma_f32_16x16x32_bf16 v[84:87], v[172:175], v[214:217], 0
	v_mfma_f32_16x16x32_bf16 v[80:83], v[184:187], v[214:217], 0
	v_mfma_f32_16x16x32_bf16 v[68:71], v[172:175], v[222:225], 0
	v_mfma_f32_16x16x32_bf16 v[64:67], v[184:187], v[222:225], 0
	v_mfma_f32_16x16x32_bf16 v[116:119], v[180:183], v[202:205], v[116:119]
	v_mfma_f32_16x16x32_bf16 v[112:115], v[188:191], v[202:205], v[112:115]
	v_mfma_f32_16x16x32_bf16 v[100:103], v[180:183], v[210:213], v[100:103]
	v_mfma_f32_16x16x32_bf16 v[96:99], v[188:191], v[210:213], v[96:99]
	v_mfma_f32_16x16x32_bf16 v[84:87], v[180:183], v[218:221], v[84:87]
	v_mfma_f32_16x16x32_bf16 v[80:83], v[188:191], v[218:221], v[80:83]
	v_mfma_f32_16x16x32_bf16 v[68:71], v[180:183], v[226:229], v[68:71]
	v_mfma_f32_16x16x32_bf16 v[64:67], v[188:191], v[226:229], v[64:67]
	s_setprio 0
	s_barrier
	s_add_i32 s42, s42, s66
	v_lshl_add_u64 v[230:231], s[4:5], 0, v[132:133]
	s_mov_b32 m0, s42
	ds_read_b128 v[198:201], v179 offset:16384
	ds_read_b128 v[202:205], v179 offset:17408
	ds_read_b128 v[206:209], v179 offset:18432
	ds_read_b128 v[210:213], v179 offset:19456
	ds_read_b128 v[214:217], v179 offset:20480
	ds_read_b128 v[218:221], v179 offset:21504
	ds_read_b128 v[222:225], v179 offset:22528
	ds_read_b128 v[226:229], v179 offset:23552
	global_load_lds_dwordx4 v[230:231], off
	s_add_i32 m0, s42, 0x2000
	s_add_u32 s42, s4, 0x40000
	v_lshl_add_u64 v[232:233], s[4:5], 0, v[128:129]
	s_addc_u32 s43, s5, 0
	s_add_i32 s44, s44, s66
	global_load_lds_dwordx4 v[232:233], off
	v_lshl_add_u64 v[234:235], s[42:43], 0, v[132:133]
	s_mov_b32 m0, s44
	v_lshl_add_u64 v[236:237], s[10:11], 0, v[130:131]
	global_load_lds_dwordx4 v[234:235], off
	v_lshl_add_u64 v[234:235], s[42:43], 0, v[128:129]
	s_add_i32 m0, s44, 0x2000
	s_nop 0
	global_load_lds_dwordx4 v[234:235], off
	v_lshl_add_u64 v[234:235], s[10:11], 0, v[134:135]
	s_mov_b32 m0, s67
	s_nop 0
	global_load_lds_dwordx4 v[234:235], off
	s_mov_b32 m0, s78
	s_nop 0
	global_load_lds_dwordx4 v[236:237], off
	s_waitcnt vmcnt(8)
	s_waitcnt lgkmcnt(0)
	s_barrier
; #define PG8_STAGE(bufoff, gbase, voff) do { _Pragma("unroll") for (int _i = 0; _i < 2; ++_i) \
;         __builtin_amdgcn_global_load_lds((const unsigned*)((const char*)(gbase) + (voff)[_i]), (PG8_LAS unsigned*)(lds + (bufoff) + ldsw + _i * 8192), 16, 0, 0); } while (0)
; #define PG8_LDA(dst, b, h) do { _Pragma("unroll") for (int m = 0; m < 4; ++m) _Pragma("unroll") for (int k = 0; k < 2; ++k) dst[m][k] = *(const PG8_LAS bf16x8*)(lds + PG8_SA(b, h) + aoff + m * 2048 + k * 1024); } while (0)
; #define PG8_LDB(dst, b, h) do { _Pragma("unroll") for (int n = 0; n < 2; ++n) _Pragma("unroll") for (int k = 0; k < 2; ++k) dst[n][k] = *(const PG8_LAS bf16x8*)(lds + PG8_SB(b, h) + boff + n * 2048 + k * 1024); } while (0)
; #define PG8_MMA(ai, bj, At, Bt) do { __builtin_amdgcn_s_setprio(1); _Pragma("unroll") for (int m = 0; m < 4; ++m) _Pragma("unroll") for (int n = 0; n < 2; ++n) _Pragma("unroll") for (int k = 0; k < 2; ++k) \
;         acc[ai][bj][m][n] = __builtin_amdgcn_mfma_f32_16x16x32_bf16(Bt[n][k], At[m][k], acc[ai][bj][m][n], 0, 0, 0); __builtin_amdgcn_s_setprio(0); } while (0)
; #define PG8_WAIT_V(n) asm volatile("s_waitcnt vmcnt(" #n ")" ::: "memory")
; #define PG8_WAIT_L(n) asm volatile("s_waitcnt lgkmcnt(" #n ")" ::: "memory")
; #define PG8_BAR __builtin_amdgcn_s_barrier()
; #define PG8_SCHED __builtin_amdgcn_sched_barrier(0)
; template <class Epi, class Sched, bool ALIGN_EPI = false, bool SP2 = false>
; __device__ __forceinline__ void gemm_phase(PG8_LAS unsigned char* lds, const Gemm g, const Sched& S, const Epi& E, int wave_in) {
;     ...
;             PG8_WAIT_V(8); PG8_WAIT_L(0); PG8_BAR; PG8_MMA(1, 0, At, B0); PG8_MMA(1, 1, At, B1); PG8_BAR; PG8_SCHED;
;             PG8_LDB(B0, 1, 0); PG8_LDB(B1, 1, 1); PG8_SCHED; PG8_LDA(At, 1, 0); PG8_STAGE(PG8_SA(0, 1), a2 + hstep, voffA);
;             PG8_WAIT_V(8); PG8_WAIT_L(0); PG8_BAR; PG8_MMA(0, 0, At, B0); PG8_MMA(0, 1, At, B1); PG8_BAR; PG8_SCHED;
	s_setprio 1
	s_waitcnt lgkmcnt(0)
	v_mfma_f32_16x16x32_bf16 v[60:63], v[156:159], v[198:201], 0
	v_mfma_f32_16x16x32_bf16 v[56:59], v[164:167], v[198:201], 0
	v_mfma_f32_16x16x32_bf16 v[44:47], v[156:159], v[206:209], 0
	v_mfma_f32_16x16x32_bf16 v[40:43], v[164:167], v[206:209], 0
	v_mfma_f32_16x16x32_bf16 v[28:31], v[156:159], v[214:217], 0
	v_mfma_f32_16x16x32_bf16 v[24:27], v[164:167], v[214:217], 0
	v_mfma_f32_16x16x32_bf16 v[12:15], v[156:159], v[222:225], 0
	v_mfma_f32_16x16x32_bf16 v[8:11], v[164:167], v[222:225], 0
	v_mfma_f32_16x16x32_bf16 v[60:63], v[160:163], v[202:205], v[60:63]
	v_mfma_f32_16x16x32_bf16 v[56:59], v[168:171], v[202:205], v[56:59]
	v_mfma_f32_16x16x32_bf16 v[44:47], v[160:163], v[210:213], v[44:47]
	v_mfma_f32_16x16x32_bf16 v[40:43], v[168:171], v[210:213], v[40:43]
	v_mfma_f32_16x16x32_bf16 v[28:31], v[160:163], v[218:221], v[28:31]
	v_mfma_f32_16x16x32_bf16 v[24:27], v[168:171], v[218:221], v[24:27]
	v_mfma_f32_16x16x32_bf16 v[12:15], v[160:163], v[226:229], v[12:15]
	v_mfma_f32_16x16x32_bf16 v[8:11], v[168:171], v[226:229], v[8:11]
	s_setprio 0
	s_setprio 1
	v_mfma_f32_16x16x32_bf16 v[52:55], v[172:175], v[198:201], 0
	v_mfma_f32_16x16x32_bf16 v[48:51], v[184:187], v[198:201], 0
	v_mfma_f32_16x16x32_bf16 v[36:39], v[172:175], v[206:209], 0
	v_mfma_f32_16x16x32_bf16 v[32:35], v[184:187], v[206:209], 0
	v_mfma_f32_16x16x32_bf16 v[20:23], v[172:175], v[214:217], 0
	v_mfma_f32_16x16x32_bf16 v[16:19], v[184:187], v[214:217], 0
	v_mfma_f32_16x16x32_bf16 v[4:7], v[172:175], v[222:225], 0
	v_mfma_f32_16x16x32_bf16 v[0:3], v[184:187], v[222:225], 0
	v_mfma_f32_16x16x32_bf16 v[52:55], v[180:183], v[202:205], v[52:55]
	v_mfma_f32_16x16x32_bf16 v[48:51], v[188:191], v[202:205], v[48:51]
	v_mfma_f32_16x16x32_bf16 v[36:39], v[180:183], v[210:213], v[36:39]
	v_mfma_f32_16x16x32_bf16 v[32:35], v[188:191], v[210:213], v[32:35]
	v_mfma_f32_16x16x32_bf16 v[20:23], v[180:183], v[218:221], v[20:23]
	v_mfma_f32_16x16x32_bf16 v[16:19], v[188:191], v[218:221], v[16:19]
	v_mfma_f32_16x16x32_bf16 v[4:7], v[180:183], v[226:229], v[4:7]
	v_mfma_f32_16x16x32_bf16 v[0:3], v[188:191], v[226:229], v[0:3]
	s_setprio 0
	s_barrier
	s_add_i32 s42, s65, 0x100
	s_add_i32 s43, s52, 0x100
	v_add_u32_e32 v168, s42, v177
	v_add_u32_e32 v188, s43, v177
	ds_read_b128 v[156:159], v168
	ds_read_b128 v[160:163], v168 offset:1024
	ds_read_b128 v[164:167], v168 offset:2048
	ds_read_b128 v[168:171], v168 offset:3072
	ds_read_b128 v[172:175], v188
	ds_read_b128 v[180:183], v188 offset:1024
	ds_read_b128 v[184:187], v188 offset:2048
	ds_read_b128 v[188:191], v188 offset:3072
	s_add_u32 s10, s10, 0x40000
	s_addc_u32 s11, s11, 0
	s_mov_b32 m0, s79
	v_lshl_add_u64 v[238:239], s[10:11], 0, v[134:135]
	ds_read_b128 v[198:201], v179 offset:32768
	ds_read_b128 v[202:205], v179 offset:33792
	ds_read_b128 v[206:209], v179 offset:34816
	ds_read_b128 v[210:213], v179 offset:35840
	ds_read_b128 v[214:217], v179 offset:36864
	ds_read_b128 v[218:221], v179 offset:37888
	ds_read_b128 v[222:225], v179 offset:38912
	ds_read_b128 v[226:229], v179 offset:39936
	global_load_lds_dwordx4 v[238:239], off
	v_lshl_add_u64 v[238:239], s[10:11], 0, v[130:131]
	s_mov_b32 m0, s82
	s_nop 0
	global_load_lds_dwordx4 v[238:239], off
	s_waitcnt vmcnt(8)
	s_waitcnt lgkmcnt(0)
	s_barrier
	s_setprio 1
	s_waitcnt lgkmcnt(0)
	v_mfma_f32_16x16x32_bf16 v[124:127], v[156:159], v[198:201], v[124:127]
	v_mfma_f32_16x16x32_bf16 v[120:123], v[164:167], v[198:201], v[120:123]
	v_mfma_f32_16x16x32_bf16 v[108:111], v[156:159], v[206:209], v[108:111]
	v_mfma_f32_16x16x32_bf16 v[104:107], v[164:167], v[206:209], v[104:107]
	v_mfma_f32_16x16x32_bf16 v[92:95], v[156:159], v[214:217], v[92:95]
	v_mfma_f32_16x16x32_bf16 v[88:91], v[164:167], v[214:217], v[88:91]
	v_mfma_f32_16x16x32_bf16 v[76:79], v[156:159], v[222:225], v[76:79]
	v_mfma_f32_16x16x32_bf16 v[72:75], v[164:167], v[222:225], v[72:75]
	v_mfma_f32_16x16x32_bf16 v[124:127], v[160:163], v[202:205], v[124:127]
	v_mfma_f32_16x16x32_bf16 v[120:123], v[168:171], v[202:205], v[120:123]
	v_mfma_f32_16x16x32_bf16 v[108:111], v[160:163], v[210:213], v[108:111]
	v_mfma_f32_16x16x32_bf16 v[104:107], v[168:171], v[210:213], v[104:107]
	v_mfma_f32_16x16x32_bf16 v[92:95], v[160:163], v[218:221], v[92:95]
	v_mfma_f32_16x16x32_bf16 v[88:91], v[168:171], v[218:221], v[88:91]
	v_mfma_f32_16x16x32_bf16 v[76:79], v[160:163], v[226:229], v[76:79]
	v_mfma_f32_16x16x32_bf16 v[72:75], v[168:171], v[226:229], v[72:75]
	s_setprio 0
	s_setprio 1
	v_mfma_f32_16x16x32_bf16 v[116:119], v[172:175], v[198:201], v[116:119]
	v_mfma_f32_16x16x32_bf16 v[112:115], v[184:187], v[198:201], v[112:115]
	v_mfma_f32_16x16x32_bf16 v[100:103], v[172:175], v[206:209], v[100:103]
	v_mfma_f32_16x16x32_bf16 v[96:99], v[184:187], v[206:209], v[96:99]
	v_mfma_f32_16x16x32_bf16 v[84:87], v[172:175], v[214:217], v[84:87]
	v_mfma_f32_16x16x32_bf16 v[80:83], v[184:187], v[214:217], v[80:83]
	v_mfma_f32_16x16x32_bf16 v[68:71], v[172:175], v[222:225], v[68:71]
	v_mfma_f32_16x16x32_bf16 v[64:67], v[184:187], v[222:225], v[64:67]
	v_mfma_f32_16x16x32_bf16 v[116:119], v[180:183], v[202:205], v[116:119]
	v_mfma_f32_16x16x32_bf16 v[112:115], v[188:191], v[202:205], v[112:115]
	v_mfma_f32_16x16x32_bf16 v[100:103], v[180:183], v[210:213], v[100:103]
	v_mfma_f32_16x16x32_bf16 v[96:99], v[188:191], v[210:213], v[96:99]
	v_mfma_f32_16x16x32_bf16 v[84:87], v[180:183], v[218:221], v[84:87]
	v_mfma_f32_16x16x32_bf16 v[80:83], v[188:191], v[218:221], v[80:83]
	v_mfma_f32_16x16x32_bf16 v[68:71], v[180:183], v[226:229], v[68:71]
	v_mfma_f32_16x16x32_bf16 v[64:67], v[188:191], v[226:229], v[64:67]
	s_setprio 0
	s_barrier
; #define PG8_STAGE(bufoff, gbase, voff) do { _Pragma("unroll") for (int _i = 0; _i < 2; ++_i) \
;         __builtin_amdgcn_global_load_lds((const unsigned*)((const char*)(gbase) + (voff)[_i]), (PG8_LAS unsigned*)(lds + (bufoff) + ldsw + _i * 8192), 16, 0, 0); } while (0)
; #define PG8_LDA(dst, b, h) do { _Pragma("unroll") for (int m = 0; m < 4; ++m) _Pragma("unroll") for (int k = 0; k < 2; ++k) dst[m][k] = *(const PG8_LAS bf16x8*)(lds + PG8_SA(b, h) + aoff + m * 2048 + k * 1024); } while (0)
; #define PG8_WAIT_V(n) asm volatile("s_waitcnt vmcnt(" #n ")" ::: "memory")
; #define PG8_WAIT_L(n) asm volatile("s_waitcnt lgkmcnt(" #n ")" ::: "memory")
; #define PG8_BAR __builtin_amdgcn_s_barrier()
; template <class Epi, class Sched, bool ALIGN_EPI = false, bool SP2 = false>
; __device__ __forceinline__ void gemm_phase(PG8_LAS unsigned char* lds, const Gemm g, const Sched& S, const Epi& E, int wave_in) {
;     ...
;         for (int t = 0; t < nt; t += 2) {
;             const bool last = (t == nt - 2);
;             const char* a1 = cA + (size_t)(t + 1) * kstep;
;             const char* a2 = last ? nA : cA + (size_t)(t + 2) * kstep; const char* b2 = last ? nB : cB + (size_t)(t + 2) * kstep;
;             const char* a3 = a2 + kstep; const char* b3 = b2 + kstep;
;             if (last && has_next) S.a_ready(nxt);
;             if constexpr (SP2) {
;             PG8_LDB(B0, 0, 0); PG8_LDB(B1, 0, 1); PG8_SCHED; PG8_LDA(At, 0, 0); PG8_STAGE(PG8_SA(1, 1), a1 + hstep, voffA);
;             PG8_WAIT_V(8); PG8_WAIT_L(0); PG8_BAR; PG8_MMA(0, 0, At, B0); PG8_MMA(0, 1, At, B1); PG8_BAR; PG8_SCHED;
;             PG8_LDA(At, 0, 1); PG8_STAGE(PG8_SB(0, 0), b2, voffB); PG8_STAGE(PG8_SB(0, 1), b2 + hstep, voffB); PG8_STAGE(PG8_SA(0, 0), a2, voffA);
;             PG8_WAIT_V(8); PG8_WAIT_L(0); PG8_BAR; PG8_MMA(1, 0, At, B0); PG8_MMA(1, 1, At, B1); PG8_BAR; PG8_SCHED;
;             PG8_LDB(B0, 1, 0); PG8_LDB(B1, 1, 1); PG8_SCHED; PG8_LDA(At, 1, 0); PG8_STAGE(PG8_SA(0, 1), a2 + hstep, voffA);
;             PG8_WAIT_V(8); PG8_WAIT_L(0); PG8_BAR; PG8_MMA(0, 0, At, B0); PG8_MMA(0, 1, At, B1); PG8_BAR; PG8_SCHED;
;             PG8_LDA(At, 1, 1); PG8_STAGE(PG8_SB(1, 0), b3, voffB); PG8_STAGE(PG8_SB(1, 1), b3 + hstep, voffB); PG8_STAGE(PG8_SA(1, 0), a3, voffA);
;             PG8_WAIT_V(8); PG8_WAIT_L(0); PG8_BAR; PG8_MMA(1, 0, At, B0); PG8_MMA(1, 1, At, B1); PG8_BAR; PG8_SCHED;
	s_add_i32 s10, s42, s66
	v_lshl_add_u64 v[230:231], v[230:231], 0, s[88:89]
	s_mov_b32 m0, s10
	ds_read_b128 v[198:201], v179 offset:49152
	ds_read_b128 v[202:205], v179 offset:50176
	ds_read_b128 v[206:209], v179 offset:51200
	ds_read_b128 v[210:213], v179 offset:52224
	ds_read_b128 v[214:217], v179 offset:53248
	ds_read_b128 v[218:221], v179 offset:54272
	ds_read_b128 v[222:225], v179 offset:55296
	ds_read_b128 v[226:229], v179 offset:56320
	global_load_lds_dwordx4 v[230:231], off
	s_add_i32 m0, s10, 0x2000
	s_add_u32 s4, s4, 0x40080
	v_lshl_add_u64 v[230:231], v[232:233], 0, s[88:89]
	s_addc_u32 s5, s5, 0
	s_add_i32 s10, s43, s66
	global_load_lds_dwordx4 v[230:231], off
	v_lshl_add_u64 v[230:231], s[4:5], 0, v[132:133]
	s_mov_b32 m0, s10
	s_nop 0
	global_load_lds_dwordx4 v[230:231], off
	v_lshl_add_u64 v[230:231], s[4:5], 0, v[128:129]
	s_add_i32 m0, s10, 0x2000
	s_nop 0
	global_load_lds_dwordx4 v[230:231], off
	v_lshl_add_u64 v[230:231], v[234:235], 0, s[88:89]
	s_mov_b32 m0, s72
	s_nop 0
	global_load_lds_dwordx4 v[230:231], off
	v_lshl_add_u64 v[230:231], v[236:237], 0, s[88:89]
	s_mov_b32 m0, s73
	s_nop 0
	global_load_lds_dwordx4 v[230:231], off
	s_waitcnt vmcnt(8)
	s_waitcnt lgkmcnt(0)
	s_barrier
	s_setprio 1
	s_waitcnt lgkmcnt(0)
	v_mfma_f32_16x16x32_bf16 v[60:63], v[156:159], v[198:201], v[60:63]
	v_mfma_f32_16x16x32_bf16 v[56:59], v[164:167], v[198:201], v[56:59]
	v_mfma_f32_16x16x32_bf16 v[44:47], v[156:159], v[206:209], v[44:47]
	v_mfma_f32_16x16x32_bf16 v[40:43], v[164:167], v[206:209], v[40:43]
	v_mfma_f32_16x16x32_bf16 v[28:31], v[156:159], v[214:217], v[28:31]
	v_mfma_f32_16x16x32_bf16 v[24:27], v[164:167], v[214:217], v[24:27]
	v_mfma_f32_16x16x32_bf16 v[12:15], v[156:159], v[222:225], v[12:15]
	v_mfma_f32_16x16x32_bf16 v[8:11], v[164:167], v[222:225], v[8:11]
	v_mfma_f32_16x16x32_bf16 v[60:63], v[160:163], v[202:205], v[60:63]
	v_mfma_f32_16x16x32_bf16 v[56:59], v[168:171], v[202:205], v[56:59]
	v_mfma_f32_16x16x32_bf16 v[44:47], v[160:163], v[210:213], v[44:47]
	v_mfma_f32_16x16x32_bf16 v[40:43], v[168:171], v[210:213], v[40:43]
	v_mfma_f32_16x16x32_bf16 v[28:31], v[160:163], v[218:221], v[28:31]
	v_mfma_f32_16x16x32_bf16 v[24:27], v[168:171], v[218:221], v[24:27]
	v_mfma_f32_16x16x32_bf16 v[12:15], v[160:163], v[226:229], v[12:15]
	v_mfma_f32_16x16x32_bf16 v[8:11], v[168:171], v[226:229], v[8:11]
	s_setprio 0
	s_setprio 1
	v_mfma_f32_16x16x32_bf16 v[52:55], v[172:175], v[198:201], v[52:55]
	v_mfma_f32_16x16x32_bf16 v[48:51], v[184:187], v[198:201], v[48:51]
	v_mfma_f32_16x16x32_bf16 v[36:39], v[172:175], v[206:209], v[36:39]
	v_mfma_f32_16x16x32_bf16 v[32:35], v[184:187], v[206:209], v[32:35]
	v_mfma_f32_16x16x32_bf16 v[20:23], v[172:175], v[214:217], v[20:23]
	v_mfma_f32_16x16x32_bf16 v[16:19], v[184:187], v[214:217], v[16:19]
	v_mfma_f32_16x16x32_bf16 v[4:7], v[172:175], v[222:225], v[4:7]
	v_mfma_f32_16x16x32_bf16 v[0:3], v[184:187], v[222:225], v[0:3]
	v_mfma_f32_16x16x32_bf16 v[52:55], v[180:183], v[202:205], v[52:55]
	v_mfma_f32_16x16x32_bf16 v[48:51], v[188:191], v[202:205], v[48:51]
	v_mfma_f32_16x16x32_bf16 v[36:39], v[180:183], v[210:213], v[36:39]
	v_mfma_f32_16x16x32_bf16 v[32:35], v[188:191], v[210:213], v[32:35]
	v_mfma_f32_16x16x32_bf16 v[20:23], v[180:183], v[218:221], v[20:23]
	v_mfma_f32_16x16x32_bf16 v[16:19], v[188:191], v[218:221], v[16:19]
	v_mfma_f32_16x16x32_bf16 v[4:7], v[180:183], v[226:229], v[4:7]
	v_mfma_f32_16x16x32_bf16 v[0:3], v[188:191], v[226:229], v[0:3]
	s_setprio 0
	s_barrier
	s_add_i32 s34, s34, 2
	s_add_u32 s31, s31, 0x100
	s_addc_u32 s33, s33, 0
	s_add_u32 s0, s0, 0x100
	s_addc_u32 s1, s1, 0
	s_cmp_gt_u32 s34, 13
	s_cbranch_scc1 .Lkexit_1

; #define PG8_BAR __builtin_amdgcn_s_barrier()
; template <class Epi, class Sched, bool ALIGN_EPI = false, bool SP2 = false>
; __device__ __forceinline__ void gemm_phase(PG8_LAS unsigned char* lds, const Gemm g, const Sched& S, const Epi& E, int wave_in) {
;     ...
;         if constexpr (ALIGN_EPI) { if (wr == 0) PG8_BAR; }
.Lkexit_1:
	s_and_b64 vcc, exec, s[26:27]
	s_cbranch_vccz .LBB0_276
	s_barrier

; #define PG8_STAGE(bufoff, gbase, voff) do { _Pragma("unroll") for (int _i = 0; _i < 2; ++_i) \
;         __builtin_amdgcn_global_load_lds((const unsigned*)((const char*)(gbase) + (voff)[_i]), (PG8_LAS unsigned*)(lds + (bufoff) + ldsw + _i * 8192), 16, 0, 0); } while (0)
; #define PG8_LDA(dst, b, h) do { _Pragma("unroll") for (int m = 0; m < 4; ++m) _Pragma("unroll") for (int k = 0; k < 2; ++k) dst[m][k] = *(const PG8_LAS bf16x8*)(lds + PG8_SA(b, h) + aoff + m * 2048 + k * 1024); } while (0)
; #define PG8_LDB(dst, b, h) do { _Pragma("unroll") for (int n = 0; n < 2; ++n) _Pragma("unroll") for (int k = 0; k < 2; ++k) dst[n][k] = *(const PG8_LAS bf16x8*)(lds + PG8_SB(b, h) + boff + n * 2048 + k * 1024); } while (0)
; #define PG8_WAIT_V(n) asm volatile("s_waitcnt vmcnt(" #n ")" ::: "memory")
; template <class Epi, class Sched, bool ALIGN_EPI = false, bool SP2 = false>
; __device__ __forceinline__ void gemm_phase(PG8_LAS unsigned char* lds, const Gemm g, const Sched& S, const Epi& E, int wave_in) {
;     ...
;         const char* nA = has_next ? (const char*)g.A + (size_t)(nxt.pm >> g.ash) * g.astride + (size_t)nxt.pm * tstep : cA; const char* nB = has_next ? (const char*)g.Bt + (size_t)(nxt.pm >> g.bsh) * g.bstride + (size_t)nxt.pn * tstep : cB;
;         for (int t = 0; t < nt; t += 2) {
;             const bool last = (t == nt - 2);
;             const char* a1 = cA + (size_t)(t + 1) * kstep;
;             const char* a2 = last ? nA : cA + (size_t)(t + 2) * kstep; const char* b2 = last ? nB : cB + (size_t)(t + 2) * kstep;
;             const char* a3 = a2 + kstep; const char* b3 = b2 + kstep;
;             if (last && has_next) S.a_ready(nxt);
;             if constexpr (SP2) {
;             PG8_LDB(B0, 0, 0); PG8_LDB(B1, 0, 1); PG8_SCHED; PG8_LDA(At, 0, 0); PG8_STAGE(PG8_SA(1, 1), a1 + hstep, voffA);
;             PG8_WAIT_V(8); PG8_WAIT_L(0); PG8_BAR; PG8_MMA(0, 0, At, B0); PG8_MMA(0, 1, At, B1); PG8_BAR; PG8_SCHED;
;             PG8_LDA(At, 0, 1); PG8_STAGE(PG8_SB(0, 0), b2, voffB); PG8_STAGE(PG8_SB(0, 1), b2 + hstep, voffB); PG8_STAGE(PG8_SA(0, 0), a2, voffA);
;     ...
; #pragma unroll
;         for (int a = 0; a < 2; ++a)
; #pragma unroll
;             for (int b = 0; b < 2; ++b)
; #pragma unroll
;                 for (int m = 0; m < 4; ++m)
; #pragma unroll
;                     for (int n = 0; n < 2; ++n) acc[a][b][m][n] = (f32x4){0.f, 0.f, 0.f, 0.f};
.LBB0_484:
	s_ashr_i32 s15, s14, 31
	s_lshl_b64 s[16:17], s[14:15], 17
	s_add_u32 s16, s47, s16
	s_addc_u32 s17, s46, s17
	s_and_b64 s[18:19], s[10:11], exec
	s_cselect_b32 s15, s17, s25
	s_cselect_b32 s21, s16, s24
	s_ashr_i32 s13, s12, 31
	s_lshl_b64 s[18:19], s[12:13], 17
	s_add_u32 s18, s63, s18
	s_addc_u32 s19, s62, s19
	s_and_b64 s[38:39], s[10:11], exec
	s_cselect_b32 s13, s19, s23
	s_cselect_b32 s27, s18, s22
	s_mov_b32 s34, 0
	s_mov_b64 s[38:39], -1
	s_mov_b64 s[40:41], 0
	s_add_u32 s53, s24, s34
	s_addc_u32 s66, s25, 0
	s_add_u32 s44, s53, 0x100
	s_addc_u32 s45, s66, 0
	s_and_b64 s[42:43], s[40:41], exec
	s_cselect_b32 s45, s15, s45
	s_cselect_b32 s44, s21, s44
	s_add_u32 s34, s22, s34
	s_addc_u32 s42, s23, 0
	s_add_u32 s34, s34, 0x100
	s_addc_u32 s42, s42, 0
	s_add_i32 s97, s35, 0x100
	s_and_b64 s[40:41], s[40:41], exec
	s_cselect_b32 s61, s13, s42
	s_cselect_b32 s60, s27, s34
	s_add_i32 s41, s90, 0x100
	s_add_u32 s76, s53, 0x10080
	s_addc_u32 s77, s66, 0
	s_add_i32 s96, s97, s72
	s_add_i32 m0, s75, 0xc000
	s_add_i32 vcc_hi, s75, 0xe000
	s_add_i32 s81, s96, 0x2000
	s_add_u32 s66, s60, 0x10000
	v_add_u32_e32 v166, s97, v152
	v_add_u32_e32 v182, s41, v152
	s_addc_u32 s67, s61, 0
	s_add_i32 s95, s41, s72
	ds_read_b128 v[154:157], v166
	ds_read_b128 v[158:161], v166 offset:1024
	ds_read_b128 v[162:165], v166 offset:2048
	ds_read_b128 v[166:169], v166 offset:3072
	ds_read_b128 v[170:173], v182
	ds_read_b128 v[174:177], v182 offset:1024
	ds_read_b128 v[178:181], v182 offset:2048
	ds_read_b128 v[182:185], v182 offset:3072
	s_add_i32 s94, s95, 0x2000
	s_add_i32 s71, s65, 0x100
	s_add_i32 s69, s52, 0x100
	s_add_u32 s42, s44, 0x10000
	s_addc_u32 s43, s45, 0
	s_add_i32 s53, s71, s72
	s_add_i32 s34, s53, 0x2000
	s_add_u32 s40, s60, 0x10080
	s_addc_u32 s41, s61, 0
	s_add_i32 vcc_lo, s69, s72
	s_add_i32 s97, vcc_lo, 0x2000
	v_lshl_add_u64 v[190:191], s[76:77], 0, v[134:135]
	ds_read_b128 v[186:189], v153
	ds_read_b128 v[198:201], v153 offset:1024
	ds_read_b128 v[202:205], v153 offset:2048
	ds_read_b128 v[206:209], v153 offset:3072
	ds_read_b128 v[210:213], v153 offset:4096
	ds_read_b128 v[214:217], v153 offset:5120
	ds_read_b128 v[218:221], v153 offset:6144
	ds_read_b128 v[222:225], v153 offset:7168
	global_load_lds_dwordx4 v[190:191], off
	v_lshl_add_u64 v[190:191], s[76:77], 0, v[130:131]
	s_mov_b32 m0, vcc_hi
	s_nop 0
	global_load_lds_dwordx4 v[190:191], off
	s_waitcnt vmcnt(8)
	s_waitcnt lgkmcnt(0)
	s_barrier
	s_setprio 1
	s_waitcnt lgkmcnt(0)
	v_mfma_f32_16x16x32_bf16 v[124:127], v[154:157], v[186:189], 0
	v_mfma_f32_16x16x32_bf16 v[120:123], v[162:165], v[186:189], 0
	v_mfma_f32_16x16x32_bf16 v[116:119], v[154:157], v[202:205], 0
	v_mfma_f32_16x16x32_bf16 v[108:111], v[162:165], v[202:205], 0
	v_mfma_f32_16x16x32_bf16 v[100:103], v[154:157], v[210:213], 0
	v_mfma_f32_16x16x32_bf16 v[92:95], v[162:165], v[210:213], 0
	v_mfma_f32_16x16x32_bf16 v[84:87], v[154:157], v[218:221], 0
	v_mfma_f32_16x16x32_bf16 v[76:79], v[162:165], v[218:221], 0
	v_mfma_f32_16x16x32_bf16 v[124:127], v[158:161], v[198:201], v[124:127]
	v_mfma_f32_16x16x32_bf16 v[120:123], v[166:169], v[198:201], v[120:123]
	v_mfma_f32_16x16x32_bf16 v[116:119], v[158:161], v[206:209], v[116:119]
	v_mfma_f32_16x16x32_bf16 v[108:111], v[166:169], v[206:209], v[108:111]
	v_mfma_f32_16x16x32_bf16 v[100:103], v[158:161], v[214:217], v[100:103]
	v_mfma_f32_16x16x32_bf16 v[92:95], v[166:169], v[214:217], v[92:95]
	v_mfma_f32_16x16x32_bf16 v[84:87], v[158:161], v[222:225], v[84:87]
	v_mfma_f32_16x16x32_bf16 v[76:79], v[166:169], v[222:225], v[76:79]
	s_setprio 0
	s_setprio 1
	v_mfma_f32_16x16x32_bf16 v[112:115], v[170:173], v[186:189], 0
	v_mfma_f32_16x16x32_bf16 v[104:107], v[178:181], v[186:189], 0
	v_mfma_f32_16x16x32_bf16 v[96:99], v[170:173], v[202:205], 0
	v_mfma_f32_16x16x32_bf16 v[88:91], v[178:181], v[202:205], 0
	v_mfma_f32_16x16x32_bf16 v[80:83], v[170:173], v[210:213], 0
	v_mfma_f32_16x16x32_bf16 v[72:75], v[178:181], v[210:213], 0
	v_mfma_f32_16x16x32_bf16 v[68:71], v[170:173], v[218:221], 0
	v_mfma_f32_16x16x32_bf16 v[64:67], v[178:181], v[218:221], 0
	v_mfma_f32_16x16x32_bf16 v[112:115], v[174:177], v[198:201], v[112:115]
	v_mfma_f32_16x16x32_bf16 v[104:107], v[182:185], v[198:201], v[104:107]
	v_mfma_f32_16x16x32_bf16 v[96:99], v[174:177], v[206:209], v[96:99]
	v_mfma_f32_16x16x32_bf16 v[88:91], v[182:185], v[206:209], v[88:91]
	v_mfma_f32_16x16x32_bf16 v[80:83], v[174:177], v[214:217], v[80:83]
	v_mfma_f32_16x16x32_bf16 v[72:75], v[182:185], v[214:217], v[72:75]
	v_mfma_f32_16x16x32_bf16 v[68:71], v[174:177], v[222:225], v[68:71]
	v_mfma_f32_16x16x32_bf16 v[64:67], v[182:185], v[222:225], v[64:67]
	s_setprio 0
	s_barrier
	s_mov_b32 m0, s96
	v_lshl_add_u64 v[190:191], s[60:61], 0, v[132:133]
	ds_read_b128 v[186:189], v153 offset:16384
	ds_read_b128 v[198:201], v153 offset:17408
	ds_read_b128 v[202:205], v153 offset:18432
	ds_read_b128 v[206:209], v153 offset:19456
	ds_read_b128 v[210:213], v153 offset:20480
	ds_read_b128 v[214:217], v153 offset:21504
	ds_read_b128 v[218:221], v153 offset:22528
	ds_read_b128 v[222:225], v153 offset:23552
	global_load_lds_dwordx4 v[190:191], off
	v_lshl_add_u64 v[226:227], s[60:61], 0, v[128:129]
	s_mov_b32 m0, s81
	v_lshl_add_u64 v[228:229], s[66:67], 0, v[132:133]
	global_load_lds_dwordx4 v[226:227], off
	s_mov_b32 m0, s95
	v_lshl_add_u64 v[230:231], s[44:45], 0, v[130:131]
	global_load_lds_dwordx4 v[228:229], off
	v_lshl_add_u64 v[228:229], s[66:67], 0, v[128:129]
	s_mov_b32 m0, s94
	s_nop 0
	global_load_lds_dwordx4 v[228:229], off
	v_lshl_add_u64 v[228:229], s[44:45], 0, v[134:135]
	s_mov_b32 m0, s75
	s_nop 0
	global_load_lds_dwordx4 v[228:229], off
	s_mov_b32 m0, s78
	s_nop 0
	global_load_lds_dwordx4 v[230:231], off
	s_waitcnt vmcnt(8)
	s_waitcnt lgkmcnt(0)
	s_barrier
; #define PG8_STAGE(bufoff, gbase, voff) do { _Pragma("unroll") for (int _i = 0; _i < 2; ++_i) \
;         __builtin_amdgcn_global_load_lds((const unsigned*)((const char*)(gbase) + (voff)[_i]), (PG8_LAS unsigned*)(lds + (bufoff) + ldsw + _i * 8192), 16, 0, 0); } while (0)
; #define PG8_LDA(dst, b, h) do { _Pragma("unroll") for (int m = 0; m < 4; ++m) _Pragma("unroll") for (int k = 0; k < 2; ++k) dst[m][k] = *(const PG8_LAS bf16x8*)(lds + PG8_SA(b, h) + aoff + m * 2048 + k * 1024); } while (0)
; #define PG8_LDB(dst, b, h) do { _Pragma("unroll") for (int n = 0; n < 2; ++n) _Pragma("unroll") for (int k = 0; k < 2; ++k) dst[n][k] = *(const PG8_LAS bf16x8*)(lds + PG8_SB(b, h) + boff + n * 2048 + k * 1024); } while (0)
; #define PG8_MMA(ai, bj, At, Bt) do { __builtin_amdgcn_s_setprio(1); _Pragma("unroll") for (int m = 0; m < 4; ++m) _Pragma("unroll") for (int n = 0; n < 2; ++n) _Pragma("unroll") for (int k = 0; k < 2; ++k) \
;         acc[ai][bj][m][n] = __builtin_amdgcn_mfma_f32_16x16x32_bf16(Bt[n][k], At[m][k], acc[ai][bj][m][n], 0, 0, 0); __builtin_amdgcn_s_setprio(0); } while (0)
; #define PG8_WAIT_V(n) asm volatile("s_waitcnt vmcnt(" #n ")" ::: "memory")
; #define PG8_WAIT_L(n) asm volatile("s_waitcnt lgkmcnt(" #n ")" ::: "memory")
; #define PG8_BAR __builtin_amdgcn_s_barrier()
; #define PG8_SCHED __builtin_amdgcn_sched_barrier(0)
; template <class Epi, class Sched, bool ALIGN_EPI = false, bool SP2 = false>
; __device__ __forceinline__ void gemm_phase(PG8_LAS unsigned char* lds, const Gemm g, const Sched& S, const Epi& E, int wave_in) {
;     ...
;             PG8_WAIT_V(8); PG8_WAIT_L(0); PG8_BAR; PG8_MMA(1, 0, At, B0); PG8_MMA(1, 1, At, B1); PG8_BAR; PG8_SCHED;
;             PG8_LDB(B0, 1, 0); PG8_LDB(B1, 1, 1); PG8_SCHED; PG8_LDA(At, 1, 0); PG8_STAGE(PG8_SA(0, 1), a2 + hstep, voffA);
;             PG8_WAIT_V(8); PG8_WAIT_L(0); PG8_BAR; PG8_MMA(0, 0, At, B0); PG8_MMA(0, 1, At, B1); PG8_BAR; PG8_SCHED;
	s_setprio 1
	s_waitcnt lgkmcnt(0)
	v_mfma_f32_16x16x32_bf16 v[60:63], v[154:157], v[186:189], 0
	v_mfma_f32_16x16x32_bf16 v[56:59], v[162:165], v[186:189], 0
	v_mfma_f32_16x16x32_bf16 v[52:55], v[154:157], v[202:205], 0
	v_mfma_f32_16x16x32_bf16 v[44:47], v[162:165], v[202:205], 0
	v_mfma_f32_16x16x32_bf16 v[36:39], v[154:157], v[210:213], 0
	v_mfma_f32_16x16x32_bf16 v[28:31], v[162:165], v[210:213], 0
	v_mfma_f32_16x16x32_bf16 v[20:23], v[154:157], v[218:221], 0
	v_mfma_f32_16x16x32_bf16 v[12:15], v[162:165], v[218:221], 0
	v_mfma_f32_16x16x32_bf16 v[60:63], v[158:161], v[198:201], v[60:63]
	v_mfma_f32_16x16x32_bf16 v[56:59], v[166:169], v[198:201], v[56:59]
	v_mfma_f32_16x16x32_bf16 v[52:55], v[158:161], v[206:209], v[52:55]
	v_mfma_f32_16x16x32_bf16 v[44:47], v[166:169], v[206:209], v[44:47]
	v_mfma_f32_16x16x32_bf16 v[36:39], v[158:161], v[214:217], v[36:39]
	v_mfma_f32_16x16x32_bf16 v[28:31], v[166:169], v[214:217], v[28:31]
	v_mfma_f32_16x16x32_bf16 v[20:23], v[158:161], v[222:225], v[20:23]
	v_mfma_f32_16x16x32_bf16 v[12:15], v[166:169], v[222:225], v[12:15]
	s_setprio 0
	s_setprio 1
	v_mfma_f32_16x16x32_bf16 v[48:51], v[170:173], v[186:189], 0
	v_mfma_f32_16x16x32_bf16 v[40:43], v[178:181], v[186:189], 0
	v_mfma_f32_16x16x32_bf16 v[32:35], v[170:173], v[202:205], 0
	v_mfma_f32_16x16x32_bf16 v[24:27], v[178:181], v[202:205], 0
	v_mfma_f32_16x16x32_bf16 v[16:19], v[170:173], v[210:213], 0
	v_mfma_f32_16x16x32_bf16 v[8:11], v[178:181], v[210:213], 0
	v_mfma_f32_16x16x32_bf16 v[4:7], v[170:173], v[218:221], 0
	v_mfma_f32_16x16x32_bf16 v[0:3], v[178:181], v[218:221], 0
	v_mfma_f32_16x16x32_bf16 v[48:51], v[174:177], v[198:201], v[48:51]
	v_mfma_f32_16x16x32_bf16 v[40:43], v[182:185], v[198:201], v[40:43]
	v_mfma_f32_16x16x32_bf16 v[32:35], v[174:177], v[206:209], v[32:35]
	v_mfma_f32_16x16x32_bf16 v[24:27], v[182:185], v[206:209], v[24:27]
	v_mfma_f32_16x16x32_bf16 v[16:19], v[174:177], v[214:217], v[16:19]
	v_mfma_f32_16x16x32_bf16 v[8:11], v[182:185], v[214:217], v[8:11]
	v_mfma_f32_16x16x32_bf16 v[4:7], v[174:177], v[222:225], v[4:7]
	v_mfma_f32_16x16x32_bf16 v[0:3], v[182:185], v[222:225], v[0:3]
	s_setprio 0
	s_barrier
	v_add_u32_e32 v166, s71, v152
	v_add_u32_e32 v182, s69, v152
	ds_read_b128 v[154:157], v166
	ds_read_b128 v[158:161], v166 offset:1024
	ds_read_b128 v[162:165], v166 offset:2048
	ds_read_b128 v[166:169], v166 offset:3072
	ds_read_b128 v[170:173], v182
	ds_read_b128 v[174:177], v182 offset:1024
	ds_read_b128 v[178:181], v182 offset:2048
	ds_read_b128 v[182:185], v182 offset:3072
	s_mov_b32 m0, s79
	v_lshl_add_u64 v[232:233], s[42:43], 0, v[134:135]
	ds_read_b128 v[186:189], v153 offset:32768
	ds_read_b128 v[198:201], v153 offset:33792
	ds_read_b128 v[202:205], v153 offset:34816
	ds_read_b128 v[206:209], v153 offset:35840
	ds_read_b128 v[210:213], v153 offset:36864
	ds_read_b128 v[214:217], v153 offset:37888
	ds_read_b128 v[218:221], v153 offset:38912
	ds_read_b128 v[222:225], v153 offset:39936
	global_load_lds_dwordx4 v[232:233], off
	v_lshl_add_u64 v[232:233], s[42:43], 0, v[130:131]
	s_mov_b32 m0, s82
	s_nop 0
	global_load_lds_dwordx4 v[232:233], off
	s_waitcnt vmcnt(8)
	s_waitcnt lgkmcnt(0)
	s_barrier
	s_setprio 1
	s_waitcnt lgkmcnt(0)
	v_mfma_f32_16x16x32_bf16 v[124:127], v[154:157], v[186:189], v[124:127]
	v_mfma_f32_16x16x32_bf16 v[120:123], v[162:165], v[186:189], v[120:123]
	v_mfma_f32_16x16x32_bf16 v[116:119], v[154:157], v[202:205], v[116:119]
	v_mfma_f32_16x16x32_bf16 v[108:111], v[162:165], v[202:205], v[108:111]
	v_mfma_f32_16x16x32_bf16 v[100:103], v[154:157], v[210:213], v[100:103]
	v_mfma_f32_16x16x32_bf16 v[92:95], v[162:165], v[210:213], v[92:95]
	v_mfma_f32_16x16x32_bf16 v[84:87], v[154:157], v[218:221], v[84:87]
	v_mfma_f32_16x16x32_bf16 v[76:79], v[162:165], v[218:221], v[76:79]
	v_mfma_f32_16x16x32_bf16 v[124:127], v[158:161], v[198:201], v[124:127]
	v_mfma_f32_16x16x32_bf16 v[120:123], v[166:169], v[198:201], v[120:123]
	v_mfma_f32_16x16x32_bf16 v[116:119], v[158:161], v[206:209], v[116:119]
	v_mfma_f32_16x16x32_bf16 v[108:111], v[166:169], v[206:209], v[108:111]
	v_mfma_f32_16x16x32_bf16 v[100:103], v[158:161], v[214:217], v[100:103]
	v_mfma_f32_16x16x32_bf16 v[92:95], v[166:169], v[214:217], v[92:95]
	v_mfma_f32_16x16x32_bf16 v[84:87], v[158:161], v[222:225], v[84:87]
	v_mfma_f32_16x16x32_bf16 v[76:79], v[166:169], v[222:225], v[76:79]
	s_setprio 0
	s_setprio 1
	v_mfma_f32_16x16x32_bf16 v[112:115], v[170:173], v[186:189], v[112:115]
	v_mfma_f32_16x16x32_bf16 v[104:107], v[178:181], v[186:189], v[104:107]
	v_mfma_f32_16x16x32_bf16 v[96:99], v[170:173], v[202:205], v[96:99]
	v_mfma_f32_16x16x32_bf16 v[88:91], v[178:181], v[202:205], v[88:91]
	v_mfma_f32_16x16x32_bf16 v[80:83], v[170:173], v[210:213], v[80:83]
	v_mfma_f32_16x16x32_bf16 v[72:75], v[178:181], v[210:213], v[72:75]
	v_mfma_f32_16x16x32_bf16 v[68:71], v[170:173], v[218:221], v[68:71]
	v_mfma_f32_16x16x32_bf16 v[64:67], v[178:181], v[218:221], v[64:67]
	v_mfma_f32_16x16x32_bf16 v[112:115], v[174:177], v[198:201], v[112:115]
	v_mfma_f32_16x16x32_bf16 v[104:107], v[182:185], v[198:201], v[104:107]
	v_mfma_f32_16x16x32_bf16 v[96:99], v[174:177], v[206:209], v[96:99]
	v_mfma_f32_16x16x32_bf16 v[88:91], v[182:185], v[206:209], v[88:91]
	v_mfma_f32_16x16x32_bf16 v[80:83], v[174:177], v[214:217], v[80:83]
	v_mfma_f32_16x16x32_bf16 v[72:75], v[182:185], v[214:217], v[72:75]
	v_mfma_f32_16x16x32_bf16 v[68:71], v[174:177], v[222:225], v[68:71]
	v_mfma_f32_16x16x32_bf16 v[64:67], v[182:185], v[222:225], v[64:67]
	s_setprio 0
	s_barrier
; #define PG8_STAGE(bufoff, gbase, voff) do { _Pragma("unroll") for (int _i = 0; _i < 2; ++_i) \
;         __builtin_amdgcn_global_load_lds((const unsigned*)((const char*)(gbase) + (voff)[_i]), (PG8_LAS unsigned*)(lds + (bufoff) + ldsw + _i * 8192), 16, 0, 0); } while (0)
; #define PG8_LDA(dst, b, h) do { _Pragma("unroll") for (int m = 0; m < 4; ++m) _Pragma("unroll") for (int k = 0; k < 2; ++k) dst[m][k] = *(const PG8_LAS bf16x8*)(lds + PG8_SA(b, h) + aoff + m * 2048 + k * 1024); } while (0)
; #define PG8_WAIT_V(n) asm volatile("s_waitcnt vmcnt(" #n ")" ::: "memory")
; #define PG8_WAIT_L(n) asm volatile("s_waitcnt lgkmcnt(" #n ")" ::: "memory")
; #define PG8_BAR __builtin_amdgcn_s_barrier()
; template <class Epi, class Sched, bool ALIGN_EPI = false, bool SP2 = false>
; __device__ __forceinline__ void gemm_phase(PG8_LAS unsigned char* lds, const Gemm g, const Sched& S, const Epi& E, int wave_in) {
;     ...
;         for (int t = 0; t < nt; t += 2) {
;             const bool last = (t == nt - 2);
;             const char* a1 = cA + (size_t)(t + 1) * kstep;
;             const char* a2 = last ? nA : cA + (size_t)(t + 2) * kstep; const char* b2 = last ? nB : cB + (size_t)(t + 2) * kstep;
;             const char* a3 = a2 + kstep; const char* b3 = b2 + kstep;
;             if (last && has_next) S.a_ready(nxt);
;             if constexpr (SP2) {
;             PG8_LDB(B0, 0, 0); PG8_LDB(B1, 0, 1); PG8_SCHED; PG8_LDA(At, 0, 0); PG8_STAGE(PG8_SA(1, 1), a1 + hstep, voffA);
;             PG8_WAIT_V(8); PG8_WAIT_L(0); PG8_BAR; PG8_MMA(0, 0, At, B0); PG8_MMA(0, 1, At, B1); PG8_BAR; PG8_SCHED;
;             PG8_LDA(At, 0, 1); PG8_STAGE(PG8_SB(0, 0), b2, voffB); PG8_STAGE(PG8_SB(0, 1), b2 + hstep, voffB); PG8_STAGE(PG8_SA(0, 0), a2, voffA);
;             PG8_WAIT_V(8); PG8_WAIT_L(0); PG8_BAR; PG8_MMA(1, 0, At, B0); PG8_MMA(1, 1, At, B1); PG8_BAR; PG8_SCHED;
;             PG8_LDB(B0, 1, 0); PG8_LDB(B1, 1, 1); PG8_SCHED; PG8_LDA(At, 1, 0); PG8_STAGE(PG8_SA(0, 1), a2 + hstep, voffA);
;             PG8_WAIT_V(8); PG8_WAIT_L(0); PG8_BAR; PG8_MMA(0, 0, At, B0); PG8_MMA(0, 1, At, B1); PG8_BAR; PG8_SCHED;
;             PG8_LDA(At, 1, 1); PG8_STAGE(PG8_SB(1, 0), b3, voffB); PG8_STAGE(PG8_SB(1, 1), b3 + hstep, voffB); PG8_STAGE(PG8_SA(1, 0), a3, voffA);
;             PG8_WAIT_V(8); PG8_WAIT_L(0); PG8_BAR; PG8_MMA(1, 0, At, B0); PG8_MMA(1, 1, At, B1); PG8_BAR; PG8_SCHED;
	s_mov_b32 m0, s53
	v_lshl_add_u64 v[190:191], v[190:191], 0, s[88:89]
	ds_read_b128 v[186:189], v153 offset:49152
	ds_read_b128 v[198:201], v153 offset:50176
	ds_read_b128 v[202:205], v153 offset:51200
	ds_read_b128 v[206:209], v153 offset:52224
	ds_read_b128 v[210:213], v153 offset:53248
	ds_read_b128 v[214:217], v153 offset:54272
	ds_read_b128 v[218:221], v153 offset:55296
	ds_read_b128 v[222:225], v153 offset:56320
	global_load_lds_dwordx4 v[190:191], off
	v_lshl_add_u64 v[190:191], v[226:227], 0, s[88:89]
	s_mov_b32 m0, s34
	s_nop 0
	global_load_lds_dwordx4 v[190:191], off
	v_lshl_add_u64 v[190:191], s[40:41], 0, v[132:133]
	s_mov_b32 m0, vcc_lo
	s_nop 0
	global_load_lds_dwordx4 v[190:191], off
	v_lshl_add_u64 v[190:191], s[40:41], 0, v[128:129]
	s_mov_b32 m0, s97
	s_nop 0
	global_load_lds_dwordx4 v[190:191], off
	v_lshl_add_u64 v[190:191], v[228:229], 0, s[88:89]
	s_mov_b32 m0, s85
	s_nop 0
	global_load_lds_dwordx4 v[190:191], off
	v_lshl_add_u64 v[190:191], v[230:231], 0, s[88:89]
	s_mov_b32 m0, s92
	s_nop 0
	global_load_lds_dwordx4 v[190:191], off
	s_waitcnt vmcnt(8)
	s_waitcnt lgkmcnt(0)
	s_barrier
	s_setprio 1
	s_waitcnt lgkmcnt(0)
	v_mfma_f32_16x16x32_bf16 v[60:63], v[154:157], v[186:189], v[60:63]
	v_mfma_f32_16x16x32_bf16 v[56:59], v[162:165], v[186:189], v[56:59]
	v_mfma_f32_16x16x32_bf16 v[52:55], v[154:157], v[202:205], v[52:55]
	v_mfma_f32_16x16x32_bf16 v[44:47], v[162:165], v[202:205], v[44:47]
	v_mfma_f32_16x16x32_bf16 v[36:39], v[154:157], v[210:213], v[36:39]
	v_mfma_f32_16x16x32_bf16 v[28:31], v[162:165], v[210:213], v[28:31]
	v_mfma_f32_16x16x32_bf16 v[20:23], v[154:157], v[218:221], v[20:23]
	v_mfma_f32_16x16x32_bf16 v[12:15], v[162:165], v[218:221], v[12:15]
	v_mfma_f32_16x16x32_bf16 v[60:63], v[158:161], v[198:201], v[60:63]
	v_mfma_f32_16x16x32_bf16 v[56:59], v[166:169], v[198:201], v[56:59]
	v_mfma_f32_16x16x32_bf16 v[52:55], v[158:161], v[206:209], v[52:55]
	v_mfma_f32_16x16x32_bf16 v[44:47], v[166:169], v[206:209], v[44:47]
	v_mfma_f32_16x16x32_bf16 v[36:39], v[158:161], v[214:217], v[36:39]
	v_mfma_f32_16x16x32_bf16 v[28:31], v[166:169], v[214:217], v[28:31]
	v_mfma_f32_16x16x32_bf16 v[20:23], v[158:161], v[222:225], v[20:23]
	v_mfma_f32_16x16x32_bf16 v[12:15], v[166:169], v[222:225], v[12:15]
	s_setprio 0
	s_setprio 1
	v_mfma_f32_16x16x32_bf16 v[48:51], v[170:173], v[186:189], v[48:51]
	v_mfma_f32_16x16x32_bf16 v[40:43], v[178:181], v[186:189], v[40:43]
	v_mfma_f32_16x16x32_bf16 v[32:35], v[170:173], v[202:205], v[32:35]
	v_mfma_f32_16x16x32_bf16 v[24:27], v[178:181], v[202:205], v[24:27]
	v_mfma_f32_16x16x32_bf16 v[16:19], v[170:173], v[210:213], v[16:19]
	v_mfma_f32_16x16x32_bf16 v[8:11], v[178:181], v[210:213], v[8:11]
	v_mfma_f32_16x16x32_bf16 v[4:7], v[170:173], v[218:221], v[4:7]
	v_mfma_f32_16x16x32_bf16 v[0:3], v[178:181], v[218:221], v[0:3]
	v_mfma_f32_16x16x32_bf16 v[48:51], v[174:177], v[198:201], v[48:51]
	v_mfma_f32_16x16x32_bf16 v[40:43], v[182:185], v[198:201], v[40:43]
	v_mfma_f32_16x16x32_bf16 v[32:35], v[174:177], v[206:209], v[32:35]
	v_mfma_f32_16x16x32_bf16 v[24:27], v[182:185], v[206:209], v[24:27]
	v_mfma_f32_16x16x32_bf16 v[16:19], v[174:177], v[214:217], v[16:19]
	v_mfma_f32_16x16x32_bf16 v[8:11], v[182:185], v[214:217], v[8:11]
	v_mfma_f32_16x16x32_bf16 v[4:7], v[174:177], v[222:225], v[4:7]
	v_mfma_f32_16x16x32_bf16 v[0:3], v[182:185], v[222:225], v[0:3]
	s_setprio 0
	s_barrier
	s_movk_i32 s34, 0x100
	s_andn2_b64 vcc, exec, s[38:39]
	s_mov_b64 s[40:41], -1
	s_mov_b64 s[38:39], 0
	s_cbranch_vccnz .Lkexit_2

; #define PG8_BAR __builtin_amdgcn_s_barrier()
; template <class Epi, class Sched, bool ALIGN_EPI = false, bool SP2 = false>
; __device__ __forceinline__ void gemm_phase(PG8_LAS unsigned char* lds, const Gemm g, const Sched& S, const Epi& E, int wave_in) {
;     ...
;         if constexpr (ALIGN_EPI) { if (wr == 0) PG8_BAR; }
.Lkexit_2:
	s_and_b64 vcc, exec, s[4:5]
	s_cbranch_vccz .LBB0_488
	s_barrier

; #define PG8_STAGE(bufoff, gbase, voff) do { _Pragma("unroll") for (int _i = 0; _i < 2; ++_i) \
;         __builtin_amdgcn_global_load_lds((const unsigned*)((const char*)(gbase) + (voff)[_i]), (PG8_LAS unsigned*)(lds + (bufoff) + ldsw + _i * 8192), 16, 0, 0); } while (0)
; #define PG8_LDA(dst, b, h) do { _Pragma("unroll") for (int m = 0; m < 4; ++m) _Pragma("unroll") for (int k = 0; k < 2; ++k) dst[m][k] = *(const PG8_LAS bf16x8*)(lds + PG8_SA(b, h) + aoff + m * 2048 + k * 1024); } while (0)
; #define PG8_LDB(dst, b, h) do { _Pragma("unroll") for (int n = 0; n < 2; ++n) _Pragma("unroll") for (int k = 0; k < 2; ++k) dst[n][k] = *(const PG8_LAS bf16x8*)(lds + PG8_SB(b, h) + boff + n * 2048 + k * 1024); } while (0)
; #define PG8_WAIT_V(n) asm volatile("s_waitcnt vmcnt(" #n ")" ::: "memory")
; template <class Epi, class Sched, bool ALIGN_EPI = false, bool SP2 = false>
; __device__ __forceinline__ void gemm_phase(PG8_LAS unsigned char* lds, const Gemm g, const Sched& S, const Epi& E, int wave_in) {
;     ...
;         const char* nA = has_next ? (const char*)g.A + (size_t)(nxt.pm >> g.ash) * g.astride + (size_t)nxt.pm * tstep : cA; const char* nB = has_next ? (const char*)g.Bt + (size_t)(nxt.pm >> g.bsh) * g.bstride + (size_t)nxt.pn * tstep : cB;
;         for (int t = 0; t < nt; t += 2) {
;             const bool last = (t == nt - 2);
;             const char* a1 = cA + (size_t)(t + 1) * kstep;
;             const char* a2 = last ? nA : cA + (size_t)(t + 2) * kstep; const char* b2 = last ? nB : cB + (size_t)(t + 2) * kstep;
;             const char* a3 = a2 + kstep; const char* b3 = b2 + kstep;
;             if (last && has_next) S.a_ready(nxt);
;             if constexpr (SP2) {
;             PG8_LDB(B0, 0, 0); PG8_LDB(B1, 0, 1); PG8_SCHED; PG8_LDA(At, 0, 0); PG8_STAGE(PG8_SA(1, 1), a1 + hstep, voffA);
;             PG8_WAIT_V(8); PG8_WAIT_L(0); PG8_BAR; PG8_MMA(0, 0, At, B0); PG8_MMA(0, 1, At, B1); PG8_BAR; PG8_SCHED;
;             PG8_LDA(At, 0, 1); PG8_STAGE(PG8_SB(0, 0), b2, voffB); PG8_STAGE(PG8_SB(0, 1), b2 + hstep, voffB); PG8_STAGE(PG8_SA(0, 0), a2, voffA);
;     ...
; #pragma unroll
;         for (int a = 0; a < 2; ++a)
; #pragma unroll
;             for (int b = 0; b < 2; ++b)
; #pragma unroll
;                 for (int m = 0; m < 4; ++m)
; #pragma unroll
;                     for (int n = 0; n < 2; ++n) acc[a][b][m][n] = (f32x4){0.f, 0.f, 0.f, 0.f};
.LBB0_589:
	s_ashr_i32 s15, s14, 31
	s_lshl_b64 s[20:21], s[14:15], 19
	s_add_u32 s20, s31, s20
	s_addc_u32 s21, s33, s21
	s_and_b64 s[26:27], s[44:45], exec
	s_cselect_b32 s15, s21, s23
	s_cselect_b32 s17, s20, s22
	s_add_u32 s34, s22, 0x100
	s_addc_u32 s44, s23, 0
	s_add_u32 s22, s24, 0x40080
	s_addc_u32 s23, s25, 0
	s_mov_b32 s45, -2
	s_add_u32 s24, s22, 0xfffc0080
	s_addc_u32 s25, s23, -1
	s_add_i32 s53, s35, 0x100
	s_cmp_eq_u32 s45, 12
	s_cselect_b32 s27, s19, s25
	s_cselect_b32 s26, s18, s24
	s_cselect_b32 s25, s15, s44
	s_cselect_b32 s24, s17, s34
	s_add_i32 s69, s90, 0x100
	v_add_u32_e32 v128, s53, v249
	v_add_u32_e32 v156, s69, v249
	ds_read_b128 v[112:115], v128
	ds_read_b128 v[120:123], v128 offset:1024
	ds_read_b128 v[124:127], v128 offset:2048
	ds_read_b128 v[128:131], v128 offset:3072
	ds_read_b128 v[136:139], v156
	ds_read_b128 v[140:143], v156 offset:1024
	ds_read_b128 v[144:147], v156 offset:2048
	ds_read_b128 v[156:159], v156 offset:3072
	v_lshl_add_u64 v[208:209], s[22:23], 0, v[206:207]
	s_add_i32 m0, s39, 0xc000
	ds_read_b128 v[160:163], v251
	ds_read_b128 v[164:167], v251 offset:1024
	ds_read_b128 v[168:171], v251 offset:2048
	ds_read_b128 v[172:175], v251 offset:3072
	ds_read_b128 v[176:179], v251 offset:4096
	ds_read_b128 v[180:183], v251 offset:5120
	ds_read_b128 v[184:187], v251 offset:6144
	ds_read_b128 v[188:191], v251 offset:7168
	global_load_lds_dwordx4 v[208:209], off
	v_lshl_add_u64 v[208:209], s[22:23], 0, v[204:205]
	s_add_i32 m0, s39, 0xe000
	s_nop 0
	global_load_lds_dwordx4 v[208:209], off
	s_waitcnt vmcnt(8)
	s_waitcnt lgkmcnt(0)
	s_barrier
	s_setprio 1
	s_waitcnt lgkmcnt(0)
	v_mfma_f32_16x16x32_bf16 v[152:155], v[112:115], v[160:163], 0
	v_mfma_f32_16x16x32_bf16 v[148:151], v[124:127], v[160:163], 0
	v_mfma_f32_16x16x32_bf16 v[108:111], v[112:115], v[168:171], 0
	v_mfma_f32_16x16x32_bf16 v[104:107], v[124:127], v[168:171], 0
	v_mfma_f32_16x16x32_bf16 v[92:95], v[112:115], v[176:179], 0
	v_mfma_f32_16x16x32_bf16 v[88:91], v[124:127], v[176:179], 0
	v_mfma_f32_16x16x32_bf16 v[76:79], v[112:115], v[184:187], 0
	v_mfma_f32_16x16x32_bf16 v[72:75], v[124:127], v[184:187], 0
	v_mfma_f32_16x16x32_bf16 v[152:155], v[120:123], v[164:167], v[152:155]
	v_mfma_f32_16x16x32_bf16 v[148:151], v[128:131], v[164:167], v[148:151]
	v_mfma_f32_16x16x32_bf16 v[108:111], v[120:123], v[172:175], v[108:111]
	v_mfma_f32_16x16x32_bf16 v[104:107], v[128:131], v[172:175], v[104:107]
	v_mfma_f32_16x16x32_bf16 v[92:95], v[120:123], v[180:183], v[92:95]
	v_mfma_f32_16x16x32_bf16 v[88:91], v[128:131], v[180:183], v[88:91]
	v_mfma_f32_16x16x32_bf16 v[76:79], v[120:123], v[188:191], v[76:79]
	v_mfma_f32_16x16x32_bf16 v[72:75], v[128:131], v[188:191], v[72:75]
	s_setprio 0
	s_setprio 1
	v_mfma_f32_16x16x32_bf16 v[132:135], v[136:139], v[160:163], 0
	v_mfma_f32_16x16x32_bf16 v[116:119], v[144:147], v[160:163], 0
	v_mfma_f32_16x16x32_bf16 v[100:103], v[136:139], v[168:171], 0
	v_mfma_f32_16x16x32_bf16 v[96:99], v[144:147], v[168:171], 0
	v_mfma_f32_16x16x32_bf16 v[84:87], v[136:139], v[176:179], 0
	v_mfma_f32_16x16x32_bf16 v[80:83], v[144:147], v[176:179], 0
	v_mfma_f32_16x16x32_bf16 v[68:71], v[136:139], v[184:187], 0
	v_mfma_f32_16x16x32_bf16 v[64:67], v[144:147], v[184:187], 0
	v_mfma_f32_16x16x32_bf16 v[132:135], v[140:143], v[164:167], v[132:135]
	v_mfma_f32_16x16x32_bf16 v[116:119], v[156:159], v[164:167], v[116:119]
	v_mfma_f32_16x16x32_bf16 v[100:103], v[140:143], v[172:175], v[100:103]
	v_mfma_f32_16x16x32_bf16 v[96:99], v[156:159], v[172:175], v[96:99]
	v_mfma_f32_16x16x32_bf16 v[84:87], v[140:143], v[180:183], v[84:87]
	v_mfma_f32_16x16x32_bf16 v[80:83], v[156:159], v[180:183], v[80:83]
	v_mfma_f32_16x16x32_bf16 v[68:71], v[140:143], v[188:191], v[68:71]
	v_mfma_f32_16x16x32_bf16 v[64:67], v[156:159], v[188:191], v[64:67]
	s_setprio 0
	s_barrier
	s_add_i32 s53, s53, s38
	v_lshl_add_u64 v[208:209], s[24:25], 0, v[192:193]
	s_mov_b32 m0, s53
	ds_read_b128 v[160:163], v251 offset:16384
	ds_read_b128 v[164:167], v251 offset:17408
	ds_read_b128 v[168:171], v251 offset:18432
	ds_read_b128 v[172:175], v251 offset:19456
	ds_read_b128 v[176:179], v251 offset:20480
	ds_read_b128 v[180:183], v251 offset:21504
	ds_read_b128 v[184:187], v251 offset:22528
	ds_read_b128 v[188:191], v251 offset:23552
	global_load_lds_dwordx4 v[208:209], off
	s_add_i32 m0, s53, 0x2000
	s_add_u32 s72, s24, 0x40000
	v_lshl_add_u64 v[210:211], s[24:25], 0, v[198:199]
	s_addc_u32 s73, s25, 0
	s_add_i32 s53, s69, s38
	global_load_lds_dwordx4 v[210:211], off
	v_lshl_add_u64 v[212:213], s[72:73], 0, v[192:193]
	s_mov_b32 m0, s53
	v_lshl_add_u64 v[214:215], s[26:27], 0, v[200:201]
	global_load_lds_dwordx4 v[212:213], off
	v_lshl_add_u64 v[212:213], s[72:73], 0, v[198:199]
	s_add_i32 m0, s53, 0x2000
	s_nop 0
	global_load_lds_dwordx4 v[212:213], off
	v_lshl_add_u64 v[212:213], s[26:27], 0, v[202:203]
	s_mov_b32 m0, s39
	s_nop 0
	global_load_lds_dwordx4 v[212:213], off
	s_mov_b32 m0, s46
	s_nop 0
	global_load_lds_dwordx4 v[214:215], off
	s_waitcnt vmcnt(8)
	s_waitcnt lgkmcnt(0)
	s_barrier
; #define PG8_STAGE(bufoff, gbase, voff) do { _Pragma("unroll") for (int _i = 0; _i < 2; ++_i) \
;         __builtin_amdgcn_global_load_lds((const unsigned*)((const char*)(gbase) + (voff)[_i]), (PG8_LAS unsigned*)(lds + (bufoff) + ldsw + _i * 8192), 16, 0, 0); } while (0)
; #define PG8_LDA(dst, b, h) do { _Pragma("unroll") for (int m = 0; m < 4; ++m) _Pragma("unroll") for (int k = 0; k < 2; ++k) dst[m][k] = *(const PG8_LAS bf16x8*)(lds + PG8_SA(b, h) + aoff + m * 2048 + k * 1024); } while (0)
; #define PG8_LDB(dst, b, h) do { _Pragma("unroll") for (int n = 0; n < 2; ++n) _Pragma("unroll") for (int k = 0; k < 2; ++k) dst[n][k] = *(const PG8_LAS bf16x8*)(lds + PG8_SB(b, h) + boff + n * 2048 + k * 1024); } while (0)
; #define PG8_MMA(ai, bj, At, Bt) do { __builtin_amdgcn_s_setprio(1); _Pragma("unroll") for (int m = 0; m < 4; ++m) _Pragma("unroll") for (int n = 0; n < 2; ++n) _Pragma("unroll") for (int k = 0; k < 2; ++k) \
;         acc[ai][bj][m][n] = __builtin_amdgcn_mfma_f32_16x16x32_bf16(Bt[n][k], At[m][k], acc[ai][bj][m][n], 0, 0, 0); __builtin_amdgcn_s_setprio(0); } while (0)
; #define PG8_WAIT_V(n) asm volatile("s_waitcnt vmcnt(" #n ")" ::: "memory")
; #define PG8_WAIT_L(n) asm volatile("s_waitcnt lgkmcnt(" #n ")" ::: "memory")
; #define PG8_BAR __builtin_amdgcn_s_barrier()
; #define PG8_SCHED __builtin_amdgcn_sched_barrier(0)
; template <class Epi, class Sched, bool ALIGN_EPI = false, bool SP2 = false>
; __device__ __forceinline__ void gemm_phase(PG8_LAS unsigned char* lds, const Gemm g, const Sched& S, const Epi& E, int wave_in) {
;     ...
;             PG8_WAIT_V(8); PG8_WAIT_L(0); PG8_BAR; PG8_MMA(1, 0, At, B0); PG8_MMA(1, 1, At, B1); PG8_BAR; PG8_SCHED;
;             PG8_LDB(B0, 1, 0); PG8_LDB(B1, 1, 1); PG8_SCHED; PG8_LDA(At, 1, 0); PG8_STAGE(PG8_SA(0, 1), a2 + hstep, voffA);
;             PG8_WAIT_V(8); PG8_WAIT_L(0); PG8_BAR; PG8_MMA(0, 0, At, B0); PG8_MMA(0, 1, At, B1); PG8_BAR; PG8_SCHED;
	s_setprio 1
	s_waitcnt lgkmcnt(0)
	v_mfma_f32_16x16x32_bf16 v[60:63], v[112:115], v[160:163], 0
	v_mfma_f32_16x16x32_bf16 v[56:59], v[124:127], v[160:163], 0
	v_mfma_f32_16x16x32_bf16 v[44:47], v[112:115], v[168:171], 0
	v_mfma_f32_16x16x32_bf16 v[40:43], v[124:127], v[168:171], 0
	v_mfma_f32_16x16x32_bf16 v[28:31], v[112:115], v[176:179], 0
	v_mfma_f32_16x16x32_bf16 v[24:27], v[124:127], v[176:179], 0
	v_mfma_f32_16x16x32_bf16 v[12:15], v[112:115], v[184:187], 0
	v_mfma_f32_16x16x32_bf16 v[8:11], v[124:127], v[184:187], 0
	v_mfma_f32_16x16x32_bf16 v[60:63], v[120:123], v[164:167], v[60:63]
	v_mfma_f32_16x16x32_bf16 v[56:59], v[128:131], v[164:167], v[56:59]
	v_mfma_f32_16x16x32_bf16 v[44:47], v[120:123], v[172:175], v[44:47]
	v_mfma_f32_16x16x32_bf16 v[40:43], v[128:131], v[172:175], v[40:43]
	v_mfma_f32_16x16x32_bf16 v[28:31], v[120:123], v[180:183], v[28:31]
	v_mfma_f32_16x16x32_bf16 v[24:27], v[128:131], v[180:183], v[24:27]
	v_mfma_f32_16x16x32_bf16 v[12:15], v[120:123], v[188:191], v[12:15]
	v_mfma_f32_16x16x32_bf16 v[8:11], v[128:131], v[188:191], v[8:11]
	s_setprio 0
	s_setprio 1
	v_mfma_f32_16x16x32_bf16 v[52:55], v[136:139], v[160:163], 0
	v_mfma_f32_16x16x32_bf16 v[48:51], v[144:147], v[160:163], 0
	v_mfma_f32_16x16x32_bf16 v[36:39], v[136:139], v[168:171], 0
	v_mfma_f32_16x16x32_bf16 v[32:35], v[144:147], v[168:171], 0
	v_mfma_f32_16x16x32_bf16 v[20:23], v[136:139], v[176:179], 0
	v_mfma_f32_16x16x32_bf16 v[16:19], v[144:147], v[176:179], 0
	v_mfma_f32_16x16x32_bf16 v[4:7], v[136:139], v[184:187], 0
	v_mfma_f32_16x16x32_bf16 v[0:3], v[144:147], v[184:187], 0
	v_mfma_f32_16x16x32_bf16 v[52:55], v[140:143], v[164:167], v[52:55]
	v_mfma_f32_16x16x32_bf16 v[48:51], v[156:159], v[164:167], v[48:51]
	v_mfma_f32_16x16x32_bf16 v[36:39], v[140:143], v[172:175], v[36:39]
	v_mfma_f32_16x16x32_bf16 v[32:35], v[156:159], v[172:175], v[32:35]
	v_mfma_f32_16x16x32_bf16 v[20:23], v[140:143], v[180:183], v[20:23]
	v_mfma_f32_16x16x32_bf16 v[16:19], v[156:159], v[180:183], v[16:19]
	v_mfma_f32_16x16x32_bf16 v[4:7], v[140:143], v[188:191], v[4:7]
	v_mfma_f32_16x16x32_bf16 v[0:3], v[156:159], v[188:191], v[0:3]
	s_setprio 0
	s_barrier
	s_add_i32 s53, s65, 0x100
	s_add_i32 s69, s52, 0x100
	v_add_u32_e32 v128, s53, v249
	v_add_u32_e32 v156, s69, v249
	ds_read_b128 v[112:115], v128
	ds_read_b128 v[120:123], v128 offset:1024
	ds_read_b128 v[124:127], v128 offset:2048
	ds_read_b128 v[128:131], v128 offset:3072
	ds_read_b128 v[136:139], v156
	ds_read_b128 v[140:143], v156 offset:1024
	ds_read_b128 v[144:147], v156 offset:2048
	ds_read_b128 v[156:159], v156 offset:3072
	s_add_u32 s26, s26, 0x40000
	s_addc_u32 s27, s27, 0
	s_mov_b32 m0, s47
	v_lshl_add_u64 v[216:217], s[26:27], 0, v[202:203]
	ds_read_b128 v[160:163], v251 offset:32768
	ds_read_b128 v[164:167], v251 offset:33792
	ds_read_b128 v[168:171], v251 offset:34816
	ds_read_b128 v[172:175], v251 offset:35840
	ds_read_b128 v[176:179], v251 offset:36864
	ds_read_b128 v[180:183], v251 offset:37888
	ds_read_b128 v[184:187], v251 offset:38912
	ds_read_b128 v[188:191], v251 offset:39936
	global_load_lds_dwordx4 v[216:217], off
	v_lshl_add_u64 v[216:217], s[26:27], 0, v[200:201]
	s_mov_b32 m0, s60
	s_nop 0
	global_load_lds_dwordx4 v[216:217], off
	s_waitcnt vmcnt(8)
	s_waitcnt lgkmcnt(0)
	s_barrier
	s_setprio 1
	s_waitcnt lgkmcnt(0)
	v_mfma_f32_16x16x32_bf16 v[152:155], v[112:115], v[160:163], v[152:155]
	v_mfma_f32_16x16x32_bf16 v[148:151], v[124:127], v[160:163], v[148:151]
	v_mfma_f32_16x16x32_bf16 v[108:111], v[112:115], v[168:171], v[108:111]
	v_mfma_f32_16x16x32_bf16 v[104:107], v[124:127], v[168:171], v[104:107]
	v_mfma_f32_16x16x32_bf16 v[92:95], v[112:115], v[176:179], v[92:95]
	v_mfma_f32_16x16x32_bf16 v[88:91], v[124:127], v[176:179], v[88:91]
	v_mfma_f32_16x16x32_bf16 v[76:79], v[112:115], v[184:187], v[76:79]
	v_mfma_f32_16x16x32_bf16 v[72:75], v[124:127], v[184:187], v[72:75]
	v_mfma_f32_16x16x32_bf16 v[152:155], v[120:123], v[164:167], v[152:155]
	v_mfma_f32_16x16x32_bf16 v[148:151], v[128:131], v[164:167], v[148:151]
	v_mfma_f32_16x16x32_bf16 v[108:111], v[120:123], v[172:175], v[108:111]
	v_mfma_f32_16x16x32_bf16 v[104:107], v[128:131], v[172:175], v[104:107]
	v_mfma_f32_16x16x32_bf16 v[92:95], v[120:123], v[180:183], v[92:95]
	v_mfma_f32_16x16x32_bf16 v[88:91], v[128:131], v[180:183], v[88:91]
	v_mfma_f32_16x16x32_bf16 v[76:79], v[120:123], v[188:191], v[76:79]
	v_mfma_f32_16x16x32_bf16 v[72:75], v[128:131], v[188:191], v[72:75]
	s_setprio 0
	s_setprio 1
	v_mfma_f32_16x16x32_bf16 v[132:135], v[136:139], v[160:163], v[132:135]
	v_mfma_f32_16x16x32_bf16 v[116:119], v[144:147], v[160:163], v[116:119]
	v_mfma_f32_16x16x32_bf16 v[100:103], v[136:139], v[168:171], v[100:103]
	v_mfma_f32_16x16x32_bf16 v[96:99], v[144:147], v[168:171], v[96:99]
	v_mfma_f32_16x16x32_bf16 v[84:87], v[136:139], v[176:179], v[84:87]
	v_mfma_f32_16x16x32_bf16 v[80:83], v[144:147], v[176:179], v[80:83]
	v_mfma_f32_16x16x32_bf16 v[68:71], v[136:139], v[184:187], v[68:71]
	v_mfma_f32_16x16x32_bf16 v[64:67], v[144:147], v[184:187], v[64:67]
	v_mfma_f32_16x16x32_bf16 v[132:135], v[140:143], v[164:167], v[132:135]
	v_mfma_f32_16x16x32_bf16 v[116:119], v[156:159], v[164:167], v[116:119]
	v_mfma_f32_16x16x32_bf16 v[100:103], v[140:143], v[172:175], v[100:103]
	v_mfma_f32_16x16x32_bf16 v[96:99], v[156:159], v[172:175], v[96:99]
	v_mfma_f32_16x16x32_bf16 v[84:87], v[140:143], v[180:183], v[84:87]
	v_mfma_f32_16x16x32_bf16 v[80:83], v[156:159], v[180:183], v[80:83]
	v_mfma_f32_16x16x32_bf16 v[68:71], v[140:143], v[188:191], v[68:71]
	v_mfma_f32_16x16x32_bf16 v[64:67], v[156:159], v[188:191], v[64:67]
	s_setprio 0
	s_barrier
; #define PG8_STAGE(bufoff, gbase, voff) do { _Pragma("unroll") for (int _i = 0; _i < 2; ++_i) \
;         __builtin_amdgcn_global_load_lds((const unsigned*)((const char*)(gbase) + (voff)[_i]), (PG8_LAS unsigned*)(lds + (bufoff) + ldsw + _i * 8192), 16, 0, 0); } while (0)
; #define PG8_LDA(dst, b, h) do { _Pragma("unroll") for (int m = 0; m < 4; ++m) _Pragma("unroll") for (int k = 0; k < 2; ++k) dst[m][k] = *(const PG8_LAS bf16x8*)(lds + PG8_SA(b, h) + aoff + m * 2048 + k * 1024); } while (0)
; #define PG8_WAIT_V(n) asm volatile("s_waitcnt vmcnt(" #n ")" ::: "memory")
; #define PG8_WAIT_L(n) asm volatile("s_waitcnt lgkmcnt(" #n ")" ::: "memory")
; #define PG8_BAR __builtin_amdgcn_s_barrier()
; template <class Epi, class Sched, bool ALIGN_EPI = false, bool SP2 = false>
; __device__ __forceinline__ void gemm_phase(PG8_LAS unsigned char* lds, const Gemm g, const Sched& S, const Epi& E, int wave_in) {
;     ...
;         for (int t = 0; t < nt; t += 2) {
;             const bool last = (t == nt - 2);
;             const char* a1 = cA + (size_t)(t + 1) * kstep;
;             const char* a2 = last ? nA : cA + (size_t)(t + 2) * kstep; const char* b2 = last ? nB : cB + (size_t)(t + 2) * kstep;
;             const char* a3 = a2 + kstep; const char* b3 = b2 + kstep;
;             if (last && has_next) S.a_ready(nxt);
;             if constexpr (SP2) {
;             PG8_LDB(B0, 0, 0); PG8_LDB(B1, 0, 1); PG8_SCHED; PG8_LDA(At, 0, 0); PG8_STAGE(PG8_SA(1, 1), a1 + hstep, voffA);
;             PG8_WAIT_V(8); PG8_WAIT_L(0); PG8_BAR; PG8_MMA(0, 0, At, B0); PG8_MMA(0, 1, At, B1); PG8_BAR; PG8_SCHED;
;             PG8_LDA(At, 0, 1); PG8_STAGE(PG8_SB(0, 0), b2, voffB); PG8_STAGE(PG8_SB(0, 1), b2 + hstep, voffB); PG8_STAGE(PG8_SA(0, 0), a2, voffA);
;             PG8_WAIT_V(8); PG8_WAIT_L(0); PG8_BAR; PG8_MMA(1, 0, At, B0); PG8_MMA(1, 1, At, B1); PG8_BAR; PG8_SCHED;
;             PG8_LDB(B0, 1, 0); PG8_LDB(B1, 1, 1); PG8_SCHED; PG8_LDA(At, 1, 0); PG8_STAGE(PG8_SA(0, 1), a2 + hstep, voffA);
;             PG8_WAIT_V(8); PG8_WAIT_L(0); PG8_BAR; PG8_MMA(0, 0, At, B0); PG8_MMA(0, 1, At, B1); PG8_BAR; PG8_SCHED;
;             PG8_LDA(At, 1, 1); PG8_STAGE(PG8_SB(1, 0), b3, voffB); PG8_STAGE(PG8_SB(1, 1), b3 + hstep, voffB); PG8_STAGE(PG8_SA(1, 0), a3, voffA);
;             PG8_WAIT_V(8); PG8_WAIT_L(0); PG8_BAR; PG8_MMA(1, 0, At, B0); PG8_MMA(1, 1, At, B1); PG8_BAR; PG8_SCHED;
	s_add_i32 s26, s53, s38
	v_lshl_add_u64 v[208:209], v[208:209], 0, s[88:89]
	s_mov_b32 m0, s26
	ds_read_b128 v[160:163], v251 offset:49152
	ds_read_b128 v[164:167], v251 offset:50176
	ds_read_b128 v[168:171], v251 offset:51200
	ds_read_b128 v[172:175], v251 offset:52224
	ds_read_b128 v[176:179], v251 offset:53248
	ds_read_b128 v[180:183], v251 offset:54272
	ds_read_b128 v[184:187], v251 offset:55296
	ds_read_b128 v[188:191], v251 offset:56320
	global_load_lds_dwordx4 v[208:209], off
	s_add_i32 m0, s26, 0x2000
	s_add_u32 s24, s24, 0x40080
	v_lshl_add_u64 v[208:209], v[210:211], 0, s[88:89]
	s_addc_u32 s25, s25, 0
	s_add_i32 s26, s69, s38
	global_load_lds_dwordx4 v[208:209], off
	v_lshl_add_u64 v[208:209], s[24:25], 0, v[192:193]
	s_mov_b32 m0, s26
	s_nop 0
	global_load_lds_dwordx4 v[208:209], off
	v_lshl_add_u64 v[208:209], s[24:25], 0, v[198:199]
	s_add_i32 m0, s26, 0x2000
	s_nop 0
	global_load_lds_dwordx4 v[208:209], off
	v_lshl_add_u64 v[208:209], v[212:213], 0, s[88:89]
	s_mov_b32 m0, s62
	s_nop 0
	global_load_lds_dwordx4 v[208:209], off
	v_lshl_add_u64 v[208:209], v[214:215], 0, s[88:89]
	s_mov_b32 m0, s63
	s_nop 0
	global_load_lds_dwordx4 v[208:209], off
	s_waitcnt vmcnt(8)
	s_waitcnt lgkmcnt(0)
	s_barrier
	s_setprio 1
	s_waitcnt lgkmcnt(0)
	v_mfma_f32_16x16x32_bf16 v[60:63], v[112:115], v[160:163], v[60:63]
	v_mfma_f32_16x16x32_bf16 v[56:59], v[124:127], v[160:163], v[56:59]
	v_mfma_f32_16x16x32_bf16 v[44:47], v[112:115], v[168:171], v[44:47]
	v_mfma_f32_16x16x32_bf16 v[40:43], v[124:127], v[168:171], v[40:43]
	v_mfma_f32_16x16x32_bf16 v[28:31], v[112:115], v[176:179], v[28:31]
	v_mfma_f32_16x16x32_bf16 v[24:27], v[124:127], v[176:179], v[24:27]
	v_mfma_f32_16x16x32_bf16 v[12:15], v[112:115], v[184:187], v[12:15]
	v_mfma_f32_16x16x32_bf16 v[8:11], v[124:127], v[184:187], v[8:11]
	v_mfma_f32_16x16x32_bf16 v[60:63], v[120:123], v[164:167], v[60:63]
	v_mfma_f32_16x16x32_bf16 v[56:59], v[128:131], v[164:167], v[56:59]
	v_mfma_f32_16x16x32_bf16 v[44:47], v[120:123], v[172:175], v[44:47]
	v_mfma_f32_16x16x32_bf16 v[40:43], v[128:131], v[172:175], v[40:43]
	v_mfma_f32_16x16x32_bf16 v[28:31], v[120:123], v[180:183], v[28:31]
	v_mfma_f32_16x16x32_bf16 v[24:27], v[128:131], v[180:183], v[24:27]
	v_mfma_f32_16x16x32_bf16 v[12:15], v[120:123], v[188:191], v[12:15]
	v_mfma_f32_16x16x32_bf16 v[8:11], v[128:131], v[188:191], v[8:11]
	s_setprio 0
	s_setprio 1
	v_mfma_f32_16x16x32_bf16 v[52:55], v[136:139], v[160:163], v[52:55]
	v_mfma_f32_16x16x32_bf16 v[48:51], v[144:147], v[160:163], v[48:51]
	v_mfma_f32_16x16x32_bf16 v[36:39], v[136:139], v[168:171], v[36:39]
	v_mfma_f32_16x16x32_bf16 v[32:35], v[144:147], v[168:171], v[32:35]
	v_mfma_f32_16x16x32_bf16 v[20:23], v[136:139], v[176:179], v[20:23]
	v_mfma_f32_16x16x32_bf16 v[16:19], v[144:147], v[176:179], v[16:19]
	v_mfma_f32_16x16x32_bf16 v[4:7], v[136:139], v[184:187], v[4:7]
	v_mfma_f32_16x16x32_bf16 v[0:3], v[144:147], v[184:187], v[0:3]
	v_mfma_f32_16x16x32_bf16 v[52:55], v[140:143], v[164:167], v[52:55]
	v_mfma_f32_16x16x32_bf16 v[48:51], v[156:159], v[164:167], v[48:51]
	v_mfma_f32_16x16x32_bf16 v[36:39], v[140:143], v[172:175], v[36:39]
	v_mfma_f32_16x16x32_bf16 v[32:35], v[156:159], v[172:175], v[32:35]
	v_mfma_f32_16x16x32_bf16 v[20:23], v[140:143], v[180:183], v[20:23]
	v_mfma_f32_16x16x32_bf16 v[16:19], v[156:159], v[180:183], v[16:19]
	v_mfma_f32_16x16x32_bf16 v[4:7], v[140:143], v[188:191], v[4:7]
	v_mfma_f32_16x16x32_bf16 v[0:3], v[156:159], v[188:191], v[0:3]
	s_setprio 0
	s_barrier
	s_add_i32 s45, s45, 2
	s_add_u32 s34, s34, 0x100
	s_addc_u32 s44, s44, 0
	s_add_u32 s22, s22, 0x100
	s_addc_u32 s23, s23, 0
	s_cmp_gt_u32 s45, 13
	s_cbranch_scc1 .Lkexit_3

; #define PG8_BAR __builtin_amdgcn_s_barrier()
; template <class Epi, class Sched, bool ALIGN_EPI = false, bool SP2 = false>
; __device__ __forceinline__ void gemm_phase(PG8_LAS unsigned char* lds, const Gemm g, const Sched& S, const Epi& E, int wave_in) {
;     ...
;         if constexpr (ALIGN_EPI) { if (wr == 0) PG8_BAR; }
.Lkexit_3:
	v_mov_b64_e32 v[246:247], 0x400
	s_and_b64 vcc, exec, s[12:13]
	s_cbranch_vccz .LBB0_593
	s_barrier

; #define PG8_STAGE(bufoff, gbase, voff) do { _Pragma("unroll") for (int _i = 0; _i < 2; ++_i) \
;         __builtin_amdgcn_global_load_lds((const unsigned*)((const char*)(gbase) + (voff)[_i]), (PG8_LAS unsigned*)(lds + (bufoff) + ldsw + _i * 8192), 16, 0, 0); } while (0)
; #define PG8_LDA(dst, b, h) do { _Pragma("unroll") for (int m = 0; m < 4; ++m) _Pragma("unroll") for (int k = 0; k < 2; ++k) dst[m][k] = *(const PG8_LAS bf16x8*)(lds + PG8_SA(b, h) + aoff + m * 2048 + k * 1024); } while (0)
; #define PG8_LDB(dst, b, h) do { _Pragma("unroll") for (int n = 0; n < 2; ++n) _Pragma("unroll") for (int k = 0; k < 2; ++k) dst[n][k] = *(const PG8_LAS bf16x8*)(lds + PG8_SB(b, h) + boff + n * 2048 + k * 1024); } while (0)
; #define PG8_WAIT_V(n) asm volatile("s_waitcnt vmcnt(" #n ")" ::: "memory")
; template <class Epi, class Sched, bool ALIGN_EPI = false, bool SP2 = false>
; __device__ __forceinline__ void gemm_phase(PG8_LAS unsigned char* lds, const Gemm g, const Sched& S, const Epi& E, int wave_in) {
;     ...
;         const char* nA = has_next ? (const char*)g.A + (size_t)(nxt.pm >> g.ash) * g.astride + (size_t)nxt.pm * tstep : cA; const char* nB = has_next ? (const char*)g.Bt + (size_t)(nxt.pm >> g.bsh) * g.bstride + (size_t)nxt.pn * tstep : cB;
;         for (int t = 0; t < nt; t += 2) {
;             const bool last = (t == nt - 2);
;             const char* a1 = cA + (size_t)(t + 1) * kstep;
;             const char* a2 = last ? nA : cA + (size_t)(t + 2) * kstep; const char* b2 = last ? nB : cB + (size_t)(t + 2) * kstep;
;             const char* a3 = a2 + kstep; const char* b3 = b2 + kstep;
;             if (last && has_next) S.a_ready(nxt);
;             if constexpr (SP2) {
;             PG8_LDB(B0, 0, 0); PG8_LDB(B1, 0, 1); PG8_SCHED; PG8_LDA(At, 0, 0); PG8_STAGE(PG8_SA(1, 1), a1 + hstep, voffA);
;             PG8_WAIT_V(8); PG8_WAIT_L(0); PG8_BAR; PG8_MMA(0, 0, At, B0); PG8_MMA(0, 1, At, B1); PG8_BAR; PG8_SCHED;
;             PG8_LDA(At, 0, 1); PG8_STAGE(PG8_SB(0, 0), b2, voffB); PG8_STAGE(PG8_SB(0, 1), b2 + hstep, voffB); PG8_STAGE(PG8_SA(0, 0), a2, voffA);
;     ...
; #pragma unroll
;         for (int a = 0; a < 2; ++a)
; #pragma unroll
;             for (int b = 0; b < 2; ++b)
; #pragma unroll
;                 for (int m = 0; m < 4; ++m)
; #pragma unroll
;                     for (int n = 0; n < 2; ++n) acc[a][b][m][n] = (f32x4){0.f, 0.f, 0.f, 0.f};
.LBB0_686:
	s_ashr_i32 s17, s16, 31
	s_lshl_b64 s[18:19], s[16:17], 19
	s_add_u32 s18, s8, s18
	s_addc_u32 s19, s9, s19
	s_and_b64 s[20:21], s[42:43], exec
	s_cselect_b32 s17, s19, s25
	s_cselect_b32 s69, s18, s24
	s_ashr_i32 s20, s16, 5
	s_ashr_i32 s21, s20, 31
	s_lshl_b64 s[20:21], s[20:21], 21
	s_add_u32 s26, s31, s20
	s_addc_u32 s27, s33, s21
	s_ashr_i32 s13, s12, 31
	s_lshl_b64 s[20:21], s[12:13], 19
	s_add_u32 s20, s26, s20
	s_addc_u32 s21, s27, s21
	s_and_b64 s[26:27], s[42:43], exec
	s_cselect_b32 s13, s21, s23
	s_cselect_b32 s34, s20, s22
	s_add_u32 s53, s22, 0x100
	s_addc_u32 s71, s23, 0
	s_add_u32 s22, s24, 0x40080
	s_addc_u32 s23, s25, 0
	s_mov_b32 s72, -2
	s_add_u32 s24, s22, 0xfffc0080
	s_addc_u32 s25, s23, -1
	s_add_i32 s73, s35, 0x100
	s_cmp_eq_u32 s72, 12
	s_cselect_b32 s27, s17, s25
	s_cselect_b32 s26, s69, s24
	s_cselect_b32 s25, s13, s71
	s_cselect_b32 s24, s34, s53
	s_add_i32 s76, s90, 0x100
	v_add_u32_e32 v140, s73, v212
	v_add_u32_e32 v168, s76, v212
	ds_read_b128 v[128:131], v140
	ds_read_b128 v[132:135], v140 offset:1024
	ds_read_b128 v[136:139], v140 offset:2048
	ds_read_b128 v[140:143], v140 offset:3072
	ds_read_b128 v[156:159], v168
	ds_read_b128 v[160:163], v168 offset:1024
	ds_read_b128 v[164:167], v168 offset:2048
	ds_read_b128 v[168:171], v168 offset:3072
	v_lshl_add_u64 v[194:195], s[22:23], 0, v[154:155]
	s_add_i32 m0, s39, 0xc000
	ds_read_b128 v[172:175], v227
	ds_read_b128 v[176:179], v227 offset:1024
	ds_read_b128 v[180:183], v227 offset:2048
	ds_read_b128 v[184:187], v227 offset:3072
	ds_read_b128 v[188:191], v227 offset:4096
	ds_read_b128 v[198:201], v227 offset:5120
	ds_read_b128 v[202:205], v227 offset:6144
	ds_read_b128 v[206:209], v227 offset:7168
	global_load_lds_dwordx4 v[194:195], off
	v_lshl_add_u64 v[194:195], s[22:23], 0, v[152:153]
	s_add_i32 m0, s39, 0xe000
	s_nop 0
	global_load_lds_dwordx4 v[194:195], off
	s_waitcnt vmcnt(8)
	s_waitcnt lgkmcnt(0)
	s_barrier
	s_setprio 1
	s_waitcnt lgkmcnt(0)
	v_mfma_f32_16x16x32_bf16 v[124:127], v[128:131], v[172:175], 0
	v_mfma_f32_16x16x32_bf16 v[120:123], v[136:139], v[172:175], 0
	v_mfma_f32_16x16x32_bf16 v[108:111], v[128:131], v[180:183], 0
	v_mfma_f32_16x16x32_bf16 v[104:107], v[136:139], v[180:183], 0
	v_mfma_f32_16x16x32_bf16 v[96:99], v[128:131], v[188:191], 0
	v_mfma_f32_16x16x32_bf16 v[88:91], v[136:139], v[188:191], 0
	v_mfma_f32_16x16x32_bf16 v[80:83], v[128:131], v[202:205], 0
	v_mfma_f32_16x16x32_bf16 v[72:75], v[136:139], v[202:205], 0
	v_mfma_f32_16x16x32_bf16 v[124:127], v[132:135], v[176:179], v[124:127]
	v_mfma_f32_16x16x32_bf16 v[120:123], v[140:143], v[176:179], v[120:123]
	v_mfma_f32_16x16x32_bf16 v[108:111], v[132:135], v[184:187], v[108:111]
	v_mfma_f32_16x16x32_bf16 v[104:107], v[140:143], v[184:187], v[104:107]
	v_mfma_f32_16x16x32_bf16 v[96:99], v[132:135], v[198:201], v[96:99]
	v_mfma_f32_16x16x32_bf16 v[88:91], v[140:143], v[198:201], v[88:91]
	v_mfma_f32_16x16x32_bf16 v[80:83], v[132:135], v[206:209], v[80:83]
	v_mfma_f32_16x16x32_bf16 v[72:75], v[140:143], v[206:209], v[72:75]
	s_setprio 0
	s_setprio 1
	v_mfma_f32_16x16x32_bf16 v[116:119], v[156:159], v[172:175], 0
	v_mfma_f32_16x16x32_bf16 v[112:115], v[164:167], v[172:175], 0
	v_mfma_f32_16x16x32_bf16 v[100:103], v[156:159], v[180:183], 0
	v_mfma_f32_16x16x32_bf16 v[92:95], v[164:167], v[180:183], 0
	v_mfma_f32_16x16x32_bf16 v[84:87], v[156:159], v[188:191], 0
	v_mfma_f32_16x16x32_bf16 v[76:79], v[164:167], v[188:191], 0
	v_mfma_f32_16x16x32_bf16 v[68:71], v[156:159], v[202:205], 0
	v_mfma_f32_16x16x32_bf16 v[64:67], v[164:167], v[202:205], 0
	v_mfma_f32_16x16x32_bf16 v[116:119], v[160:163], v[176:179], v[116:119]
	v_mfma_f32_16x16x32_bf16 v[112:115], v[168:171], v[176:179], v[112:115]
	v_mfma_f32_16x16x32_bf16 v[100:103], v[160:163], v[184:187], v[100:103]
	v_mfma_f32_16x16x32_bf16 v[92:95], v[168:171], v[184:187], v[92:95]
	v_mfma_f32_16x16x32_bf16 v[84:87], v[160:163], v[198:201], v[84:87]
	v_mfma_f32_16x16x32_bf16 v[76:79], v[168:171], v[198:201], v[76:79]
	v_mfma_f32_16x16x32_bf16 v[68:71], v[160:163], v[206:209], v[68:71]
	v_mfma_f32_16x16x32_bf16 v[64:67], v[168:171], v[206:209], v[64:67]
	s_setprio 0
	s_barrier
	s_add_i32 s73, s73, s38
	v_lshl_add_u64 v[194:195], s[24:25], 0, v[148:149]
	s_mov_b32 m0, s73
	ds_read_b128 v[172:175], v227 offset:16384
	ds_read_b128 v[176:179], v227 offset:17408
	ds_read_b128 v[180:183], v227 offset:18432
	ds_read_b128 v[184:187], v227 offset:19456
	ds_read_b128 v[188:191], v227 offset:20480
	ds_read_b128 v[198:201], v227 offset:21504
	ds_read_b128 v[202:205], v227 offset:22528
	ds_read_b128 v[206:209], v227 offset:23552
	global_load_lds_dwordx4 v[194:195], off
	s_add_i32 m0, s73, 0x2000
	s_add_u32 s74, s24, 0x40000
	v_lshl_add_u64 v[196:197], s[24:25], 0, v[144:145]
	s_addc_u32 s75, s25, 0
	s_add_i32 s73, s76, s38
	global_load_lds_dwordx4 v[196:197], off
	v_lshl_add_u64 v[234:235], s[74:75], 0, v[148:149]
	s_mov_b32 m0, s73
	v_lshl_add_u64 v[236:237], s[26:27], 0, v[146:147]
	global_load_lds_dwordx4 v[234:235], off
	v_lshl_add_u64 v[234:235], s[74:75], 0, v[144:145]
	s_add_i32 m0, s73, 0x2000
	s_nop 0
	global_load_lds_dwordx4 v[234:235], off
	v_lshl_add_u64 v[234:235], s[26:27], 0, v[150:151]
	s_mov_b32 m0, s39
	s_nop 0
	global_load_lds_dwordx4 v[234:235], off
	s_mov_b32 m0, s44
	s_nop 0
	global_load_lds_dwordx4 v[236:237], off
	s_waitcnt vmcnt(8)
	s_waitcnt lgkmcnt(0)
	s_barrier
; #define PG8_STAGE(bufoff, gbase, voff) do { _Pragma("unroll") for (int _i = 0; _i < 2; ++_i) \
;         __builtin_amdgcn_global_load_lds((const unsigned*)((const char*)(gbase) + (voff)[_i]), (PG8_LAS unsigned*)(lds + (bufoff) + ldsw + _i * 8192), 16, 0, 0); } while (0)
; #define PG8_LDA(dst, b, h) do { _Pragma("unroll") for (int m = 0; m < 4; ++m) _Pragma("unroll") for (int k = 0; k < 2; ++k) dst[m][k] = *(const PG8_LAS bf16x8*)(lds + PG8_SA(b, h) + aoff + m * 2048 + k * 1024); } while (0)
; #define PG8_LDB(dst, b, h) do { _Pragma("unroll") for (int n = 0; n < 2; ++n) _Pragma("unroll") for (int k = 0; k < 2; ++k) dst[n][k] = *(const PG8_LAS bf16x8*)(lds + PG8_SB(b, h) + boff + n * 2048 + k * 1024); } while (0)
; #define PG8_MMA(ai, bj, At, Bt) do { __builtin_amdgcn_s_setprio(1); _Pragma("unroll") for (int m = 0; m < 4; ++m) _Pragma("unroll") for (int n = 0; n < 2; ++n) _Pragma("unroll") for (int k = 0; k < 2; ++k) \
;         acc[ai][bj][m][n] = __builtin_amdgcn_mfma_f32_16x16x32_bf16(Bt[n][k], At[m][k], acc[ai][bj][m][n], 0, 0, 0); __builtin_amdgcn_s_setprio(0); } while (0)
; #define PG8_WAIT_V(n) asm volatile("s_waitcnt vmcnt(" #n ")" ::: "memory")
; #define PG8_WAIT_L(n) asm volatile("s_waitcnt lgkmcnt(" #n ")" ::: "memory")
; #define PG8_BAR __builtin_amdgcn_s_barrier()
; #define PG8_SCHED __builtin_amdgcn_sched_barrier(0)
; template <class Epi, class Sched, bool ALIGN_EPI = false, bool SP2 = false>
; __device__ __forceinline__ void gemm_phase(PG8_LAS unsigned char* lds, const Gemm g, const Sched& S, const Epi& E, int wave_in) {
;     ...
;             PG8_WAIT_V(8); PG8_WAIT_L(0); PG8_BAR; PG8_MMA(1, 0, At, B0); PG8_MMA(1, 1, At, B1); PG8_BAR; PG8_SCHED;
;             PG8_LDB(B0, 1, 0); PG8_LDB(B1, 1, 1); PG8_SCHED; PG8_LDA(At, 1, 0); PG8_STAGE(PG8_SA(0, 1), a2 + hstep, voffA);
;             PG8_WAIT_V(8); PG8_WAIT_L(0); PG8_BAR; PG8_MMA(0, 0, At, B0); PG8_MMA(0, 1, At, B1); PG8_BAR; PG8_SCHED;
	s_setprio 1
	s_waitcnt lgkmcnt(0)
	v_mfma_f32_16x16x32_bf16 v[60:63], v[128:131], v[172:175], 0
	v_mfma_f32_16x16x32_bf16 v[56:59], v[136:139], v[172:175], 0
	v_mfma_f32_16x16x32_bf16 v[48:51], v[128:131], v[180:183], 0
	v_mfma_f32_16x16x32_bf16 v[40:43], v[136:139], v[180:183], 0
	v_mfma_f32_16x16x32_bf16 v[32:35], v[128:131], v[188:191], 0
	v_mfma_f32_16x16x32_bf16 v[24:27], v[136:139], v[188:191], 0
	v_mfma_f32_16x16x32_bf16 v[16:19], v[128:131], v[202:205], 0
	v_mfma_f32_16x16x32_bf16 v[8:11], v[136:139], v[202:205], 0
	v_mfma_f32_16x16x32_bf16 v[60:63], v[132:135], v[176:179], v[60:63]
	v_mfma_f32_16x16x32_bf16 v[56:59], v[140:143], v[176:179], v[56:59]
	v_mfma_f32_16x16x32_bf16 v[48:51], v[132:135], v[184:187], v[48:51]
	v_mfma_f32_16x16x32_bf16 v[40:43], v[140:143], v[184:187], v[40:43]
	v_mfma_f32_16x16x32_bf16 v[32:35], v[132:135], v[198:201], v[32:35]
	v_mfma_f32_16x16x32_bf16 v[24:27], v[140:143], v[198:201], v[24:27]
	v_mfma_f32_16x16x32_bf16 v[16:19], v[132:135], v[206:209], v[16:19]
	v_mfma_f32_16x16x32_bf16 v[8:11], v[140:143], v[206:209], v[8:11]
	s_setprio 0
	s_setprio 1
	v_mfma_f32_16x16x32_bf16 v[52:55], v[156:159], v[172:175], 0
	v_mfma_f32_16x16x32_bf16 v[44:47], v[164:167], v[172:175], 0
	v_mfma_f32_16x16x32_bf16 v[36:39], v[156:159], v[180:183], 0
	v_mfma_f32_16x16x32_bf16 v[28:31], v[164:167], v[180:183], 0
	v_mfma_f32_16x16x32_bf16 v[20:23], v[156:159], v[188:191], 0
	v_mfma_f32_16x16x32_bf16 v[12:15], v[164:167], v[188:191], 0
	v_mfma_f32_16x16x32_bf16 v[4:7], v[156:159], v[202:205], 0
	v_mfma_f32_16x16x32_bf16 v[0:3], v[164:167], v[202:205], 0
	v_mfma_f32_16x16x32_bf16 v[52:55], v[160:163], v[176:179], v[52:55]
	v_mfma_f32_16x16x32_bf16 v[44:47], v[168:171], v[176:179], v[44:47]
	v_mfma_f32_16x16x32_bf16 v[36:39], v[160:163], v[184:187], v[36:39]
	v_mfma_f32_16x16x32_bf16 v[28:31], v[168:171], v[184:187], v[28:31]
	v_mfma_f32_16x16x32_bf16 v[20:23], v[160:163], v[198:201], v[20:23]
	v_mfma_f32_16x16x32_bf16 v[12:15], v[168:171], v[198:201], v[12:15]
	v_mfma_f32_16x16x32_bf16 v[4:7], v[160:163], v[206:209], v[4:7]
	v_mfma_f32_16x16x32_bf16 v[0:3], v[168:171], v[206:209], v[0:3]
	s_setprio 0
	s_barrier
	s_add_i32 s73, s65, 0x100
	s_add_i32 s74, s52, 0x100
	v_add_u32_e32 v140, s73, v212
	v_add_u32_e32 v168, s74, v212
	ds_read_b128 v[128:131], v140
	ds_read_b128 v[132:135], v140 offset:1024
	ds_read_b128 v[136:139], v140 offset:2048
	ds_read_b128 v[140:143], v140 offset:3072
	ds_read_b128 v[156:159], v168
	ds_read_b128 v[160:163], v168 offset:1024
	ds_read_b128 v[164:167], v168 offset:2048
	ds_read_b128 v[168:171], v168 offset:3072
	s_add_u32 s26, s26, 0x40000
	s_addc_u32 s27, s27, 0
	s_mov_b32 m0, s45
	v_lshl_add_u64 v[238:239], s[26:27], 0, v[150:151]
	ds_read_b128 v[172:175], v227 offset:32768
	ds_read_b128 v[176:179], v227 offset:33792
	ds_read_b128 v[180:183], v227 offset:34816
	ds_read_b128 v[184:187], v227 offset:35840
	ds_read_b128 v[188:191], v227 offset:36864
	ds_read_b128 v[198:201], v227 offset:37888
	ds_read_b128 v[202:205], v227 offset:38912
	ds_read_b128 v[206:209], v227 offset:39936
	global_load_lds_dwordx4 v[238:239], off
	v_lshl_add_u64 v[238:239], s[26:27], 0, v[146:147]
	s_mov_b32 m0, s46
	s_nop 0
	global_load_lds_dwordx4 v[238:239], off
	s_waitcnt vmcnt(8)
	s_waitcnt lgkmcnt(0)
	s_barrier
	s_setprio 1
	s_waitcnt lgkmcnt(0)
	v_mfma_f32_16x16x32_bf16 v[124:127], v[128:131], v[172:175], v[124:127]
	v_mfma_f32_16x16x32_bf16 v[120:123], v[136:139], v[172:175], v[120:123]
	v_mfma_f32_16x16x32_bf16 v[108:111], v[128:131], v[180:183], v[108:111]
	v_mfma_f32_16x16x32_bf16 v[104:107], v[136:139], v[180:183], v[104:107]
	v_mfma_f32_16x16x32_bf16 v[96:99], v[128:131], v[188:191], v[96:99]
	v_mfma_f32_16x16x32_bf16 v[88:91], v[136:139], v[188:191], v[88:91]
	v_mfma_f32_16x16x32_bf16 v[80:83], v[128:131], v[202:205], v[80:83]
	v_mfma_f32_16x16x32_bf16 v[72:75], v[136:139], v[202:205], v[72:75]
	v_mfma_f32_16x16x32_bf16 v[124:127], v[132:135], v[176:179], v[124:127]
	v_mfma_f32_16x16x32_bf16 v[120:123], v[140:143], v[176:179], v[120:123]
	v_mfma_f32_16x16x32_bf16 v[108:111], v[132:135], v[184:187], v[108:111]
	v_mfma_f32_16x16x32_bf16 v[104:107], v[140:143], v[184:187], v[104:107]
	v_mfma_f32_16x16x32_bf16 v[96:99], v[132:135], v[198:201], v[96:99]
	v_mfma_f32_16x16x32_bf16 v[88:91], v[140:143], v[198:201], v[88:91]
	v_mfma_f32_16x16x32_bf16 v[80:83], v[132:135], v[206:209], v[80:83]
	v_mfma_f32_16x16x32_bf16 v[72:75], v[140:143], v[206:209], v[72:75]
	s_setprio 0
	s_setprio 1
	v_mfma_f32_16x16x32_bf16 v[116:119], v[156:159], v[172:175], v[116:119]
	v_mfma_f32_16x16x32_bf16 v[112:115], v[164:167], v[172:175], v[112:115]
	v_mfma_f32_16x16x32_bf16 v[100:103], v[156:159], v[180:183], v[100:103]
	v_mfma_f32_16x16x32_bf16 v[92:95], v[164:167], v[180:183], v[92:95]
	v_mfma_f32_16x16x32_bf16 v[84:87], v[156:159], v[188:191], v[84:87]
	v_mfma_f32_16x16x32_bf16 v[76:79], v[164:167], v[188:191], v[76:79]
	v_mfma_f32_16x16x32_bf16 v[68:71], v[156:159], v[202:205], v[68:71]
	v_mfma_f32_16x16x32_bf16 v[64:67], v[164:167], v[202:205], v[64:67]
	v_mfma_f32_16x16x32_bf16 v[116:119], v[160:163], v[176:179], v[116:119]
	v_mfma_f32_16x16x32_bf16 v[112:115], v[168:171], v[176:179], v[112:115]
	v_mfma_f32_16x16x32_bf16 v[100:103], v[160:163], v[184:187], v[100:103]
	v_mfma_f32_16x16x32_bf16 v[92:95], v[168:171], v[184:187], v[92:95]
	v_mfma_f32_16x16x32_bf16 v[84:87], v[160:163], v[198:201], v[84:87]
	v_mfma_f32_16x16x32_bf16 v[76:79], v[168:171], v[198:201], v[76:79]
	v_mfma_f32_16x16x32_bf16 v[68:71], v[160:163], v[206:209], v[68:71]
	v_mfma_f32_16x16x32_bf16 v[64:67], v[168:171], v[206:209], v[64:67]
	s_setprio 0
	s_barrier
; #define PG8_STAGE(bufoff, gbase, voff) do { _Pragma("unroll") for (int _i = 0; _i < 2; ++_i) \
;         __builtin_amdgcn_global_load_lds((const unsigned*)((const char*)(gbase) + (voff)[_i]), (PG8_LAS unsigned*)(lds + (bufoff) + ldsw + _i * 8192), 16, 0, 0); } while (0)
; #define PG8_LDA(dst, b, h) do { _Pragma("unroll") for (int m = 0; m < 4; ++m) _Pragma("unroll") for (int k = 0; k < 2; ++k) dst[m][k] = *(const PG8_LAS bf16x8*)(lds + PG8_SA(b, h) + aoff + m * 2048 + k * 1024); } while (0)
; #define PG8_WAIT_V(n) asm volatile("s_waitcnt vmcnt(" #n ")" ::: "memory")
; #define PG8_WAIT_L(n) asm volatile("s_waitcnt lgkmcnt(" #n ")" ::: "memory")
; #define PG8_BAR __builtin_amdgcn_s_barrier()
; template <class Epi, class Sched, bool ALIGN_EPI = false, bool SP2 = false>
; __device__ __forceinline__ void gemm_phase(PG8_LAS unsigned char* lds, const Gemm g, const Sched& S, const Epi& E, int wave_in) {
;     ...
;         for (int t = 0; t < nt; t += 2) {
;             const bool last = (t == nt - 2);
;             const char* a1 = cA + (size_t)(t + 1) * kstep;
;             const char* a2 = last ? nA : cA + (size_t)(t + 2) * kstep; const char* b2 = last ? nB : cB + (size_t)(t + 2) * kstep;
;             const char* a3 = a2 + kstep; const char* b3 = b2 + kstep;
;             if (last && has_next) S.a_ready(nxt);
;             if constexpr (SP2) {
;             PG8_LDB(B0, 0, 0); PG8_LDB(B1, 0, 1); PG8_SCHED; PG8_LDA(At, 0, 0); PG8_STAGE(PG8_SA(1, 1), a1 + hstep, voffA);
;             PG8_WAIT_V(8); PG8_WAIT_L(0); PG8_BAR; PG8_MMA(0, 0, At, B0); PG8_MMA(0, 1, At, B1); PG8_BAR; PG8_SCHED;
;             PG8_LDA(At, 0, 1); PG8_STAGE(PG8_SB(0, 0), b2, voffB); PG8_STAGE(PG8_SB(0, 1), b2 + hstep, voffB); PG8_STAGE(PG8_SA(0, 0), a2, voffA);
;             PG8_WAIT_V(8); PG8_WAIT_L(0); PG8_BAR; PG8_MMA(1, 0, At, B0); PG8_MMA(1, 1, At, B1); PG8_BAR; PG8_SCHED;
;             PG8_LDB(B0, 1, 0); PG8_LDB(B1, 1, 1); PG8_SCHED; PG8_LDA(At, 1, 0); PG8_STAGE(PG8_SA(0, 1), a2 + hstep, voffA);
;             PG8_WAIT_V(8); PG8_WAIT_L(0); PG8_BAR; PG8_MMA(0, 0, At, B0); PG8_MMA(0, 1, At, B1); PG8_BAR; PG8_SCHED;
;             PG8_LDA(At, 1, 1); PG8_STAGE(PG8_SB(1, 0), b3, voffB); PG8_STAGE(PG8_SB(1, 1), b3 + hstep, voffB); PG8_STAGE(PG8_SA(1, 0), a3, voffA);
;             PG8_WAIT_V(8); PG8_WAIT_L(0); PG8_BAR; PG8_MMA(1, 0, At, B0); PG8_MMA(1, 1, At, B1); PG8_BAR; PG8_SCHED;
	s_add_i32 s26, s73, s38
	v_lshl_add_u64 v[194:195], v[194:195], 0, s[88:89]
	s_mov_b32 m0, s26
	ds_read_b128 v[172:175], v227 offset:49152
	ds_read_b128 v[176:179], v227 offset:50176
	ds_read_b128 v[180:183], v227 offset:51200
	ds_read_b128 v[184:187], v227 offset:52224
	ds_read_b128 v[188:191], v227 offset:53248
	ds_read_b128 v[198:201], v227 offset:54272
	ds_read_b128 v[202:205], v227 offset:55296
	ds_read_b128 v[206:209], v227 offset:56320
	global_load_lds_dwordx4 v[194:195], off
	s_add_i32 m0, s26, 0x2000
	s_add_u32 s24, s24, 0x40080
	v_lshl_add_u64 v[194:195], v[196:197], 0, s[88:89]
	s_addc_u32 s25, s25, 0
	s_add_i32 s26, s74, s38
	global_load_lds_dwordx4 v[194:195], off
	v_lshl_add_u64 v[194:195], s[24:25], 0, v[148:149]
	s_mov_b32 m0, s26
	s_nop 0
	global_load_lds_dwordx4 v[194:195], off
	v_lshl_add_u64 v[194:195], s[24:25], 0, v[144:145]
	s_add_i32 m0, s26, 0x2000
	s_nop 0
	global_load_lds_dwordx4 v[194:195], off
	v_lshl_add_u64 v[194:195], v[234:235], 0, s[88:89]
	s_mov_b32 m0, s61
	s_nop 0
	global_load_lds_dwordx4 v[194:195], off
	v_lshl_add_u64 v[194:195], v[236:237], 0, s[88:89]
	s_mov_b32 m0, s62
	s_nop 0
	global_load_lds_dwordx4 v[194:195], off
	s_waitcnt vmcnt(8)
	s_waitcnt lgkmcnt(0)
	s_barrier
	s_setprio 1
	s_waitcnt lgkmcnt(0)
	v_mfma_f32_16x16x32_bf16 v[60:63], v[128:131], v[172:175], v[60:63]
	v_mfma_f32_16x16x32_bf16 v[56:59], v[136:139], v[172:175], v[56:59]
	v_mfma_f32_16x16x32_bf16 v[48:51], v[128:131], v[180:183], v[48:51]
	v_mfma_f32_16x16x32_bf16 v[40:43], v[136:139], v[180:183], v[40:43]
	v_mfma_f32_16x16x32_bf16 v[32:35], v[128:131], v[188:191], v[32:35]
	v_mfma_f32_16x16x32_bf16 v[24:27], v[136:139], v[188:191], v[24:27]
	v_mfma_f32_16x16x32_bf16 v[16:19], v[128:131], v[202:205], v[16:19]
	v_mfma_f32_16x16x32_bf16 v[8:11], v[136:139], v[202:205], v[8:11]
	v_mfma_f32_16x16x32_bf16 v[60:63], v[132:135], v[176:179], v[60:63]
	v_mfma_f32_16x16x32_bf16 v[56:59], v[140:143], v[176:179], v[56:59]
	v_mfma_f32_16x16x32_bf16 v[48:51], v[132:135], v[184:187], v[48:51]
	v_mfma_f32_16x16x32_bf16 v[40:43], v[140:143], v[184:187], v[40:43]
	v_mfma_f32_16x16x32_bf16 v[32:35], v[132:135], v[198:201], v[32:35]
	v_mfma_f32_16x16x32_bf16 v[24:27], v[140:143], v[198:201], v[24:27]
	v_mfma_f32_16x16x32_bf16 v[16:19], v[132:135], v[206:209], v[16:19]
	v_mfma_f32_16x16x32_bf16 v[8:11], v[140:143], v[206:209], v[8:11]
	s_setprio 0
	s_setprio 1
	v_mfma_f32_16x16x32_bf16 v[52:55], v[156:159], v[172:175], v[52:55]
	v_mfma_f32_16x16x32_bf16 v[44:47], v[164:167], v[172:175], v[44:47]
	v_mfma_f32_16x16x32_bf16 v[36:39], v[156:159], v[180:183], v[36:39]
	v_mfma_f32_16x16x32_bf16 v[28:31], v[164:167], v[180:183], v[28:31]
	v_mfma_f32_16x16x32_bf16 v[20:23], v[156:159], v[188:191], v[20:23]
	v_mfma_f32_16x16x32_bf16 v[12:15], v[164:167], v[188:191], v[12:15]
	v_mfma_f32_16x16x32_bf16 v[4:7], v[156:159], v[202:205], v[4:7]
	v_mfma_f32_16x16x32_bf16 v[0:3], v[164:167], v[202:205], v[0:3]
	v_mfma_f32_16x16x32_bf16 v[52:55], v[160:163], v[176:179], v[52:55]
	v_mfma_f32_16x16x32_bf16 v[44:47], v[168:171], v[176:179], v[44:47]
	v_mfma_f32_16x16x32_bf16 v[36:39], v[160:163], v[184:187], v[36:39]
	v_mfma_f32_16x16x32_bf16 v[28:31], v[168:171], v[184:187], v[28:31]
	v_mfma_f32_16x16x32_bf16 v[20:23], v[160:163], v[198:201], v[20:23]
	v_mfma_f32_16x16x32_bf16 v[12:15], v[168:171], v[198:201], v[12:15]
	v_mfma_f32_16x16x32_bf16 v[4:7], v[160:163], v[206:209], v[4:7]
	v_mfma_f32_16x16x32_bf16 v[0:3], v[168:171], v[206:209], v[0:3]
	s_setprio 0
	s_barrier
	s_add_i32 s72, s72, 2
	s_add_u32 s53, s53, 0x100
	s_addc_u32 s71, s71, 0
	s_add_u32 s22, s22, 0x100
	s_addc_u32 s23, s23, 0
	s_cmp_gt_u32 s72, 13
	s_cbranch_scc1 .Lkexit_4

; #define PG8_BAR __builtin_amdgcn_s_barrier()
; template <class Epi, class Sched, bool ALIGN_EPI = false, bool SP2 = false>
; __device__ __forceinline__ void gemm_phase(PG8_LAS unsigned char* lds, const Gemm g, const Sched& S, const Epi& E, int wave_in) {
;     ...
;         if constexpr (ALIGN_EPI) { if (wr == 0) PG8_BAR; }
.Lkexit_4:
	s_and_b64 vcc, exec, s[10:11]
	s_cbranch_vccz .LBB0_690
	s_barrier

; #define PG8_STAGE(bufoff, gbase, voff) do { _Pragma("unroll") for (int _i = 0; _i < 2; ++_i) \
;         __builtin_amdgcn_global_load_lds((const unsigned*)((const char*)(gbase) + (voff)[_i]), (PG8_LAS unsigned*)(lds + (bufoff) + ldsw + _i * 8192), 16, 0, 0); } while (0)
; #define PG8_LDA(dst, b, h) do { _Pragma("unroll") for (int m = 0; m < 4; ++m) _Pragma("unroll") for (int k = 0; k < 2; ++k) dst[m][k] = *(const PG8_LAS bf16x8*)(lds + PG8_SA(b, h) + aoff + m * 2048 + k * 1024); } while (0)
; #define PG8_LDB(dst, b, h) do { _Pragma("unroll") for (int n = 0; n < 2; ++n) _Pragma("unroll") for (int k = 0; k < 2; ++k) dst[n][k] = *(const PG8_LAS bf16x8*)(lds + PG8_SB(b, h) + boff + n * 2048 + k * 1024); } while (0)
; #define PG8_WAIT_V(n) asm volatile("s_waitcnt vmcnt(" #n ")" ::: "memory")
; template <class Epi, class Sched, bool ALIGN_EPI = false, bool SP2 = false>
; __device__ __forceinline__ void gemm_phase(PG8_LAS unsigned char* lds, const Gemm g, const Sched& S, const Epi& E, int wave_in) {
;     ...
;         const char* nA = has_next ? (const char*)g.A + (size_t)(nxt.pm >> g.ash) * g.astride + (size_t)nxt.pm * tstep : cA; const char* nB = has_next ? (const char*)g.Bt + (size_t)(nxt.pm >> g.bsh) * g.bstride + (size_t)nxt.pn * tstep : cB;
;         for (int t = 0; t < nt; t += 2) {
;             const bool last = (t == nt - 2);
;             const char* a1 = cA + (size_t)(t + 1) * kstep;
;             const char* a2 = last ? nA : cA + (size_t)(t + 2) * kstep; const char* b2 = last ? nB : cB + (size_t)(t + 2) * kstep;
;             const char* a3 = a2 + kstep; const char* b3 = b2 + kstep;
;             if (last && has_next) S.a_ready(nxt);
;             if constexpr (SP2) {
;             PG8_LDB(B0, 0, 0); PG8_LDB(B1, 0, 1); PG8_SCHED; PG8_LDA(At, 0, 0); PG8_STAGE(PG8_SA(1, 1), a1 + hstep, voffA);
;             PG8_WAIT_V(8); PG8_WAIT_L(0); PG8_BAR; PG8_MMA(0, 0, At, B0); PG8_MMA(0, 1, At, B1); PG8_BAR; PG8_SCHED;
;             PG8_LDA(At, 0, 1); PG8_STAGE(PG8_SB(0, 0), b2, voffB); PG8_STAGE(PG8_SB(0, 1), b2 + hstep, voffB); PG8_STAGE(PG8_SA(0, 0), a2, voffA);
;     ...
; #pragma unroll
;         for (int a = 0; a < 2; ++a)
; #pragma unroll
;             for (int b = 0; b < 2; ++b)
; #pragma unroll
;                 for (int m = 0; m < 4; ++m)
; #pragma unroll
;                     for (int n = 0; n < 2; ++n) acc[a][b][m][n] = (f32x4){0.f, 0.f, 0.f, 0.f};
.LBB0_803:
	s_add_u32 s15, s22, 0x100
	s_addc_u32 s17, s23, 0
	s_add_u32 s22, s24, 0x40080
	s_addc_u32 s23, s25, 0
	s_mov_b32 s34, -2
	s_add_u32 s24, s22, 0xfffc0080
	s_addc_u32 s25, s23, -1
	s_add_i32 s44, s35, 0x100
	s_cmp_eq_u32 s34, 12
	s_cselect_b32 s27, s19, s25
	s_cselect_b32 s26, s18, s24
	s_cselect_b32 s25, s21, s17
	s_cselect_b32 s24, s20, s15
	s_add_i32 s53, s90, 0x100
	v_add_u32_e32 v128, s44, v249
	v_add_u32_e32 v156, s53, v249
	ds_read_b128 v[112:115], v128
	ds_read_b128 v[120:123], v128 offset:1024
	ds_read_b128 v[124:127], v128 offset:2048
	ds_read_b128 v[128:131], v128 offset:3072
	ds_read_b128 v[136:139], v156
	ds_read_b128 v[140:143], v156 offset:1024
	ds_read_b128 v[144:147], v156 offset:2048
	ds_read_b128 v[156:159], v156 offset:3072
	v_lshl_add_u64 v[194:195], s[22:23], 0, v[206:207]
	s_add_i32 m0, s39, 0xc000
	ds_read_b128 v[160:163], v251
	ds_read_b128 v[164:167], v251 offset:1024
	ds_read_b128 v[168:171], v251 offset:2048
	ds_read_b128 v[172:175], v251 offset:3072
	ds_read_b128 v[176:179], v251 offset:4096
	ds_read_b128 v[180:183], v251 offset:5120
	ds_read_b128 v[184:187], v251 offset:6144
	ds_read_b128 v[188:191], v251 offset:7168
	global_load_lds_dwordx4 v[194:195], off
	v_lshl_add_u64 v[194:195], s[22:23], 0, v[204:205]
	s_add_i32 m0, s39, 0xe000
	s_nop 0
	global_load_lds_dwordx4 v[194:195], off
	s_waitcnt vmcnt(8)
	s_waitcnt lgkmcnt(0)
	s_barrier
	s_setprio 1
	s_waitcnt lgkmcnt(0)
	v_mfma_f32_16x16x32_bf16 v[152:155], v[112:115], v[160:163], 0
	v_mfma_f32_16x16x32_bf16 v[148:151], v[124:127], v[160:163], 0
	v_mfma_f32_16x16x32_bf16 v[108:111], v[112:115], v[168:171], 0
	v_mfma_f32_16x16x32_bf16 v[104:107], v[124:127], v[168:171], 0
	v_mfma_f32_16x16x32_bf16 v[92:95], v[112:115], v[176:179], 0
	v_mfma_f32_16x16x32_bf16 v[88:91], v[124:127], v[176:179], 0
	v_mfma_f32_16x16x32_bf16 v[76:79], v[112:115], v[184:187], 0
	v_mfma_f32_16x16x32_bf16 v[72:75], v[124:127], v[184:187], 0
	v_mfma_f32_16x16x32_bf16 v[152:155], v[120:123], v[164:167], v[152:155]
	v_mfma_f32_16x16x32_bf16 v[148:151], v[128:131], v[164:167], v[148:151]
	v_mfma_f32_16x16x32_bf16 v[108:111], v[120:123], v[172:175], v[108:111]
	v_mfma_f32_16x16x32_bf16 v[104:107], v[128:131], v[172:175], v[104:107]
	v_mfma_f32_16x16x32_bf16 v[92:95], v[120:123], v[180:183], v[92:95]
	v_mfma_f32_16x16x32_bf16 v[88:91], v[128:131], v[180:183], v[88:91]
	v_mfma_f32_16x16x32_bf16 v[76:79], v[120:123], v[188:191], v[76:79]
	v_mfma_f32_16x16x32_bf16 v[72:75], v[128:131], v[188:191], v[72:75]
	s_setprio 0
	s_setprio 1
	v_mfma_f32_16x16x32_bf16 v[132:135], v[136:139], v[160:163], 0
	v_mfma_f32_16x16x32_bf16 v[116:119], v[144:147], v[160:163], 0
	v_mfma_f32_16x16x32_bf16 v[100:103], v[136:139], v[168:171], 0
	v_mfma_f32_16x16x32_bf16 v[96:99], v[144:147], v[168:171], 0
	v_mfma_f32_16x16x32_bf16 v[84:87], v[136:139], v[176:179], 0
	v_mfma_f32_16x16x32_bf16 v[80:83], v[144:147], v[176:179], 0
	v_mfma_f32_16x16x32_bf16 v[68:71], v[136:139], v[184:187], 0
	v_mfma_f32_16x16x32_bf16 v[64:67], v[144:147], v[184:187], 0
	v_mfma_f32_16x16x32_bf16 v[132:135], v[140:143], v[164:167], v[132:135]
	v_mfma_f32_16x16x32_bf16 v[116:119], v[156:159], v[164:167], v[116:119]
	v_mfma_f32_16x16x32_bf16 v[100:103], v[140:143], v[172:175], v[100:103]
	v_mfma_f32_16x16x32_bf16 v[96:99], v[156:159], v[172:175], v[96:99]
	v_mfma_f32_16x16x32_bf16 v[84:87], v[140:143], v[180:183], v[84:87]
	v_mfma_f32_16x16x32_bf16 v[80:83], v[156:159], v[180:183], v[80:83]
	v_mfma_f32_16x16x32_bf16 v[68:71], v[140:143], v[188:191], v[68:71]
	v_mfma_f32_16x16x32_bf16 v[64:67], v[156:159], v[188:191], v[64:67]
	s_setprio 0
	s_barrier
	s_add_i32 s44, s44, s38
	v_lshl_add_u64 v[194:195], s[24:25], 0, v[192:193]
	s_mov_b32 m0, s44
	ds_read_b128 v[160:163], v251 offset:16384
	ds_read_b128 v[164:167], v251 offset:17408
	ds_read_b128 v[168:171], v251 offset:18432
	ds_read_b128 v[172:175], v251 offset:19456
	ds_read_b128 v[176:179], v251 offset:20480
	ds_read_b128 v[180:183], v251 offset:21504
	ds_read_b128 v[184:187], v251 offset:22528
	ds_read_b128 v[188:191], v251 offset:23552
	global_load_lds_dwordx4 v[194:195], off
	s_add_i32 m0, s44, 0x2000
	s_add_u32 s44, s24, 0x40000
	v_lshl_add_u64 v[196:197], s[24:25], 0, v[198:199]
	s_addc_u32 s45, s25, 0
	s_add_i32 s53, s53, s38
	global_load_lds_dwordx4 v[196:197], off
	v_lshl_add_u64 v[208:209], s[44:45], 0, v[192:193]
	s_mov_b32 m0, s53
	v_lshl_add_u64 v[210:211], s[26:27], 0, v[200:201]
	global_load_lds_dwordx4 v[208:209], off
	v_lshl_add_u64 v[208:209], s[44:45], 0, v[198:199]
	s_add_i32 m0, s53, 0x2000
	s_nop 0
	global_load_lds_dwordx4 v[208:209], off
	v_lshl_add_u64 v[208:209], s[26:27], 0, v[202:203]
	s_mov_b32 m0, s39
	s_nop 0
	global_load_lds_dwordx4 v[208:209], off
	s_mov_b32 m0, s46
	s_nop 0
	global_load_lds_dwordx4 v[210:211], off
	s_waitcnt vmcnt(8)
	s_waitcnt lgkmcnt(0)
	s_barrier
; #define PG8_STAGE(bufoff, gbase, voff) do { _Pragma("unroll") for (int _i = 0; _i < 2; ++_i) \
;         __builtin_amdgcn_global_load_lds((const unsigned*)((const char*)(gbase) + (voff)[_i]), (PG8_LAS unsigned*)(lds + (bufoff) + ldsw + _i * 8192), 16, 0, 0); } while (0)
; #define PG8_LDA(dst, b, h) do { _Pragma("unroll") for (int m = 0; m < 4; ++m) _Pragma("unroll") for (int k = 0; k < 2; ++k) dst[m][k] = *(const PG8_LAS bf16x8*)(lds + PG8_SA(b, h) + aoff + m * 2048 + k * 1024); } while (0)
; #define PG8_LDB(dst, b, h) do { _Pragma("unroll") for (int n = 0; n < 2; ++n) _Pragma("unroll") for (int k = 0; k < 2; ++k) dst[n][k] = *(const PG8_LAS bf16x8*)(lds + PG8_SB(b, h) + boff + n * 2048 + k * 1024); } while (0)
; #define PG8_MMA(ai, bj, At, Bt) do { __builtin_amdgcn_s_setprio(1); _Pragma("unroll") for (int m = 0; m < 4; ++m) _Pragma("unroll") for (int n = 0; n < 2; ++n) _Pragma("unroll") for (int k = 0; k < 2; ++k) \
;         acc[ai][bj][m][n] = __builtin_amdgcn_mfma_f32_16x16x32_bf16(Bt[n][k], At[m][k], acc[ai][bj][m][n], 0, 0, 0); __builtin_amdgcn_s_setprio(0); } while (0)
; #define PG8_WAIT_V(n) asm volatile("s_waitcnt vmcnt(" #n ")" ::: "memory")
; #define PG8_WAIT_L(n) asm volatile("s_waitcnt lgkmcnt(" #n ")" ::: "memory")
; #define PG8_BAR __builtin_amdgcn_s_barrier()
; #define PG8_SCHED __builtin_amdgcn_sched_barrier(0)
; template <class Epi, class Sched, bool ALIGN_EPI = false, bool SP2 = false>
; __device__ __forceinline__ void gemm_phase(PG8_LAS unsigned char* lds, const Gemm g, const Sched& S, const Epi& E, int wave_in) {
;     ...
;             PG8_WAIT_V(8); PG8_WAIT_L(0); PG8_BAR; PG8_MMA(1, 0, At, B0); PG8_MMA(1, 1, At, B1); PG8_BAR; PG8_SCHED;
;             PG8_LDB(B0, 1, 0); PG8_LDB(B1, 1, 1); PG8_SCHED; PG8_LDA(At, 1, 0); PG8_STAGE(PG8_SA(0, 1), a2 + hstep, voffA);
;             PG8_WAIT_V(8); PG8_WAIT_L(0); PG8_BAR; PG8_MMA(0, 0, At, B0); PG8_MMA(0, 1, At, B1); PG8_BAR; PG8_SCHED;
	s_setprio 1
	s_waitcnt lgkmcnt(0)
	v_mfma_f32_16x16x32_bf16 v[60:63], v[112:115], v[160:163], 0
	v_mfma_f32_16x16x32_bf16 v[56:59], v[124:127], v[160:163], 0
	v_mfma_f32_16x16x32_bf16 v[44:47], v[112:115], v[168:171], 0
	v_mfma_f32_16x16x32_bf16 v[40:43], v[124:127], v[168:171], 0
	v_mfma_f32_16x16x32_bf16 v[28:31], v[112:115], v[176:179], 0
	v_mfma_f32_16x16x32_bf16 v[24:27], v[124:127], v[176:179], 0
	v_mfma_f32_16x16x32_bf16 v[12:15], v[112:115], v[184:187], 0
	v_mfma_f32_16x16x32_bf16 v[8:11], v[124:127], v[184:187], 0
	v_mfma_f32_16x16x32_bf16 v[60:63], v[120:123], v[164:167], v[60:63]
	v_mfma_f32_16x16x32_bf16 v[56:59], v[128:131], v[164:167], v[56:59]
	v_mfma_f32_16x16x32_bf16 v[44:47], v[120:123], v[172:175], v[44:47]
	v_mfma_f32_16x16x32_bf16 v[40:43], v[128:131], v[172:175], v[40:43]
	v_mfma_f32_16x16x32_bf16 v[28:31], v[120:123], v[180:183], v[28:31]
	v_mfma_f32_16x16x32_bf16 v[24:27], v[128:131], v[180:183], v[24:27]
	v_mfma_f32_16x16x32_bf16 v[12:15], v[120:123], v[188:191], v[12:15]
	v_mfma_f32_16x16x32_bf16 v[8:11], v[128:131], v[188:191], v[8:11]
	s_setprio 0
	s_setprio 1
	v_mfma_f32_16x16x32_bf16 v[52:55], v[136:139], v[160:163], 0
	v_mfma_f32_16x16x32_bf16 v[48:51], v[144:147], v[160:163], 0
	v_mfma_f32_16x16x32_bf16 v[36:39], v[136:139], v[168:171], 0
	v_mfma_f32_16x16x32_bf16 v[32:35], v[144:147], v[168:171], 0
	v_mfma_f32_16x16x32_bf16 v[20:23], v[136:139], v[176:179], 0
	v_mfma_f32_16x16x32_bf16 v[16:19], v[144:147], v[176:179], 0
	v_mfma_f32_16x16x32_bf16 v[4:7], v[136:139], v[184:187], 0
	v_mfma_f32_16x16x32_bf16 v[0:3], v[144:147], v[184:187], 0
	v_mfma_f32_16x16x32_bf16 v[52:55], v[140:143], v[164:167], v[52:55]
	v_mfma_f32_16x16x32_bf16 v[48:51], v[156:159], v[164:167], v[48:51]
	v_mfma_f32_16x16x32_bf16 v[36:39], v[140:143], v[172:175], v[36:39]
	v_mfma_f32_16x16x32_bf16 v[32:35], v[156:159], v[172:175], v[32:35]
	v_mfma_f32_16x16x32_bf16 v[20:23], v[140:143], v[180:183], v[20:23]
	v_mfma_f32_16x16x32_bf16 v[16:19], v[156:159], v[180:183], v[16:19]
	v_mfma_f32_16x16x32_bf16 v[4:7], v[140:143], v[188:191], v[4:7]
	v_mfma_f32_16x16x32_bf16 v[0:3], v[156:159], v[188:191], v[0:3]
	s_setprio 0
	s_barrier
	s_add_i32 s44, s65, 0x100
	s_add_i32 s45, s52, 0x100
	v_add_u32_e32 v128, s44, v249
	v_add_u32_e32 v156, s45, v249
	ds_read_b128 v[112:115], v128
	ds_read_b128 v[120:123], v128 offset:1024
	ds_read_b128 v[124:127], v128 offset:2048
	ds_read_b128 v[128:131], v128 offset:3072
	ds_read_b128 v[136:139], v156
	ds_read_b128 v[140:143], v156 offset:1024
	ds_read_b128 v[144:147], v156 offset:2048
	ds_read_b128 v[156:159], v156 offset:3072
	s_add_u32 s26, s26, 0x40000
	s_addc_u32 s27, s27, 0
	s_mov_b32 m0, s47
	v_lshl_add_u64 v[212:213], s[26:27], 0, v[202:203]
	ds_read_b128 v[160:163], v251 offset:32768
	ds_read_b128 v[164:167], v251 offset:33792
	ds_read_b128 v[168:171], v251 offset:34816
	ds_read_b128 v[172:175], v251 offset:35840
	ds_read_b128 v[176:179], v251 offset:36864
	ds_read_b128 v[180:183], v251 offset:37888
	ds_read_b128 v[184:187], v251 offset:38912
	ds_read_b128 v[188:191], v251 offset:39936
	global_load_lds_dwordx4 v[212:213], off
	v_lshl_add_u64 v[212:213], s[26:27], 0, v[200:201]
	s_mov_b32 m0, s60
	s_nop 0
	global_load_lds_dwordx4 v[212:213], off
	s_waitcnt vmcnt(8)
	s_waitcnt lgkmcnt(0)
	s_barrier
	s_setprio 1
	s_waitcnt lgkmcnt(0)
	v_mfma_f32_16x16x32_bf16 v[152:155], v[112:115], v[160:163], v[152:155]
	v_mfma_f32_16x16x32_bf16 v[148:151], v[124:127], v[160:163], v[148:151]
	v_mfma_f32_16x16x32_bf16 v[108:111], v[112:115], v[168:171], v[108:111]
	v_mfma_f32_16x16x32_bf16 v[104:107], v[124:127], v[168:171], v[104:107]
	v_mfma_f32_16x16x32_bf16 v[92:95], v[112:115], v[176:179], v[92:95]
	v_mfma_f32_16x16x32_bf16 v[88:91], v[124:127], v[176:179], v[88:91]
	v_mfma_f32_16x16x32_bf16 v[76:79], v[112:115], v[184:187], v[76:79]
	v_mfma_f32_16x16x32_bf16 v[72:75], v[124:127], v[184:187], v[72:75]
	v_mfma_f32_16x16x32_bf16 v[152:155], v[120:123], v[164:167], v[152:155]
	v_mfma_f32_16x16x32_bf16 v[148:151], v[128:131], v[164:167], v[148:151]
	v_mfma_f32_16x16x32_bf16 v[108:111], v[120:123], v[172:175], v[108:111]
	v_mfma_f32_16x16x32_bf16 v[104:107], v[128:131], v[172:175], v[104:107]
	v_mfma_f32_16x16x32_bf16 v[92:95], v[120:123], v[180:183], v[92:95]
	v_mfma_f32_16x16x32_bf16 v[88:91], v[128:131], v[180:183], v[88:91]
	v_mfma_f32_16x16x32_bf16 v[76:79], v[120:123], v[188:191], v[76:79]
	v_mfma_f32_16x16x32_bf16 v[72:75], v[128:131], v[188:191], v[72:75]
	s_setprio 0
	s_setprio 1
	v_mfma_f32_16x16x32_bf16 v[132:135], v[136:139], v[160:163], v[132:135]
	v_mfma_f32_16x16x32_bf16 v[116:119], v[144:147], v[160:163], v[116:119]
	v_mfma_f32_16x16x32_bf16 v[100:103], v[136:139], v[168:171], v[100:103]
	v_mfma_f32_16x16x32_bf16 v[96:99], v[144:147], v[168:171], v[96:99]
	v_mfma_f32_16x16x32_bf16 v[84:87], v[136:139], v[176:179], v[84:87]
	v_mfma_f32_16x16x32_bf16 v[80:83], v[144:147], v[176:179], v[80:83]
	v_mfma_f32_16x16x32_bf16 v[68:71], v[136:139], v[184:187], v[68:71]
	v_mfma_f32_16x16x32_bf16 v[64:67], v[144:147], v[184:187], v[64:67]
	v_mfma_f32_16x16x32_bf16 v[132:135], v[140:143], v[164:167], v[132:135]
	v_mfma_f32_16x16x32_bf16 v[116:119], v[156:159], v[164:167], v[116:119]
	v_mfma_f32_16x16x32_bf16 v[100:103], v[140:143], v[172:175], v[100:103]
	v_mfma_f32_16x16x32_bf16 v[96:99], v[156:159], v[172:175], v[96:99]
	v_mfma_f32_16x16x32_bf16 v[84:87], v[140:143], v[180:183], v[84:87]
	v_mfma_f32_16x16x32_bf16 v[80:83], v[156:159], v[180:183], v[80:83]
	v_mfma_f32_16x16x32_bf16 v[68:71], v[140:143], v[188:191], v[68:71]
	v_mfma_f32_16x16x32_bf16 v[64:67], v[156:159], v[188:191], v[64:67]
	s_setprio 0
	s_barrier
; #define PG8_STAGE(bufoff, gbase, voff) do { _Pragma("unroll") for (int _i = 0; _i < 2; ++_i) \
;         __builtin_amdgcn_global_load_lds((const unsigned*)((const char*)(gbase) + (voff)[_i]), (PG8_LAS unsigned*)(lds + (bufoff) + ldsw + _i * 8192), 16, 0, 0); } while (0)
; #define PG8_LDA(dst, b, h) do { _Pragma("unroll") for (int m = 0; m < 4; ++m) _Pragma("unroll") for (int k = 0; k < 2; ++k) dst[m][k] = *(const PG8_LAS bf16x8*)(lds + PG8_SA(b, h) + aoff + m * 2048 + k * 1024); } while (0)
; #define PG8_WAIT_V(n) asm volatile("s_waitcnt vmcnt(" #n ")" ::: "memory")
; #define PG8_WAIT_L(n) asm volatile("s_waitcnt lgkmcnt(" #n ")" ::: "memory")
; #define PG8_BAR __builtin_amdgcn_s_barrier()
; template <class Epi, class Sched, bool ALIGN_EPI = false, bool SP2 = false>
; __device__ __forceinline__ void gemm_phase(PG8_LAS unsigned char* lds, const Gemm g, const Sched& S, const Epi& E, int wave_in) {
;     ...
;         for (int t = 0; t < nt; t += 2) {
;             const bool last = (t == nt - 2);
;             const char* a1 = cA + (size_t)(t + 1) * kstep;
;             const char* a2 = last ? nA : cA + (size_t)(t + 2) * kstep; const char* b2 = last ? nB : cB + (size_t)(t + 2) * kstep;
;             const char* a3 = a2 + kstep; const char* b3 = b2 + kstep;
;             if (last && has_next) S.a_ready(nxt);
;             if constexpr (SP2) {
;             PG8_LDB(B0, 0, 0); PG8_LDB(B1, 0, 1); PG8_SCHED; PG8_LDA(At, 0, 0); PG8_STAGE(PG8_SA(1, 1), a1 + hstep, voffA);
;             PG8_WAIT_V(8); PG8_WAIT_L(0); PG8_BAR; PG8_MMA(0, 0, At, B0); PG8_MMA(0, 1, At, B1); PG8_BAR; PG8_SCHED;
;             PG8_LDA(At, 0, 1); PG8_STAGE(PG8_SB(0, 0), b2, voffB); PG8_STAGE(PG8_SB(0, 1), b2 + hstep, voffB); PG8_STAGE(PG8_SA(0, 0), a2, voffA);
;             PG8_WAIT_V(8); PG8_WAIT_L(0); PG8_BAR; PG8_MMA(1, 0, At, B0); PG8_MMA(1, 1, At, B1); PG8_BAR; PG8_SCHED;
;             PG8_LDB(B0, 1, 0); PG8_LDB(B1, 1, 1); PG8_SCHED; PG8_LDA(At, 1, 0); PG8_STAGE(PG8_SA(0, 1), a2 + hstep, voffA);
;             PG8_WAIT_V(8); PG8_WAIT_L(0); PG8_BAR; PG8_MMA(0, 0, At, B0); PG8_MMA(0, 1, At, B1); PG8_BAR; PG8_SCHED;
;             PG8_LDA(At, 1, 1); PG8_STAGE(PG8_SB(1, 0), b3, voffB); PG8_STAGE(PG8_SB(1, 1), b3 + hstep, voffB); PG8_STAGE(PG8_SA(1, 0), a3, voffA);
;             PG8_WAIT_V(8); PG8_WAIT_L(0); PG8_BAR; PG8_MMA(1, 0, At, B0); PG8_MMA(1, 1, At, B1); PG8_BAR; PG8_SCHED;
	s_add_i32 s26, s44, s38
	v_lshl_add_u64 v[194:195], v[194:195], 0, s[88:89]
	s_mov_b32 m0, s26
	ds_read_b128 v[160:163], v251 offset:49152
	ds_read_b128 v[164:167], v251 offset:50176
	ds_read_b128 v[168:171], v251 offset:51200
	ds_read_b128 v[172:175], v251 offset:52224
	ds_read_b128 v[176:179], v251 offset:53248
	ds_read_b128 v[180:183], v251 offset:54272
	ds_read_b128 v[184:187], v251 offset:55296
	ds_read_b128 v[188:191], v251 offset:56320
	global_load_lds_dwordx4 v[194:195], off
	s_add_i32 m0, s26, 0x2000
	s_add_u32 s24, s24, 0x40080
	v_lshl_add_u64 v[194:195], v[196:197], 0, s[88:89]
	s_addc_u32 s25, s25, 0
	s_add_i32 s26, s45, s38
	global_load_lds_dwordx4 v[194:195], off
	v_lshl_add_u64 v[194:195], s[24:25], 0, v[192:193]
	s_mov_b32 m0, s26
	s_nop 0
	global_load_lds_dwordx4 v[194:195], off
	v_lshl_add_u64 v[194:195], s[24:25], 0, v[198:199]
	s_add_i32 m0, s26, 0x2000
	s_nop 0
	global_load_lds_dwordx4 v[194:195], off
	v_lshl_add_u64 v[194:195], v[208:209], 0, s[88:89]
	s_mov_b32 m0, s62
	s_nop 0
	global_load_lds_dwordx4 v[194:195], off
	v_lshl_add_u64 v[194:195], v[210:211], 0, s[88:89]
	s_mov_b32 m0, s63
	s_nop 0
	global_load_lds_dwordx4 v[194:195], off
	s_waitcnt vmcnt(8)
	s_waitcnt lgkmcnt(0)
	s_barrier
	s_setprio 1
	s_waitcnt lgkmcnt(0)
	v_mfma_f32_16x16x32_bf16 v[60:63], v[112:115], v[160:163], v[60:63]
	v_mfma_f32_16x16x32_bf16 v[56:59], v[124:127], v[160:163], v[56:59]
	v_mfma_f32_16x16x32_bf16 v[44:47], v[112:115], v[168:171], v[44:47]
	v_mfma_f32_16x16x32_bf16 v[40:43], v[124:127], v[168:171], v[40:43]
	v_mfma_f32_16x16x32_bf16 v[28:31], v[112:115], v[176:179], v[28:31]
	v_mfma_f32_16x16x32_bf16 v[24:27], v[124:127], v[176:179], v[24:27]
	v_mfma_f32_16x16x32_bf16 v[12:15], v[112:115], v[184:187], v[12:15]
	v_mfma_f32_16x16x32_bf16 v[8:11], v[124:127], v[184:187], v[8:11]
	v_mfma_f32_16x16x32_bf16 v[60:63], v[120:123], v[164:167], v[60:63]
	v_mfma_f32_16x16x32_bf16 v[56:59], v[128:131], v[164:167], v[56:59]
	v_mfma_f32_16x16x32_bf16 v[44:47], v[120:123], v[172:175], v[44:47]
	v_mfma_f32_16x16x32_bf16 v[40:43], v[128:131], v[172:175], v[40:43]
	v_mfma_f32_16x16x32_bf16 v[28:31], v[120:123], v[180:183], v[28:31]
	v_mfma_f32_16x16x32_bf16 v[24:27], v[128:131], v[180:183], v[24:27]
	v_mfma_f32_16x16x32_bf16 v[12:15], v[120:123], v[188:191], v[12:15]
	v_mfma_f32_16x16x32_bf16 v[8:11], v[128:131], v[188:191], v[8:11]
	s_setprio 0
	s_setprio 1
	v_mfma_f32_16x16x32_bf16 v[52:55], v[136:139], v[160:163], v[52:55]
	v_mfma_f32_16x16x32_bf16 v[48:51], v[144:147], v[160:163], v[48:51]
	v_mfma_f32_16x16x32_bf16 v[36:39], v[136:139], v[168:171], v[36:39]
	v_mfma_f32_16x16x32_bf16 v[32:35], v[144:147], v[168:171], v[32:35]
	v_mfma_f32_16x16x32_bf16 v[20:23], v[136:139], v[176:179], v[20:23]
	v_mfma_f32_16x16x32_bf16 v[16:19], v[144:147], v[176:179], v[16:19]
	v_mfma_f32_16x16x32_bf16 v[4:7], v[136:139], v[184:187], v[4:7]
	v_mfma_f32_16x16x32_bf16 v[0:3], v[144:147], v[184:187], v[0:3]
	v_mfma_f32_16x16x32_bf16 v[52:55], v[140:143], v[164:167], v[52:55]
	v_mfma_f32_16x16x32_bf16 v[48:51], v[156:159], v[164:167], v[48:51]
	v_mfma_f32_16x16x32_bf16 v[36:39], v[140:143], v[172:175], v[36:39]
	v_mfma_f32_16x16x32_bf16 v[32:35], v[156:159], v[172:175], v[32:35]
	v_mfma_f32_16x16x32_bf16 v[20:23], v[140:143], v[180:183], v[20:23]
	v_mfma_f32_16x16x32_bf16 v[16:19], v[156:159], v[180:183], v[16:19]
	v_mfma_f32_16x16x32_bf16 v[4:7], v[140:143], v[188:191], v[4:7]
	v_mfma_f32_16x16x32_bf16 v[0:3], v[156:159], v[188:191], v[0:3]
	s_setprio 0
	s_barrier
	s_add_i32 s34, s34, 2
	s_add_u32 s15, s15, 0x100
	s_addc_u32 s17, s17, 0
	s_add_u32 s22, s22, 0x100
	s_addc_u32 s23, s23, 0
	s_cmp_gt_u32 s34, 13
	s_cbranch_scc1 .Lkexit_5

; #define PG8_STAGE(bufoff, gbase, voff) do { _Pragma("unroll") for (int _i = 0; _i < 2; ++_i) \
;         __builtin_amdgcn_global_load_lds((const unsigned*)((const char*)(gbase) + (voff)[_i]), (PG8_LAS unsigned*)(lds + (bufoff) + ldsw + _i * 8192), 16, 0, 0); } while (0)
; #define PG8_LDA(dst, b, h) do { _Pragma("unroll") for (int m = 0; m < 4; ++m) _Pragma("unroll") for (int k = 0; k < 2; ++k) dst[m][k] = *(const PG8_LAS bf16x8*)(lds + PG8_SA(b, h) + aoff + m * 2048 + k * 1024); } while (0)
; #define PG8_LDB(dst, b, h) do { _Pragma("unroll") for (int n = 0; n < 2; ++n) _Pragma("unroll") for (int k = 0; k < 2; ++k) dst[n][k] = *(const PG8_LAS bf16x8*)(lds + PG8_SB(b, h) + boff + n * 2048 + k * 1024); } while (0)
; #define PG8_WAIT_V(n) asm volatile("s_waitcnt vmcnt(" #n ")" ::: "memory")
; template <class Epi, class Sched, bool ALIGN_EPI = false, bool SP2 = false>
; __device__ __forceinline__ void gemm_phase(PG8_LAS unsigned char* lds, const Gemm g, const Sched& S, const Epi& E, int wave_in) {
;     ...
;         const char* nA = has_next ? (const char*)g.A + (size_t)(nxt.pm >> g.ash) * g.astride + (size_t)nxt.pm * tstep : cA; const char* nB = has_next ? (const char*)g.Bt + (size_t)(nxt.pm >> g.bsh) * g.bstride + (size_t)nxt.pn * tstep : cB;
;         for (int t = 0; t < nt; t += 2) {
;             const bool last = (t == nt - 2);
;             const char* a1 = cA + (size_t)(t + 1) * kstep;
;             const char* a2 = last ? nA : cA + (size_t)(t + 2) * kstep; const char* b2 = last ? nB : cB + (size_t)(t + 2) * kstep;
;             const char* a3 = a2 + kstep; const char* b3 = b2 + kstep;
;             if (last && has_next) S.a_ready(nxt);
;             if constexpr (SP2) {
;             PG8_LDB(B0, 0, 0); PG8_LDB(B1, 0, 1); PG8_SCHED; PG8_LDA(At, 0, 0); PG8_STAGE(PG8_SA(1, 1), a1 + hstep, voffA);
;             PG8_WAIT_V(8); PG8_WAIT_L(0); PG8_BAR; PG8_MMA(0, 0, At, B0); PG8_MMA(0, 1, At, B1); PG8_BAR; PG8_SCHED;
;             PG8_LDA(At, 0, 1); PG8_STAGE(PG8_SB(0, 0), b2, voffB); PG8_STAGE(PG8_SB(0, 1), b2 + hstep, voffB); PG8_STAGE(PG8_SA(0, 0), a2, voffA);
;     ...
; #pragma unroll
;         for (int a = 0; a < 2; ++a)
; #pragma unroll
;             for (int b = 0; b < 2; ++b)
; #pragma unroll
;                 for (int m = 0; m < 4; ++m)
; #pragma unroll
;                     for (int n = 0; n < 2; ++n) acc[a][b][m][n] = (f32x4){0.f, 0.f, 0.f, 0.f};
.LBB0_896:
	s_ashr_i32 s11, s10, 31
	s_lshl_b64 s[18:19], s[10:11], 19
	s_add_u32 s66, s6, s18
	s_addc_u32 s67, s72, s19
	s_and_b64 s[18:19], s[46:47], exec
	s_cselect_b32 s11, s67, s1
	s_cselect_b32 s34, s66, s0
	s_ashr_i32 s5, s4, 31
	s_lshl_b64 s[18:19], s[4:5], 19
	s_add_u32 s38, s73, s18
	s_addc_u32 s39, s74, s19
	s_and_b64 s[18:19], s[46:47], exec
	s_cselect_b32 s5, s39, s79
	s_cselect_b32 s53, s38, s78
	s_add_u32 s81, s78, 0x100
	s_addc_u32 s18, s79, 0
	s_add_u32 vcc_lo, s0, 0x40080
	s_addc_u32 vcc_hi, s1, 0
	s_mov_b32 s19, -2
	s_add_u32 s0, vcc_lo, 0xfffc0080
	s_addc_u32 s1, vcc_hi, -1
	s_add_i32 s76, s35, 0x100
	s_cmp_eq_u32 s19, 12
	s_cselect_b32 s79, s11, s1
	s_cselect_b32 s78, s34, s0
	s_cselect_b32 s1, s5, s18
	s_cselect_b32 s0, s53, s81
	s_add_i32 s29, s90, 0x100
	v_add_u32_e32 v140, s76, v207
	v_add_u32_e32 v156, s29, v207
	ds_read_b128 v[128:131], v140
	ds_read_b128 v[132:135], v140 offset:1024
	ds_read_b128 v[136:139], v140 offset:2048
	ds_read_b128 v[140:143], v140 offset:3072
	ds_read_b128 v[144:147], v156
	ds_read_b128 v[148:151], v156 offset:1024
	ds_read_b128 v[152:155], v156 offset:2048
	ds_read_b128 v[156:159], v156 offset:3072
	v_lshl_add_u64 v[190:191], vcc, 0, v[176:177]
	s_add_i32 m0, s33, 0xc000
	ds_read_b128 v[160:163], v219
	ds_read_b128 v[164:167], v219 offset:1024
	ds_read_b128 v[178:181], v219 offset:2048
	ds_read_b128 v[182:185], v219 offset:3072
	ds_read_b128 v[186:189], v219 offset:4096
	ds_read_b128 v[198:201], v219 offset:5120
	ds_read_b128 v[202:205], v219 offset:6144
	ds_read_b128 v[220:223], v219 offset:7168
	global_load_lds_dwordx4 v[190:191], off
	v_lshl_add_u64 v[190:191], vcc, 0, v[174:175]
	s_add_i32 m0, s33, 0xe000
	s_nop 0
	global_load_lds_dwordx4 v[190:191], off
	s_waitcnt vmcnt(8)
	s_waitcnt lgkmcnt(0)
	s_barrier
	s_setprio 1
	s_waitcnt lgkmcnt(0)
	v_mfma_f32_16x16x32_bf16 v[124:127], v[128:131], v[160:163], 0
	v_mfma_f32_16x16x32_bf16 v[60:63], v[136:139], v[160:163], 0
	v_mfma_f32_16x16x32_bf16 v[116:119], v[128:131], v[178:181], 0
	v_mfma_f32_16x16x32_bf16 v[52:55], v[136:139], v[178:181], 0
	v_mfma_f32_16x16x32_bf16 v[108:111], v[128:131], v[186:189], 0
	v_mfma_f32_16x16x32_bf16 v[44:47], v[136:139], v[186:189], 0
	v_mfma_f32_16x16x32_bf16 v[100:103], v[128:131], v[202:205], 0
	v_mfma_f32_16x16x32_bf16 v[36:39], v[136:139], v[202:205], 0
	v_mfma_f32_16x16x32_bf16 v[124:127], v[132:135], v[164:167], v[124:127]
	v_mfma_f32_16x16x32_bf16 v[60:63], v[140:143], v[164:167], v[60:63]
	v_mfma_f32_16x16x32_bf16 v[116:119], v[132:135], v[182:185], v[116:119]
	v_mfma_f32_16x16x32_bf16 v[52:55], v[140:143], v[182:185], v[52:55]
	v_mfma_f32_16x16x32_bf16 v[108:111], v[132:135], v[198:201], v[108:111]
	v_mfma_f32_16x16x32_bf16 v[44:47], v[140:143], v[198:201], v[44:47]
	v_mfma_f32_16x16x32_bf16 v[100:103], v[132:135], v[220:223], v[100:103]
	v_mfma_f32_16x16x32_bf16 v[36:39], v[140:143], v[220:223], v[36:39]
	s_setprio 0
	s_setprio 1
	v_mfma_f32_16x16x32_bf16 v[120:123], v[144:147], v[160:163], 0
	v_mfma_f32_16x16x32_bf16 v[56:59], v[152:155], v[160:163], 0
	v_mfma_f32_16x16x32_bf16 v[112:115], v[144:147], v[178:181], 0
	v_mfma_f32_16x16x32_bf16 v[48:51], v[152:155], v[178:181], 0
	v_mfma_f32_16x16x32_bf16 v[104:107], v[144:147], v[186:189], 0
	v_mfma_f32_16x16x32_bf16 v[40:43], v[152:155], v[186:189], 0
	v_mfma_f32_16x16x32_bf16 v[96:99], v[144:147], v[202:205], 0
	v_mfma_f32_16x16x32_bf16 v[32:35], v[152:155], v[202:205], 0
	v_mfma_f32_16x16x32_bf16 v[120:123], v[148:151], v[164:167], v[120:123]
	v_mfma_f32_16x16x32_bf16 v[56:59], v[156:159], v[164:167], v[56:59]
	v_mfma_f32_16x16x32_bf16 v[112:115], v[148:151], v[182:185], v[112:115]
	v_mfma_f32_16x16x32_bf16 v[48:51], v[156:159], v[182:185], v[48:51]
	v_mfma_f32_16x16x32_bf16 v[104:107], v[148:151], v[198:201], v[104:107]
	v_mfma_f32_16x16x32_bf16 v[40:43], v[156:159], v[198:201], v[40:43]
	v_mfma_f32_16x16x32_bf16 v[96:99], v[148:151], v[220:223], v[96:99]
	v_mfma_f32_16x16x32_bf16 v[32:35], v[156:159], v[220:223], v[32:35]
	s_setprio 0
	s_barrier
	s_add_i32 s76, s76, s75
	v_lshl_add_u64 v[190:191], s[0:1], 0, v[192:193]
	s_mov_b32 m0, s76
	ds_read_b128 v[160:163], v219 offset:16384
	ds_read_b128 v[164:167], v219 offset:17408
	ds_read_b128 v[178:181], v219 offset:18432
	ds_read_b128 v[182:185], v219 offset:19456
	ds_read_b128 v[186:189], v219 offset:20480
	ds_read_b128 v[198:201], v219 offset:21504
	ds_read_b128 v[202:205], v219 offset:22528
	ds_read_b128 v[220:223], v219 offset:23552
	global_load_lds_dwordx4 v[190:191], off
	s_add_i32 m0, s76, 0x2000
	s_add_u32 s76, s0, 0x40000
	v_lshl_add_u64 v[194:195], s[0:1], 0, v[168:169]
	s_addc_u32 s77, s1, 0
	s_add_i32 s29, s29, s75
	global_load_lds_dwordx4 v[194:195], off
	v_lshl_add_u64 v[196:197], s[76:77], 0, v[192:193]
	s_mov_b32 m0, s29
	v_lshl_add_u64 v[224:225], s[78:79], 0, v[170:171]
	global_load_lds_dwordx4 v[196:197], off
	v_lshl_add_u64 v[196:197], s[76:77], 0, v[168:169]
	s_add_i32 m0, s29, 0x2000
	s_nop 0
	global_load_lds_dwordx4 v[196:197], off
	v_lshl_add_u64 v[196:197], s[78:79], 0, v[172:173]
	s_mov_b32 m0, s33
	s_nop 0
	global_load_lds_dwordx4 v[196:197], off
	s_mov_b32 m0, s62
	s_nop 0
	global_load_lds_dwordx4 v[224:225], off
	s_waitcnt vmcnt(8)
	s_waitcnt lgkmcnt(0)
	s_barrier
; #define PG8_STAGE(bufoff, gbase, voff) do { _Pragma("unroll") for (int _i = 0; _i < 2; ++_i) \
;         __builtin_amdgcn_global_load_lds((const unsigned*)((const char*)(gbase) + (voff)[_i]), (PG8_LAS unsigned*)(lds + (bufoff) + ldsw + _i * 8192), 16, 0, 0); } while (0)
; #define PG8_LDA(dst, b, h) do { _Pragma("unroll") for (int m = 0; m < 4; ++m) _Pragma("unroll") for (int k = 0; k < 2; ++k) dst[m][k] = *(const PG8_LAS bf16x8*)(lds + PG8_SA(b, h) + aoff + m * 2048 + k * 1024); } while (0)
; #define PG8_LDB(dst, b, h) do { _Pragma("unroll") for (int n = 0; n < 2; ++n) _Pragma("unroll") for (int k = 0; k < 2; ++k) dst[n][k] = *(const PG8_LAS bf16x8*)(lds + PG8_SB(b, h) + boff + n * 2048 + k * 1024); } while (0)
; #define PG8_MMA(ai, bj, At, Bt) do { __builtin_amdgcn_s_setprio(1); _Pragma("unroll") for (int m = 0; m < 4; ++m) _Pragma("unroll") for (int n = 0; n < 2; ++n) _Pragma("unroll") for (int k = 0; k < 2; ++k) \
;         acc[ai][bj][m][n] = __builtin_amdgcn_mfma_f32_16x16x32_bf16(Bt[n][k], At[m][k], acc[ai][bj][m][n], 0, 0, 0); __builtin_amdgcn_s_setprio(0); } while (0)
; #define PG8_WAIT_V(n) asm volatile("s_waitcnt vmcnt(" #n ")" ::: "memory")
; #define PG8_WAIT_L(n) asm volatile("s_waitcnt lgkmcnt(" #n ")" ::: "memory")
; #define PG8_BAR __builtin_amdgcn_s_barrier()
; #define PG8_SCHED __builtin_amdgcn_sched_barrier(0)
; template <class Epi, class Sched, bool ALIGN_EPI = false, bool SP2 = false>
; __device__ __forceinline__ void gemm_phase(PG8_LAS unsigned char* lds, const Gemm g, const Sched& S, const Epi& E, int wave_in) {
;     ...
;             PG8_WAIT_V(8); PG8_WAIT_L(0); PG8_BAR; PG8_MMA(1, 0, At, B0); PG8_MMA(1, 1, At, B1); PG8_BAR; PG8_SCHED;
;             PG8_LDB(B0, 1, 0); PG8_LDB(B1, 1, 1); PG8_SCHED; PG8_LDA(At, 1, 0); PG8_STAGE(PG8_SA(0, 1), a2 + hstep, voffA);
;             PG8_WAIT_V(8); PG8_WAIT_L(0); PG8_BAR; PG8_MMA(0, 0, At, B0); PG8_MMA(0, 1, At, B1); PG8_BAR; PG8_SCHED;
	s_setprio 1
	s_waitcnt lgkmcnt(0)
	v_mfma_f32_16x16x32_bf16 v[92:95], v[128:131], v[160:163], 0
	v_mfma_f32_16x16x32_bf16 v[28:31], v[136:139], v[160:163], 0
	v_mfma_f32_16x16x32_bf16 v[84:87], v[128:131], v[178:181], 0
	v_mfma_f32_16x16x32_bf16 v[20:23], v[136:139], v[178:181], 0
	v_mfma_f32_16x16x32_bf16 v[76:79], v[128:131], v[186:189], 0
	v_mfma_f32_16x16x32_bf16 v[12:15], v[136:139], v[186:189], 0
	v_mfma_f32_16x16x32_bf16 v[68:71], v[128:131], v[202:205], 0
	v_mfma_f32_16x16x32_bf16 v[4:7], v[136:139], v[202:205], 0
	v_mfma_f32_16x16x32_bf16 v[92:95], v[132:135], v[164:167], v[92:95]
	v_mfma_f32_16x16x32_bf16 v[28:31], v[140:143], v[164:167], v[28:31]
	v_mfma_f32_16x16x32_bf16 v[84:87], v[132:135], v[182:185], v[84:87]
	v_mfma_f32_16x16x32_bf16 v[20:23], v[140:143], v[182:185], v[20:23]
	v_mfma_f32_16x16x32_bf16 v[76:79], v[132:135], v[198:201], v[76:79]
	v_mfma_f32_16x16x32_bf16 v[12:15], v[140:143], v[198:201], v[12:15]
	v_mfma_f32_16x16x32_bf16 v[68:71], v[132:135], v[220:223], v[68:71]
	v_mfma_f32_16x16x32_bf16 v[4:7], v[140:143], v[220:223], v[4:7]
	s_setprio 0
	s_setprio 1
	v_mfma_f32_16x16x32_bf16 v[88:91], v[144:147], v[160:163], 0
	v_mfma_f32_16x16x32_bf16 v[24:27], v[152:155], v[160:163], 0
	v_mfma_f32_16x16x32_bf16 v[80:83], v[144:147], v[178:181], 0
	v_mfma_f32_16x16x32_bf16 v[16:19], v[152:155], v[178:181], 0
	v_mfma_f32_16x16x32_bf16 v[72:75], v[144:147], v[186:189], 0
	v_mfma_f32_16x16x32_bf16 v[8:11], v[152:155], v[186:189], 0
	v_mfma_f32_16x16x32_bf16 v[64:67], v[144:147], v[202:205], 0
	v_mfma_f32_16x16x32_bf16 v[0:3], v[152:155], v[202:205], 0
	v_mfma_f32_16x16x32_bf16 v[88:91], v[148:151], v[164:167], v[88:91]
	v_mfma_f32_16x16x32_bf16 v[24:27], v[156:159], v[164:167], v[24:27]
	v_mfma_f32_16x16x32_bf16 v[80:83], v[148:151], v[182:185], v[80:83]
	v_mfma_f32_16x16x32_bf16 v[16:19], v[156:159], v[182:185], v[16:19]
	v_mfma_f32_16x16x32_bf16 v[72:75], v[148:151], v[198:201], v[72:75]
	v_mfma_f32_16x16x32_bf16 v[8:11], v[156:159], v[198:201], v[8:11]
	v_mfma_f32_16x16x32_bf16 v[64:67], v[148:151], v[220:223], v[64:67]
	v_mfma_f32_16x16x32_bf16 v[0:3], v[156:159], v[220:223], v[0:3]
	s_setprio 0
	s_barrier
	s_add_i32 s29, s65, 0x100
	s_add_i32 s2, s52, 0x100
	v_add_u32_e32 v140, s29, v207
	v_add_u32_e32 v156, s2, v207
	ds_read_b128 v[128:131], v140
	ds_read_b128 v[132:135], v140 offset:1024
	ds_read_b128 v[136:139], v140 offset:2048
	ds_read_b128 v[140:143], v140 offset:3072
	ds_read_b128 v[144:147], v156
	ds_read_b128 v[148:151], v156 offset:1024
	ds_read_b128 v[152:155], v156 offset:2048
	ds_read_b128 v[156:159], v156 offset:3072
	s_add_u32 s76, s78, 0x40000
	s_addc_u32 s77, s79, 0
	s_mov_b32 m0, s63
	v_lshl_add_u64 v[226:227], s[76:77], 0, v[172:173]
	ds_read_b128 v[160:163], v219 offset:32768
	ds_read_b128 v[164:167], v219 offset:33792
	ds_read_b128 v[178:181], v219 offset:34816
	ds_read_b128 v[182:185], v219 offset:35840
	ds_read_b128 v[186:189], v219 offset:36864
	ds_read_b128 v[198:201], v219 offset:37888
	ds_read_b128 v[202:205], v219 offset:38912
	ds_read_b128 v[220:223], v219 offset:39936
	global_load_lds_dwordx4 v[226:227], off
	v_lshl_add_u64 v[226:227], s[76:77], 0, v[170:171]
	s_mov_b32 m0, s31
	s_nop 0
	global_load_lds_dwordx4 v[226:227], off
	s_waitcnt vmcnt(8)
	s_waitcnt lgkmcnt(0)
	s_barrier
	s_setprio 1
	s_waitcnt lgkmcnt(0)
	v_mfma_f32_16x16x32_bf16 v[124:127], v[128:131], v[160:163], v[124:127]
	v_mfma_f32_16x16x32_bf16 v[60:63], v[136:139], v[160:163], v[60:63]
	v_mfma_f32_16x16x32_bf16 v[116:119], v[128:131], v[178:181], v[116:119]
	v_mfma_f32_16x16x32_bf16 v[52:55], v[136:139], v[178:181], v[52:55]
	v_mfma_f32_16x16x32_bf16 v[108:111], v[128:131], v[186:189], v[108:111]
	v_mfma_f32_16x16x32_bf16 v[44:47], v[136:139], v[186:189], v[44:47]
	v_mfma_f32_16x16x32_bf16 v[100:103], v[128:131], v[202:205], v[100:103]
	v_mfma_f32_16x16x32_bf16 v[36:39], v[136:139], v[202:205], v[36:39]
	v_mfma_f32_16x16x32_bf16 v[124:127], v[132:135], v[164:167], v[124:127]
	v_mfma_f32_16x16x32_bf16 v[60:63], v[140:143], v[164:167], v[60:63]
	v_mfma_f32_16x16x32_bf16 v[116:119], v[132:135], v[182:185], v[116:119]
	v_mfma_f32_16x16x32_bf16 v[52:55], v[140:143], v[182:185], v[52:55]
	v_mfma_f32_16x16x32_bf16 v[108:111], v[132:135], v[198:201], v[108:111]
	v_mfma_f32_16x16x32_bf16 v[44:47], v[140:143], v[198:201], v[44:47]
	v_mfma_f32_16x16x32_bf16 v[100:103], v[132:135], v[220:223], v[100:103]
	v_mfma_f32_16x16x32_bf16 v[36:39], v[140:143], v[220:223], v[36:39]
	s_setprio 0
	s_setprio 1
	v_mfma_f32_16x16x32_bf16 v[120:123], v[144:147], v[160:163], v[120:123]
	v_mfma_f32_16x16x32_bf16 v[56:59], v[152:155], v[160:163], v[56:59]
	v_mfma_f32_16x16x32_bf16 v[112:115], v[144:147], v[178:181], v[112:115]
	v_mfma_f32_16x16x32_bf16 v[48:51], v[152:155], v[178:181], v[48:51]
	v_mfma_f32_16x16x32_bf16 v[104:107], v[144:147], v[186:189], v[104:107]
	v_mfma_f32_16x16x32_bf16 v[40:43], v[152:155], v[186:189], v[40:43]
	v_mfma_f32_16x16x32_bf16 v[96:99], v[144:147], v[202:205], v[96:99]
	v_mfma_f32_16x16x32_bf16 v[32:35], v[152:155], v[202:205], v[32:35]
	v_mfma_f32_16x16x32_bf16 v[120:123], v[148:151], v[164:167], v[120:123]
	v_mfma_f32_16x16x32_bf16 v[56:59], v[156:159], v[164:167], v[56:59]
	v_mfma_f32_16x16x32_bf16 v[112:115], v[148:151], v[182:185], v[112:115]
	v_mfma_f32_16x16x32_bf16 v[48:51], v[156:159], v[182:185], v[48:51]
	v_mfma_f32_16x16x32_bf16 v[104:107], v[148:151], v[198:201], v[104:107]
	v_mfma_f32_16x16x32_bf16 v[40:43], v[156:159], v[198:201], v[40:43]
	v_mfma_f32_16x16x32_bf16 v[96:99], v[148:151], v[220:223], v[96:99]
	v_mfma_f32_16x16x32_bf16 v[32:35], v[156:159], v[220:223], v[32:35]
	s_setprio 0
	s_barrier
; #define PG8_STAGE(bufoff, gbase, voff) do { _Pragma("unroll") for (int _i = 0; _i < 2; ++_i) \
;         __builtin_amdgcn_global_load_lds((const unsigned*)((const char*)(gbase) + (voff)[_i]), (PG8_LAS unsigned*)(lds + (bufoff) + ldsw + _i * 8192), 16, 0, 0); } while (0)
; #define PG8_LDA(dst, b, h) do { _Pragma("unroll") for (int m = 0; m < 4; ++m) _Pragma("unroll") for (int k = 0; k < 2; ++k) dst[m][k] = *(const PG8_LAS bf16x8*)(lds + PG8_SA(b, h) + aoff + m * 2048 + k * 1024); } while (0)
; #define PG8_MMA(ai, bj, At, Bt) do { __builtin_amdgcn_s_setprio(1); _Pragma("unroll") for (int m = 0; m < 4; ++m) _Pragma("unroll") for (int n = 0; n < 2; ++n) _Pragma("unroll") for (int k = 0; k < 2; ++k) \
;         acc[ai][bj][m][n] = __builtin_amdgcn_mfma_f32_16x16x32_bf16(Bt[n][k], At[m][k], acc[ai][bj][m][n], 0, 0, 0); __builtin_amdgcn_s_setprio(0); } while (0)
; #define PG8_WAIT_V(n) asm volatile("s_waitcnt vmcnt(" #n ")" ::: "memory")
; #define PG8_WAIT_L(n) asm volatile("s_waitcnt lgkmcnt(" #n ")" ::: "memory")
; #define PG8_BAR __builtin_amdgcn_s_barrier()
; #define PG8_SCHED __builtin_amdgcn_sched_barrier(0)
; template <class Epi, class Sched, bool ALIGN_EPI = false, bool SP2 = false>
; __device__ __forceinline__ void gemm_phase(PG8_LAS unsigned char* lds, const Gemm g, const Sched& S, const Epi& E, int wave_in) {
;     ...
;         for (int t = 0; t < nt; t += 2) {
;             const bool last = (t == nt - 2);
;             const char* a1 = cA + (size_t)(t + 1) * kstep;
;             const char* a2 = last ? nA : cA + (size_t)(t + 2) * kstep; const char* b2 = last ? nB : cB + (size_t)(t + 2) * kstep;
;     ...
;             PG8_LDA(At, 1, 1); PG8_STAGE(PG8_SB(1, 0), b3, voffB); PG8_STAGE(PG8_SB(1, 1), b3 + hstep, voffB); PG8_STAGE(PG8_SA(1, 0), a3, voffA);
;             PG8_WAIT_V(8); PG8_WAIT_L(0); PG8_BAR; PG8_MMA(1, 0, At, B0); PG8_MMA(1, 1, At, B1); PG8_BAR; PG8_SCHED;
	s_add_i32 s29, s29, s75
	v_lshl_add_u64 v[190:191], v[190:191], 0, s[88:89]
	s_mov_b32 m0, s29
	ds_read_b128 v[160:163], v219 offset:49152
	ds_read_b128 v[164:167], v219 offset:50176
	ds_read_b128 v[178:181], v219 offset:51200
	ds_read_b128 v[182:185], v219 offset:52224
	ds_read_b128 v[186:189], v219 offset:53248
	ds_read_b128 v[198:201], v219 offset:54272
	ds_read_b128 v[202:205], v219 offset:55296
	ds_read_b128 v[220:223], v219 offset:56320
	global_load_lds_dwordx4 v[190:191], off
	s_add_i32 m0, s29, 0x2000
	s_add_u32 s0, s0, 0x40080
	v_lshl_add_u64 v[190:191], v[194:195], 0, s[88:89]
	s_addc_u32 s1, s1, 0
	s_add_i32 s2, s2, s75
	global_load_lds_dwordx4 v[190:191], off
	v_lshl_add_u64 v[190:191], s[0:1], 0, v[192:193]
	s_mov_b32 m0, s2
	s_nop 0
	global_load_lds_dwordx4 v[190:191], off
	v_lshl_add_u64 v[190:191], s[0:1], 0, v[168:169]
	s_add_i32 m0, s2, 0x2000
	s_nop 0
	global_load_lds_dwordx4 v[190:191], off
	v_lshl_add_u64 v[190:191], v[196:197], 0, s[88:89]
	s_mov_b32 m0, s9
	s_nop 0
	global_load_lds_dwordx4 v[190:191], off
	v_lshl_add_u64 v[190:191], v[224:225], 0, s[88:89]
	s_mov_b32 m0, s96
	s_nop 0
	global_load_lds_dwordx4 v[190:191], off
	s_waitcnt vmcnt(8)
	s_waitcnt lgkmcnt(0)
	s_barrier
	s_setprio 1
	s_waitcnt lgkmcnt(0)
	v_mfma_f32_16x16x32_bf16 v[92:95], v[128:131], v[160:163], v[92:95]
	v_mfma_f32_16x16x32_bf16 v[28:31], v[136:139], v[160:163], v[28:31]
	v_mfma_f32_16x16x32_bf16 v[84:87], v[128:131], v[178:181], v[84:87]
	v_mfma_f32_16x16x32_bf16 v[20:23], v[136:139], v[178:181], v[20:23]
	v_mfma_f32_16x16x32_bf16 v[76:79], v[128:131], v[186:189], v[76:79]
	v_mfma_f32_16x16x32_bf16 v[12:15], v[136:139], v[186:189], v[12:15]
	v_mfma_f32_16x16x32_bf16 v[68:71], v[128:131], v[202:205], v[68:71]
	v_mfma_f32_16x16x32_bf16 v[4:7], v[136:139], v[202:205], v[4:7]
	v_mfma_f32_16x16x32_bf16 v[92:95], v[132:135], v[164:167], v[92:95]
	v_mfma_f32_16x16x32_bf16 v[28:31], v[140:143], v[164:167], v[28:31]
	v_mfma_f32_16x16x32_bf16 v[84:87], v[132:135], v[182:185], v[84:87]
	v_mfma_f32_16x16x32_bf16 v[20:23], v[140:143], v[182:185], v[20:23]
	v_mfma_f32_16x16x32_bf16 v[76:79], v[132:135], v[198:201], v[76:79]
	v_mfma_f32_16x16x32_bf16 v[12:15], v[140:143], v[198:201], v[12:15]
	v_mfma_f32_16x16x32_bf16 v[68:71], v[132:135], v[220:223], v[68:71]
	v_mfma_f32_16x16x32_bf16 v[4:7], v[140:143], v[220:223], v[4:7]
	s_setprio 0
	s_setprio 1
	v_mfma_f32_16x16x32_bf16 v[88:91], v[144:147], v[160:163], v[88:91]
	v_mfma_f32_16x16x32_bf16 v[24:27], v[152:155], v[160:163], v[24:27]
	v_mfma_f32_16x16x32_bf16 v[80:83], v[144:147], v[178:181], v[80:83]
	v_mfma_f32_16x16x32_bf16 v[16:19], v[152:155], v[178:181], v[16:19]
	v_mfma_f32_16x16x32_bf16 v[72:75], v[144:147], v[186:189], v[72:75]
	v_mfma_f32_16x16x32_bf16 v[8:11], v[152:155], v[186:189], v[8:11]
	v_mfma_f32_16x16x32_bf16 v[64:67], v[144:147], v[202:205], v[64:67]
	v_mfma_f32_16x16x32_bf16 v[0:3], v[152:155], v[202:205], v[0:3]
	v_mfma_f32_16x16x32_bf16 v[88:91], v[148:151], v[164:167], v[88:91]
	v_mfma_f32_16x16x32_bf16 v[24:27], v[156:159], v[164:167], v[24:27]
	v_mfma_f32_16x16x32_bf16 v[80:83], v[148:151], v[182:185], v[80:83]
	v_mfma_f32_16x16x32_bf16 v[16:19], v[156:159], v[182:185], v[16:19]
	v_mfma_f32_16x16x32_bf16 v[72:75], v[148:151], v[198:201], v[72:75]
	v_mfma_f32_16x16x32_bf16 v[8:11], v[156:159], v[198:201], v[8:11]
	v_mfma_f32_16x16x32_bf16 v[64:67], v[148:151], v[220:223], v[64:67]
	v_mfma_f32_16x16x32_bf16 v[0:3], v[156:159], v[220:223], v[0:3]
	s_setprio 0
	s_barrier
	s_add_i32 s19, s19, 2
	s_add_u32 s81, s81, 0x100
	s_addc_u32 s18, s18, 0
	s_add_u32 vcc_lo, vcc_lo, 0x100
	s_addc_u32 vcc_hi, vcc_hi, 0
	s_cmp_gt_u32 s19, 13
	s_cbranch_scc1 .Lkexit_6

; #define PG8_BAR __builtin_amdgcn_s_barrier()
; template <class Epi, class Sched, bool ALIGN_EPI = false, bool SP2 = false>
; __device__ __forceinline__ void gemm_phase(PG8_LAS unsigned char* lds, const Gemm g, const Sched& S, const Epi& E, int wave_in) {
;     ...
;         if constexpr (ALIGN_EPI) { if (wr == 0) PG8_BAR; }
.Lkexit_6:
	s_and_b64 vcc, exec, s[94:95]
	s_cbranch_vccz .LBB0_900
	s_barrier

; #define PG8_STAGE(bufoff, gbase, voff) do { _Pragma("unroll") for (int _i = 0; _i < 2; ++_i) \
;         __builtin_amdgcn_global_load_lds((const unsigned*)((const char*)(gbase) + (voff)[_i]), (PG8_LAS unsigned*)(lds + (bufoff) + ldsw + _i * 8192), 16, 0, 0); } while (0)
; #define PG8_LDA(dst, b, h) do { _Pragma("unroll") for (int m = 0; m < 4; ++m) _Pragma("unroll") for (int k = 0; k < 2; ++k) dst[m][k] = *(const PG8_LAS bf16x8*)(lds + PG8_SA(b, h) + aoff + m * 2048 + k * 1024); } while (0)
; #define PG8_LDB(dst, b, h) do { _Pragma("unroll") for (int n = 0; n < 2; ++n) _Pragma("unroll") for (int k = 0; k < 2; ++k) dst[n][k] = *(const PG8_LAS bf16x8*)(lds + PG8_SB(b, h) + boff + n * 2048 + k * 1024); } while (0)
; #define PG8_WAIT_V(n) asm volatile("s_waitcnt vmcnt(" #n ")" ::: "memory")
; #define PG8_WAIT_L(n) asm volatile("s_waitcnt lgkmcnt(" #n ")" ::: "memory")
; #define PG8_BAR __builtin_amdgcn_s_barrier()
; #define PG8_SCHED __builtin_amdgcn_sched_barrier(0)
; template <class Epi, class Sched, bool ALIGN_EPI = false, bool SP2 = false>
; __device__ __forceinline__ void gemm_phase(PG8_LAS unsigned char* lds, const Gemm g, const Sched& S, const Epi& E, int wave_in) {
;     ...
;             const char* a1 = cA + (size_t)(t + 1) * kstep;
;             const char* a2 = last ? nA : cA + (size_t)(t + 2) * kstep; const char* b2 = last ? nB : cB + (size_t)(t + 2) * kstep;
;             const char* a3 = a2 + kstep; const char* b3 = b2 + kstep;
;             if (last && has_next) S.a_ready(nxt);
;             if constexpr (SP2) {
;             PG8_LDB(B0, 0, 0); PG8_LDB(B1, 0, 1); PG8_SCHED; PG8_LDA(At, 0, 0); PG8_STAGE(PG8_SA(1, 1), a1 + hstep, voffA);
;             PG8_WAIT_V(8); PG8_WAIT_L(0); PG8_BAR; PG8_MMA(0, 0, At, B0); PG8_MMA(0, 1, At, B1); PG8_BAR; PG8_SCHED;
;             PG8_LDA(At, 0, 1); PG8_STAGE(PG8_SB(0, 0), b2, voffB); PG8_STAGE(PG8_SB(0, 1), b2 + hstep, voffB); PG8_STAGE(PG8_SA(0, 0), a2, voffA);
;             PG8_WAIT_V(8); PG8_WAIT_L(0); PG8_BAR; PG8_MMA(1, 0, At, B0); PG8_MMA(1, 1, At, B1); PG8_BAR; PG8_SCHED;
;     ...
;         for (int a = 0; a < 2; ++a)
; #pragma unroll
;             for (int b = 0; b < 2; ++b)
; #pragma unroll
;                 for (int m = 0; m < 4; ++m)
; #pragma unroll
;                     for (int n = 0; n < 2; ++n) acc[a][b][m][n] = (f32x4){0.f, 0.f, 0.f, 0.f};
.LBB0_1030:
	s_add_u32 s34, s20, 0x100
	s_addc_u32 s42, s21, 0
	s_mov_b32 s43, -2
	s_add_u32 s20, s16, 0x100
	s_addc_u32 s21, s17, 0
	s_add_i32 s2, s35, 0x100
	s_cmp_eq_u32 s43, 40
	s_cselect_b32 s25, s13, s21
	s_cselect_b32 s24, s12, s20
	s_cselect_b32 s23, s15, s42
	s_cselect_b32 s22, s14, s34
	s_add_i32 s29, s90, 0x100
	v_add_u32_e32 v128, s2, v249
	v_add_u32_e32 v156, s29, v249
	ds_read_b128 v[112:115], v128
	ds_read_b128 v[120:123], v128 offset:1024
	ds_read_b128 v[124:127], v128 offset:2048
	ds_read_b128 v[128:131], v128 offset:3072
	ds_read_b128 v[136:139], v156
	ds_read_b128 v[140:143], v156 offset:1024
	ds_read_b128 v[144:147], v156 offset:2048
	ds_read_b128 v[156:159], v156 offset:3072
	v_lshl_add_u64 v[194:195], s[16:17], 0, v[206:207]
	s_add_i32 m0, s45, 0xc000
	ds_read_b128 v[160:163], v251
	ds_read_b128 v[164:167], v251 offset:1024
	ds_read_b128 v[168:171], v251 offset:2048
	ds_read_b128 v[172:175], v251 offset:3072
	ds_read_b128 v[176:179], v251 offset:4096
	ds_read_b128 v[180:183], v251 offset:5120
	ds_read_b128 v[184:187], v251 offset:6144
	ds_read_b128 v[188:191], v251 offset:7168
	global_load_lds_dwordx4 v[194:195], off
	v_lshl_add_u64 v[194:195], s[16:17], 0, v[204:205]
	s_add_i32 m0, s45, 0xe000
	s_nop 0
	global_load_lds_dwordx4 v[194:195], off
	s_waitcnt vmcnt(8)
	s_waitcnt lgkmcnt(0)
	s_barrier
	s_setprio 1
	s_waitcnt lgkmcnt(0)
	v_mfma_f32_16x16x32_bf16 v[152:155], v[112:115], v[160:163], 0
	v_mfma_f32_16x16x32_bf16 v[148:151], v[124:127], v[160:163], 0
	v_mfma_f32_16x16x32_bf16 v[108:111], v[112:115], v[168:171], 0
	v_mfma_f32_16x16x32_bf16 v[104:107], v[124:127], v[168:171], 0
	v_mfma_f32_16x16x32_bf16 v[92:95], v[112:115], v[176:179], 0
	v_mfma_f32_16x16x32_bf16 v[88:91], v[124:127], v[176:179], 0
	v_mfma_f32_16x16x32_bf16 v[76:79], v[112:115], v[184:187], 0
	v_mfma_f32_16x16x32_bf16 v[72:75], v[124:127], v[184:187], 0
	v_mfma_f32_16x16x32_bf16 v[152:155], v[120:123], v[164:167], v[152:155]
	v_mfma_f32_16x16x32_bf16 v[148:151], v[128:131], v[164:167], v[148:151]
	v_mfma_f32_16x16x32_bf16 v[108:111], v[120:123], v[172:175], v[108:111]
	v_mfma_f32_16x16x32_bf16 v[104:107], v[128:131], v[172:175], v[104:107]
	v_mfma_f32_16x16x32_bf16 v[92:95], v[120:123], v[180:183], v[92:95]
	v_mfma_f32_16x16x32_bf16 v[88:91], v[128:131], v[180:183], v[88:91]
	v_mfma_f32_16x16x32_bf16 v[76:79], v[120:123], v[188:191], v[76:79]
	v_mfma_f32_16x16x32_bf16 v[72:75], v[128:131], v[188:191], v[72:75]
	s_setprio 0
	s_setprio 1
	v_mfma_f32_16x16x32_bf16 v[132:135], v[136:139], v[160:163], 0
	v_mfma_f32_16x16x32_bf16 v[116:119], v[144:147], v[160:163], 0
	v_mfma_f32_16x16x32_bf16 v[100:103], v[136:139], v[168:171], 0
	v_mfma_f32_16x16x32_bf16 v[96:99], v[144:147], v[168:171], 0
	v_mfma_f32_16x16x32_bf16 v[84:87], v[136:139], v[176:179], 0
	v_mfma_f32_16x16x32_bf16 v[80:83], v[144:147], v[176:179], 0
	v_mfma_f32_16x16x32_bf16 v[68:71], v[136:139], v[184:187], 0
	v_mfma_f32_16x16x32_bf16 v[64:67], v[144:147], v[184:187], 0
	v_mfma_f32_16x16x32_bf16 v[132:135], v[140:143], v[164:167], v[132:135]
	v_mfma_f32_16x16x32_bf16 v[116:119], v[156:159], v[164:167], v[116:119]
	v_mfma_f32_16x16x32_bf16 v[100:103], v[140:143], v[172:175], v[100:103]
	v_mfma_f32_16x16x32_bf16 v[96:99], v[156:159], v[172:175], v[96:99]
	v_mfma_f32_16x16x32_bf16 v[84:87], v[140:143], v[180:183], v[84:87]
	v_mfma_f32_16x16x32_bf16 v[80:83], v[156:159], v[180:183], v[80:83]
	v_mfma_f32_16x16x32_bf16 v[68:71], v[140:143], v[188:191], v[68:71]
	v_mfma_f32_16x16x32_bf16 v[64:67], v[156:159], v[188:191], v[64:67]
	s_setprio 0
	s_barrier
	s_add_i32 s2, s2, s44
	v_lshl_add_u64 v[194:195], s[22:23], 0, v[192:193]
	s_mov_b32 m0, s2
	ds_read_b128 v[160:163], v251 offset:16384
	ds_read_b128 v[164:167], v251 offset:17408
	ds_read_b128 v[168:171], v251 offset:18432
	ds_read_b128 v[172:175], v251 offset:19456
	ds_read_b128 v[176:179], v251 offset:20480
	ds_read_b128 v[180:183], v251 offset:21504
	ds_read_b128 v[184:187], v251 offset:22528
	ds_read_b128 v[188:191], v251 offset:23552
	global_load_lds_dwordx4 v[194:195], off
	s_add_i32 m0, s2, 0x2000
	s_add_u32 s16, s22, 0xb0000
	v_lshl_add_u64 v[196:197], s[22:23], 0, v[198:199]
	s_addc_u32 s17, s23, 0
	s_add_i32 s2, s29, s44
	global_load_lds_dwordx4 v[196:197], off
	v_lshl_add_u64 v[208:209], s[16:17], 0, v[192:193]
	s_mov_b32 m0, s2
	v_lshl_add_u64 v[210:211], s[24:25], 0, v[200:201]
	global_load_lds_dwordx4 v[208:209], off
	v_lshl_add_u64 v[208:209], s[16:17], 0, v[198:199]
	s_add_i32 m0, s2, 0x2000
	s_nop 0
	global_load_lds_dwordx4 v[208:209], off
	v_lshl_add_u64 v[208:209], s[24:25], 0, v[202:203]
	s_mov_b32 m0, s45
	s_nop 0
	global_load_lds_dwordx4 v[208:209], off
	s_mov_b32 m0, s46
	s_nop 0
	global_load_lds_dwordx4 v[210:211], off
	s_waitcnt vmcnt(8)
	s_waitcnt lgkmcnt(0)
	s_barrier
; #define PG8_STAGE(bufoff, gbase, voff) do { _Pragma("unroll") for (int _i = 0; _i < 2; ++_i) \
;         __builtin_amdgcn_global_load_lds((const unsigned*)((const char*)(gbase) + (voff)[_i]), (PG8_LAS unsigned*)(lds + (bufoff) + ldsw + _i * 8192), 16, 0, 0); } while (0)
; #define PG8_LDA(dst, b, h) do { _Pragma("unroll") for (int m = 0; m < 4; ++m) _Pragma("unroll") for (int k = 0; k < 2; ++k) dst[m][k] = *(const PG8_LAS bf16x8*)(lds + PG8_SA(b, h) + aoff + m * 2048 + k * 1024); } while (0)
; #define PG8_LDB(dst, b, h) do { _Pragma("unroll") for (int n = 0; n < 2; ++n) _Pragma("unroll") for (int k = 0; k < 2; ++k) dst[n][k] = *(const PG8_LAS bf16x8*)(lds + PG8_SB(b, h) + boff + n * 2048 + k * 1024); } while (0)
; #define PG8_MMA(ai, bj, At, Bt) do { __builtin_amdgcn_s_setprio(1); _Pragma("unroll") for (int m = 0; m < 4; ++m) _Pragma("unroll") for (int n = 0; n < 2; ++n) _Pragma("unroll") for (int k = 0; k < 2; ++k) \
;         acc[ai][bj][m][n] = __builtin_amdgcn_mfma_f32_16x16x32_bf16(Bt[n][k], At[m][k], acc[ai][bj][m][n], 0, 0, 0); __builtin_amdgcn_s_setprio(0); } while (0)
; #define PG8_WAIT_V(n) asm volatile("s_waitcnt vmcnt(" #n ")" ::: "memory")
; #define PG8_WAIT_L(n) asm volatile("s_waitcnt lgkmcnt(" #n ")" ::: "memory")
; #define PG8_BAR __builtin_amdgcn_s_barrier()
; #define PG8_SCHED __builtin_amdgcn_sched_barrier(0)
; template <class Epi, class Sched, bool ALIGN_EPI = false, bool SP2 = false>
; __device__ __forceinline__ void gemm_phase(PG8_LAS unsigned char* lds, const Gemm g, const Sched& S, const Epi& E, int wave_in) {
;     ...
;             PG8_WAIT_V(8); PG8_WAIT_L(0); PG8_BAR; PG8_MMA(1, 0, At, B0); PG8_MMA(1, 1, At, B1); PG8_BAR; PG8_SCHED;
;             PG8_LDB(B0, 1, 0); PG8_LDB(B1, 1, 1); PG8_SCHED; PG8_LDA(At, 1, 0); PG8_STAGE(PG8_SA(0, 1), a2 + hstep, voffA);
;             PG8_WAIT_V(8); PG8_WAIT_L(0); PG8_BAR; PG8_MMA(0, 0, At, B0); PG8_MMA(0, 1, At, B1); PG8_BAR; PG8_SCHED;
	s_setprio 1
	s_waitcnt lgkmcnt(0)
	v_mfma_f32_16x16x32_bf16 v[60:63], v[112:115], v[160:163], 0
	v_mfma_f32_16x16x32_bf16 v[56:59], v[124:127], v[160:163], 0
	v_mfma_f32_16x16x32_bf16 v[44:47], v[112:115], v[168:171], 0
	v_mfma_f32_16x16x32_bf16 v[40:43], v[124:127], v[168:171], 0
	v_mfma_f32_16x16x32_bf16 v[28:31], v[112:115], v[176:179], 0
	v_mfma_f32_16x16x32_bf16 v[24:27], v[124:127], v[176:179], 0
	v_mfma_f32_16x16x32_bf16 v[12:15], v[112:115], v[184:187], 0
	v_mfma_f32_16x16x32_bf16 v[8:11], v[124:127], v[184:187], 0
	v_mfma_f32_16x16x32_bf16 v[60:63], v[120:123], v[164:167], v[60:63]
	v_mfma_f32_16x16x32_bf16 v[56:59], v[128:131], v[164:167], v[56:59]
	v_mfma_f32_16x16x32_bf16 v[44:47], v[120:123], v[172:175], v[44:47]
	v_mfma_f32_16x16x32_bf16 v[40:43], v[128:131], v[172:175], v[40:43]
	v_mfma_f32_16x16x32_bf16 v[28:31], v[120:123], v[180:183], v[28:31]
	v_mfma_f32_16x16x32_bf16 v[24:27], v[128:131], v[180:183], v[24:27]
	v_mfma_f32_16x16x32_bf16 v[12:15], v[120:123], v[188:191], v[12:15]
	v_mfma_f32_16x16x32_bf16 v[8:11], v[128:131], v[188:191], v[8:11]
	s_setprio 0
	s_setprio 1
	v_mfma_f32_16x16x32_bf16 v[52:55], v[136:139], v[160:163], 0
	v_mfma_f32_16x16x32_bf16 v[48:51], v[144:147], v[160:163], 0
	v_mfma_f32_16x16x32_bf16 v[36:39], v[136:139], v[168:171], 0
	v_mfma_f32_16x16x32_bf16 v[32:35], v[144:147], v[168:171], 0
	v_mfma_f32_16x16x32_bf16 v[20:23], v[136:139], v[176:179], 0
	v_mfma_f32_16x16x32_bf16 v[16:19], v[144:147], v[176:179], 0
	v_mfma_f32_16x16x32_bf16 v[4:7], v[136:139], v[184:187], 0
	v_mfma_f32_16x16x32_bf16 v[0:3], v[144:147], v[184:187], 0
	v_mfma_f32_16x16x32_bf16 v[52:55], v[140:143], v[164:167], v[52:55]
	v_mfma_f32_16x16x32_bf16 v[48:51], v[156:159], v[164:167], v[48:51]
	v_mfma_f32_16x16x32_bf16 v[36:39], v[140:143], v[172:175], v[36:39]
	v_mfma_f32_16x16x32_bf16 v[32:35], v[156:159], v[172:175], v[32:35]
	v_mfma_f32_16x16x32_bf16 v[20:23], v[140:143], v[180:183], v[20:23]
	v_mfma_f32_16x16x32_bf16 v[16:19], v[156:159], v[180:183], v[16:19]
	v_mfma_f32_16x16x32_bf16 v[4:7], v[140:143], v[188:191], v[4:7]
	v_mfma_f32_16x16x32_bf16 v[0:3], v[156:159], v[188:191], v[0:3]
	s_setprio 0
	s_barrier
	s_add_i32 s2, s65, 0x100
	s_add_i32 s29, s52, 0x100
	v_add_u32_e32 v128, s2, v249
	v_add_u32_e32 v156, s29, v249
	ds_read_b128 v[112:115], v128
	ds_read_b128 v[120:123], v128 offset:1024
	ds_read_b128 v[124:127], v128 offset:2048
	ds_read_b128 v[128:131], v128 offset:3072
	ds_read_b128 v[136:139], v156
	ds_read_b128 v[140:143], v156 offset:1024
	ds_read_b128 v[144:147], v156 offset:2048
	ds_read_b128 v[156:159], v156 offset:3072
	s_add_u32 s16, s24, 0xb0000
	s_addc_u32 s17, s25, 0
	s_mov_b32 m0, s47
	v_lshl_add_u64 v[212:213], s[16:17], 0, v[202:203]
	ds_read_b128 v[160:163], v251 offset:32768
	ds_read_b128 v[164:167], v251 offset:33792
	ds_read_b128 v[168:171], v251 offset:34816
	ds_read_b128 v[172:175], v251 offset:35840
	ds_read_b128 v[176:179], v251 offset:36864
	ds_read_b128 v[180:183], v251 offset:37888
	ds_read_b128 v[184:187], v251 offset:38912
	ds_read_b128 v[188:191], v251 offset:39936
	global_load_lds_dwordx4 v[212:213], off
	v_lshl_add_u64 v[212:213], s[16:17], 0, v[200:201]
	s_mov_b32 m0, s60
	s_nop 0
	global_load_lds_dwordx4 v[212:213], off
	s_waitcnt vmcnt(8)
	s_waitcnt lgkmcnt(0)
	s_barrier
	s_setprio 1
	s_waitcnt lgkmcnt(0)
	v_mfma_f32_16x16x32_bf16 v[152:155], v[112:115], v[160:163], v[152:155]
	v_mfma_f32_16x16x32_bf16 v[148:151], v[124:127], v[160:163], v[148:151]
	v_mfma_f32_16x16x32_bf16 v[108:111], v[112:115], v[168:171], v[108:111]
	v_mfma_f32_16x16x32_bf16 v[104:107], v[124:127], v[168:171], v[104:107]
	v_mfma_f32_16x16x32_bf16 v[92:95], v[112:115], v[176:179], v[92:95]
	v_mfma_f32_16x16x32_bf16 v[88:91], v[124:127], v[176:179], v[88:91]
	v_mfma_f32_16x16x32_bf16 v[76:79], v[112:115], v[184:187], v[76:79]
	v_mfma_f32_16x16x32_bf16 v[72:75], v[124:127], v[184:187], v[72:75]
	v_mfma_f32_16x16x32_bf16 v[152:155], v[120:123], v[164:167], v[152:155]
	v_mfma_f32_16x16x32_bf16 v[148:151], v[128:131], v[164:167], v[148:151]
	v_mfma_f32_16x16x32_bf16 v[108:111], v[120:123], v[172:175], v[108:111]
	v_mfma_f32_16x16x32_bf16 v[104:107], v[128:131], v[172:175], v[104:107]
	v_mfma_f32_16x16x32_bf16 v[92:95], v[120:123], v[180:183], v[92:95]
	v_mfma_f32_16x16x32_bf16 v[88:91], v[128:131], v[180:183], v[88:91]
	v_mfma_f32_16x16x32_bf16 v[76:79], v[120:123], v[188:191], v[76:79]
	v_mfma_f32_16x16x32_bf16 v[72:75], v[128:131], v[188:191], v[72:75]
	s_setprio 0
	s_setprio 1
	v_mfma_f32_16x16x32_bf16 v[132:135], v[136:139], v[160:163], v[132:135]
	v_mfma_f32_16x16x32_bf16 v[116:119], v[144:147], v[160:163], v[116:119]
	v_mfma_f32_16x16x32_bf16 v[100:103], v[136:139], v[168:171], v[100:103]
	v_mfma_f32_16x16x32_bf16 v[96:99], v[144:147], v[168:171], v[96:99]
	v_mfma_f32_16x16x32_bf16 v[84:87], v[136:139], v[176:179], v[84:87]
	v_mfma_f32_16x16x32_bf16 v[80:83], v[144:147], v[176:179], v[80:83]
	v_mfma_f32_16x16x32_bf16 v[68:71], v[136:139], v[184:187], v[68:71]
	v_mfma_f32_16x16x32_bf16 v[64:67], v[144:147], v[184:187], v[64:67]
	v_mfma_f32_16x16x32_bf16 v[132:135], v[140:143], v[164:167], v[132:135]
	v_mfma_f32_16x16x32_bf16 v[116:119], v[156:159], v[164:167], v[116:119]
	v_mfma_f32_16x16x32_bf16 v[100:103], v[140:143], v[172:175], v[100:103]
	v_mfma_f32_16x16x32_bf16 v[96:99], v[156:159], v[172:175], v[96:99]
	v_mfma_f32_16x16x32_bf16 v[84:87], v[140:143], v[180:183], v[84:87]
	v_mfma_f32_16x16x32_bf16 v[80:83], v[156:159], v[180:183], v[80:83]
	v_mfma_f32_16x16x32_bf16 v[68:71], v[140:143], v[188:191], v[68:71]
	v_mfma_f32_16x16x32_bf16 v[64:67], v[156:159], v[188:191], v[64:67]
	s_setprio 0
	s_barrier
; #define PG8_STAGE(bufoff, gbase, voff) do { _Pragma("unroll") for (int _i = 0; _i < 2; ++_i) \
;         __builtin_amdgcn_global_load_lds((const unsigned*)((const char*)(gbase) + (voff)[_i]), (PG8_LAS unsigned*)(lds + (bufoff) + ldsw + _i * 8192), 16, 0, 0); } while (0)
; #define PG8_LDA(dst, b, h) do { _Pragma("unroll") for (int m = 0; m < 4; ++m) _Pragma("unroll") for (int k = 0; k < 2; ++k) dst[m][k] = *(const PG8_LAS bf16x8*)(lds + PG8_SA(b, h) + aoff + m * 2048 + k * 1024); } while (0)
; #define PG8_MMA(ai, bj, At, Bt) do { __builtin_amdgcn_s_setprio(1); _Pragma("unroll") for (int m = 0; m < 4; ++m) _Pragma("unroll") for (int n = 0; n < 2; ++n) _Pragma("unroll") for (int k = 0; k < 2; ++k) \
;         acc[ai][bj][m][n] = __builtin_amdgcn_mfma_f32_16x16x32_bf16(Bt[n][k], At[m][k], acc[ai][bj][m][n], 0, 0, 0); __builtin_amdgcn_s_setprio(0); } while (0)
; #define PG8_WAIT_V(n) asm volatile("s_waitcnt vmcnt(" #n ")" ::: "memory")
; #define PG8_WAIT_L(n) asm volatile("s_waitcnt lgkmcnt(" #n ")" ::: "memory")
; #define PG8_BAR __builtin_amdgcn_s_barrier()
; #define PG8_SCHED __builtin_amdgcn_sched_barrier(0)
; template <class Epi, class Sched, bool ALIGN_EPI = false, bool SP2 = false>
; __device__ __forceinline__ void gemm_phase(PG8_LAS unsigned char* lds, const Gemm g, const Sched& S, const Epi& E, int wave_in) {
;     ...
;         for (int t = 0; t < nt; t += 2) {
;             const bool last = (t == nt - 2);
;             const char* a1 = cA + (size_t)(t + 1) * kstep;
;             const char* a2 = last ? nA : cA + (size_t)(t + 2) * kstep; const char* b2 = last ? nB : cB + (size_t)(t + 2) * kstep;
;     ...
;             PG8_LDA(At, 1, 1); PG8_STAGE(PG8_SB(1, 0), b3, voffB); PG8_STAGE(PG8_SB(1, 1), b3 + hstep, voffB); PG8_STAGE(PG8_SA(1, 0), a3, voffA);
;             PG8_WAIT_V(8); PG8_WAIT_L(0); PG8_BAR; PG8_MMA(1, 0, At, B0); PG8_MMA(1, 1, At, B1); PG8_BAR; PG8_SCHED;
	s_add_i32 s2, s2, s44
	v_lshl_add_u64 v[194:195], v[194:195], 0, s[88:89]
	s_mov_b32 m0, s2
	ds_read_b128 v[160:163], v251 offset:49152
	ds_read_b128 v[164:167], v251 offset:50176
	ds_read_b128 v[168:171], v251 offset:51200
	ds_read_b128 v[172:175], v251 offset:52224
	ds_read_b128 v[176:179], v251 offset:53248
	ds_read_b128 v[180:183], v251 offset:54272
	ds_read_b128 v[184:187], v251 offset:55296
	ds_read_b128 v[188:191], v251 offset:56320
	global_load_lds_dwordx4 v[194:195], off
	s_add_i32 m0, s2, 0x2000
	s_add_u32 s16, s22, 0xb0080
	v_lshl_add_u64 v[194:195], v[196:197], 0, s[88:89]
	s_addc_u32 s17, s23, 0
	s_add_i32 s2, s29, s44
	global_load_lds_dwordx4 v[194:195], off
	v_lshl_add_u64 v[194:195], s[16:17], 0, v[192:193]
	s_mov_b32 m0, s2
	s_nop 0
	global_load_lds_dwordx4 v[194:195], off
	v_lshl_add_u64 v[194:195], s[16:17], 0, v[198:199]
	s_add_i32 m0, s2, 0x2000
	s_nop 0
	global_load_lds_dwordx4 v[194:195], off
	v_lshl_add_u64 v[194:195], v[208:209], 0, s[88:89]
	s_mov_b32 m0, s62
	s_nop 0
	global_load_lds_dwordx4 v[194:195], off
	v_lshl_add_u64 v[194:195], v[210:211], 0, s[88:89]
	s_mov_b32 m0, s63
	s_nop 0
	global_load_lds_dwordx4 v[194:195], off
	s_waitcnt vmcnt(8)
	s_waitcnt lgkmcnt(0)
	s_barrier
	s_setprio 1
	s_waitcnt lgkmcnt(0)
	v_mfma_f32_16x16x32_bf16 v[60:63], v[112:115], v[160:163], v[60:63]
	v_mfma_f32_16x16x32_bf16 v[56:59], v[124:127], v[160:163], v[56:59]
	v_mfma_f32_16x16x32_bf16 v[44:47], v[112:115], v[168:171], v[44:47]
	v_mfma_f32_16x16x32_bf16 v[40:43], v[124:127], v[168:171], v[40:43]
	v_mfma_f32_16x16x32_bf16 v[28:31], v[112:115], v[176:179], v[28:31]
	v_mfma_f32_16x16x32_bf16 v[24:27], v[124:127], v[176:179], v[24:27]
	v_mfma_f32_16x16x32_bf16 v[12:15], v[112:115], v[184:187], v[12:15]
	v_mfma_f32_16x16x32_bf16 v[8:11], v[124:127], v[184:187], v[8:11]
	v_mfma_f32_16x16x32_bf16 v[60:63], v[120:123], v[164:167], v[60:63]
	v_mfma_f32_16x16x32_bf16 v[56:59], v[128:131], v[164:167], v[56:59]
	v_mfma_f32_16x16x32_bf16 v[44:47], v[120:123], v[172:175], v[44:47]
	v_mfma_f32_16x16x32_bf16 v[40:43], v[128:131], v[172:175], v[40:43]
	v_mfma_f32_16x16x32_bf16 v[28:31], v[120:123], v[180:183], v[28:31]
	v_mfma_f32_16x16x32_bf16 v[24:27], v[128:131], v[180:183], v[24:27]
	v_mfma_f32_16x16x32_bf16 v[12:15], v[120:123], v[188:191], v[12:15]
	v_mfma_f32_16x16x32_bf16 v[8:11], v[128:131], v[188:191], v[8:11]
	s_setprio 0
	s_setprio 1
	v_mfma_f32_16x16x32_bf16 v[52:55], v[136:139], v[160:163], v[52:55]
	v_mfma_f32_16x16x32_bf16 v[48:51], v[144:147], v[160:163], v[48:51]
	v_mfma_f32_16x16x32_bf16 v[36:39], v[136:139], v[168:171], v[36:39]
	v_mfma_f32_16x16x32_bf16 v[32:35], v[144:147], v[168:171], v[32:35]
	v_mfma_f32_16x16x32_bf16 v[20:23], v[136:139], v[176:179], v[20:23]
	v_mfma_f32_16x16x32_bf16 v[16:19], v[144:147], v[176:179], v[16:19]
	v_mfma_f32_16x16x32_bf16 v[4:7], v[136:139], v[184:187], v[4:7]
	v_mfma_f32_16x16x32_bf16 v[0:3], v[144:147], v[184:187], v[0:3]
	v_mfma_f32_16x16x32_bf16 v[52:55], v[140:143], v[164:167], v[52:55]
	v_mfma_f32_16x16x32_bf16 v[48:51], v[156:159], v[164:167], v[48:51]
	v_mfma_f32_16x16x32_bf16 v[36:39], v[140:143], v[172:175], v[36:39]
	v_mfma_f32_16x16x32_bf16 v[32:35], v[156:159], v[172:175], v[32:35]
	v_mfma_f32_16x16x32_bf16 v[20:23], v[140:143], v[180:183], v[20:23]
	v_mfma_f32_16x16x32_bf16 v[16:19], v[156:159], v[180:183], v[16:19]
	v_mfma_f32_16x16x32_bf16 v[4:7], v[140:143], v[188:191], v[4:7]
	v_mfma_f32_16x16x32_bf16 v[0:3], v[156:159], v[188:191], v[0:3]
	s_setprio 0
	s_barrier
	s_add_i32 s43, s43, 2
	s_add_u32 s34, s34, 0x100
	s_addc_u32 s42, s42, 0
	s_cmp_gt_u32 s43, 41
	s_mov_b64 s[16:17], s[20:21]
	s_cbranch_scc1 .Lkexit_7

; #define PG8_BAR __builtin_amdgcn_s_barrier()
; template <class Epi, class Sched, bool ALIGN_EPI = false, bool SP2 = false>
; __device__ __forceinline__ void gemm_phase(PG8_LAS unsigned char* lds, const Gemm g, const Sched& S, const Epi& E, int wave_in) {
;     ...
;         if constexpr (ALIGN_EPI) { if (wr == 0) PG8_BAR; }
.Lkexit_7:
	v_mov_b64_e32 v[246:247], 0x400
	s_and_b64 vcc, exec, s[10:11]
	s_cbranch_vccz .LBB0_1034
	s_barrier
